# code placement: the eight GEMM K-loop heads and the attention kv-loop head aligned to 64 bytes
# baseline (speedup 1.0000x reference)
; template <class Epi, class Sched, bool ALIGN_EPI = false, bool SP2 = false>
; __device__ __forceinline__ void gemm_phase(PG8_LAS unsigned char* lds, const Gemm g, const Sched& S, const Epi& E) {
;     ...
;         const bool has_next = S.next(ui + 1, nxt);
;         const char* nA = has_next ? (const char*)g.A + (size_t)nxt.pm * tstep : cA; const char* nB = has_next ? (const char*)g.Bt + (size_t)nxt.pn * tstep : cB;
;     ...
; #pragma unroll
;         for (int a = 0; a < 2; ++a)
; #pragma unroll
;             for (int b = 0; b < 2; ++b)
; #pragma unroll
;                 for (int m = 0; m < 4; ++m)
; #pragma unroll
;                     for (int n = 0; n < 2; ++n) acc[a][b][m][n] = (f32x4){0.f, 0.f, 0.f, 0.f};
;         cur = nxt; cA = nA; cB = nB; ++ui;
.LBB0_191:
	s_ashr_i32 s55, s54, 31
	s_lshl_b64 s[58:59], s[54:55], 20
	s_add_u32 s58, s31, s58
	s_addc_u32 s59, s35, s59
	s_and_b64 s[60:61], s[4:5], exec
	s_cselect_b32 s55, s59, s67
	s_cselect_b32 s84, s58, s66
	s_ashr_i32 s57, s56, 31
	s_lshl_b64 s[60:61], s[56:57], 20
	s_add_u32 s60, s27, s60
	s_addc_u32 s61, s29, s61
	s_and_b64 s[68:69], s[4:5], exec
	s_cselect_b32 s57, s61, s7
	s_cselect_b32 s85, s60, s6
	s_add_u32 s86, s6, 0x100
	s_addc_u32 s87, s7, 0
	s_add_u32 s6, s66, 0x80080
	v_mov_b32_e32 v0, 0
	s_addc_u32 s7, s67, 0
	s_mov_b32 s88, -2
	v_mov_b32_e32 v1, v0
	v_mov_b32_e32 v2, v0
	v_mov_b32_e32 v3, v0
	v_mov_b32_e32 v4, v0
	v_mov_b32_e32 v5, v0
	v_mov_b32_e32 v6, v0
	v_mov_b32_e32 v7, v0
	v_mov_b32_e32 v16, v0
	v_mov_b32_e32 v17, v0
	v_mov_b32_e32 v18, v0
	v_mov_b32_e32 v19, v0
	v_mov_b32_e32 v20, v0
	v_mov_b32_e32 v21, v0
	v_mov_b32_e32 v22, v0
	v_mov_b32_e32 v23, v0
	v_mov_b32_e32 v32, v0
	v_mov_b32_e32 v33, v0
	v_mov_b32_e32 v34, v0
	v_mov_b32_e32 v35, v0
	v_mov_b32_e32 v36, v0
	v_mov_b32_e32 v37, v0
	v_mov_b32_e32 v38, v0
	v_mov_b32_e32 v39, v0
	v_mov_b32_e32 v56, v0
	v_mov_b32_e32 v57, v0
	v_mov_b32_e32 v58, v0
	v_mov_b32_e32 v59, v0
	v_mov_b32_e32 v60, v0
	v_mov_b32_e32 v61, v0
	v_mov_b32_e32 v62, v0
	v_mov_b32_e32 v63, v0
	v_mov_b32_e32 v8, v0
	v_mov_b32_e32 v9, v0
	v_mov_b32_e32 v10, v0
	v_mov_b32_e32 v11, v0
	v_mov_b32_e32 v12, v0
	v_mov_b32_e32 v13, v0
	v_mov_b32_e32 v14, v0
	v_mov_b32_e32 v15, v0
	v_mov_b32_e32 v24, v0
	v_mov_b32_e32 v25, v0
	v_mov_b32_e32 v26, v0
	v_mov_b32_e32 v27, v0
	v_mov_b32_e32 v28, v0
	v_mov_b32_e32 v29, v0
	v_mov_b32_e32 v30, v0
	v_mov_b32_e32 v31, v0
	v_mov_b32_e32 v40, v0
	v_mov_b32_e32 v41, v0
	v_mov_b32_e32 v42, v0
	v_mov_b32_e32 v43, v0
	v_mov_b32_e32 v44, v0
	v_mov_b32_e32 v45, v0
	v_mov_b32_e32 v46, v0
	v_mov_b32_e32 v47, v0
	v_mov_b32_e32 v72, v0
	v_mov_b32_e32 v73, v0
	v_mov_b32_e32 v74, v0
	v_mov_b32_e32 v75, v0
	v_mov_b32_e32 v76, v0
	v_mov_b32_e32 v77, v0
	v_mov_b32_e32 v78, v0
	v_mov_b32_e32 v79, v0
	v_mov_b32_e32 v80, v0
	v_mov_b32_e32 v81, v0
	v_mov_b32_e32 v82, v0
	v_mov_b32_e32 v83, v0
	v_mov_b32_e32 v84, v0
	v_mov_b32_e32 v85, v0
	v_mov_b32_e32 v86, v0
	v_mov_b32_e32 v87, v0
	v_mov_b32_e32 v96, v0
	v_mov_b32_e32 v97, v0
	v_mov_b32_e32 v98, v0
	v_mov_b32_e32 v99, v0
	v_mov_b32_e32 v100, v0
	v_mov_b32_e32 v101, v0
	v_mov_b32_e32 v102, v0
	v_mov_b32_e32 v103, v0
	v_mov_b32_e32 v112, v0
	v_mov_b32_e32 v113, v0
	v_mov_b32_e32 v114, v0
	v_mov_b32_e32 v115, v0
	v_mov_b32_e32 v116, v0
	v_mov_b32_e32 v117, v0
	v_mov_b32_e32 v118, v0
	v_mov_b32_e32 v119, v0
	v_mov_b32_e32 v128, v0
	v_mov_b32_e32 v129, v0
	v_mov_b32_e32 v130, v0
	v_mov_b32_e32 v131, v0
	v_mov_b32_e32 v132, v0
	v_mov_b32_e32 v133, v0
	v_mov_b32_e32 v134, v0
	v_mov_b32_e32 v135, v0
	v_mov_b32_e32 v88, v0
	v_mov_b32_e32 v89, v0
	v_mov_b32_e32 v90, v0
	v_mov_b32_e32 v91, v0
	v_mov_b32_e32 v92, v0
	v_mov_b32_e32 v93, v0
	v_mov_b32_e32 v94, v0
	v_mov_b32_e32 v95, v0
	v_mov_b32_e32 v104, v0
	v_mov_b32_e32 v105, v0
	v_mov_b32_e32 v106, v0
	v_mov_b32_e32 v107, v0
	v_mov_b32_e32 v108, v0
	v_mov_b32_e32 v109, v0
	v_mov_b32_e32 v110, v0
	v_mov_b32_e32 v111, v0
	v_mov_b32_e32 v120, v0
	v_mov_b32_e32 v121, v0
	v_mov_b32_e32 v122, v0
	v_mov_b32_e32 v123, v0
	v_mov_b32_e32 v124, v0
	v_mov_b32_e32 v125, v0
	v_mov_b32_e32 v126, v0
	v_mov_b32_e32 v127, v0
	v_mov_b32_e32 v136, v0
	v_mov_b32_e32 v137, v0
	v_mov_b32_e32 v138, v0
	v_mov_b32_e32 v139, v0
	v_mov_b32_e32 v140, v0
	v_mov_b32_e32 v141, v0
	v_mov_b32_e32 v142, v0
	v_mov_b32_e32 v143, v0
	.p2align	6

; #define PG8_STAGE(bufoff, gbase, voff) do { _Pragma("unroll") for (int _i = 0; _i < 2; ++_i) \
;         __builtin_amdgcn_global_load_lds((const unsigned*)((const char*)(gbase) + (voff)[_i]), (PG8_LAS unsigned*)(lds + (bufoff) + ldsw + _i * 8192), 16, 0, 0); } while (0)
; #define PG8_LDA(dst, b, h) do { _Pragma("unroll") for (int m = 0; m < 4; ++m) _Pragma("unroll") for (int k = 0; k < 2; ++k) dst[m][k] = *(const PG8_LAS bf16x8*)(lds + PG8_SA(b, h) + aoff + m * 2048 + k * 1024); } while (0)
; #define PG8_LDB(dst, b, h) do { _Pragma("unroll") for (int n = 0; n < 2; ++n) _Pragma("unroll") for (int k = 0; k < 2; ++k) dst[n][k] = *(const PG8_LAS bf16x8*)(lds + PG8_SB(b, h) + boff + n * 2048 + k * 1024); } while (0)
; #define PG8_MMA(ai, bj, At, Bt) do { __builtin_amdgcn_s_setprio(1); _Pragma("unroll") for (int m = 0; m < 4; ++m) _Pragma("unroll") for (int n = 0; n < 2; ++n) _Pragma("unroll") for (int k = 0; k < 2; ++k) \
;         acc[ai][bj][m][n] = __builtin_amdgcn_mfma_f32_16x16x32_bf16(Bt[n][k], At[m][k], acc[ai][bj][m][n], 0, 0, 0); __builtin_amdgcn_s_setprio(0); } while (0)
; #define PG8_WAIT_V(n) asm volatile("s_waitcnt vmcnt(" #n ")" ::: "memory")
; #define PG8_WAIT_L(n) asm volatile("s_waitcnt lgkmcnt(" #n ")" ::: "memory")
; template <class Epi, class Sched, bool ALIGN_EPI = false, bool SP2 = false>
; __device__ __forceinline__ void gemm_phase(PG8_LAS unsigned char* lds, const Gemm g, const Sched& S, const Epi& E) {
;     ...
;             const bool last = (t == nt - 2);
;             const char* a1 = cA + (size_t)(t + 1) * kstep;
;             const char* a2 = last ? nA : cA + (size_t)(t + 2) * kstep; const char* b2 = last ? nB : cB + (size_t)(t + 2) * kstep;
;             const char* a3 = a2 + kstep; const char* b3 = b2 + kstep;
;             if (last && has_next) S.a_ready(nxt);
;             if constexpr (SP2) {
;             PG8_LDB(B0, 0, 0); PG8_LDB(B1, 0, 1); PG8_SCHED; PG8_LDA(At, 0, 0); PG8_STAGE(PG8_SA(1, 1), a1 + hstep, voffA);
;             PG8_WAIT_V(8); PG8_WAIT_L(0); PG8_BAR; PG8_MMA(0, 0, At, B0); PG8_MMA(0, 1, At, B1); PG8_BAR; PG8_SCHED;
;             PG8_LDA(At, 0, 1); PG8_STAGE(PG8_SB(0, 0), b2, voffB); PG8_STAGE(PG8_SB(0, 1), b2 + hstep, voffB); PG8_STAGE(PG8_SA(0, 0), a2, voffA);
;             PG8_WAIT_V(8); PG8_WAIT_L(0); PG8_BAR; PG8_MMA(1, 0, At, B0); PG8_MMA(1, 1, At, B1); PG8_BAR; PG8_SCHED;
.LBB0_352:
	s_ashr_i32 s27, s26, 31
	s_lshl_b64 s[30:31], s[26:27], 20
	s_add_u32 s30, s60, s30
	s_addc_u32 s31, s61, s31
	s_and_b64 s[34:35], s[6:7], exec
	s_cselect_b32 s27, s31, s53
	s_cselect_b32 s73, s30, s52
	s_ashr_i32 s29, s28, 31
	s_lshl_b64 s[34:35], s[28:29], 20
	s_add_u32 s34, s58, s34
	s_addc_u32 s35, s59, s35
	s_and_b64 s[54:55], s[6:7], exec
	s_cselect_b32 s29, s35, s51
	s_cselect_b32 s74, s34, s50
	s_add_u32 s75, s50, 0x100
	s_addc_u32 s76, s51, 0
	s_add_u32 s50, s52, 0x80080
	s_addc_u32 s51, s53, 0
	s_mov_b32 s77, -2
	ds_read_b128 v[128:131], v169
	ds_read_b128 v[132:135], v169 offset:1024
	ds_read_b128 v[136:139], v169 offset:2048
	ds_read_b128 v[140:143], v169 offset:3072
	ds_read_b128 v[160:163], v170
	ds_read_b128 v[172:175], v170 offset:1024
	ds_read_b128 v[176:179], v170 offset:2048
	ds_read_b128 v[180:183], v170 offset:3072
	s_add_u32 s52, s50, 0xfff80080
	s_addc_u32 s53, s51, -1
	s_cmp_eq_u32 s77, 28
	s_cselect_b32 s55, s27, s53
	s_cselect_b32 s54, s73, s52
	s_cselect_b32 s53, s29, s76
	s_cselect_b32 s52, s74, s75
	v_lshl_add_u64 v[164:165], s[50:51], 0, v[154:155]
	s_add_i32 m0, s37, 0xc000
	ds_read_b128 v[184:187], v171
	ds_read_b128 v[188:191], v171 offset:1024
	ds_read_b128 v[194:197], v171 offset:2048
	ds_read_b128 v[198:201], v171 offset:3072
	ds_read_b128 v[202:205], v171 offset:4096
	ds_read_b128 v[206:209], v171 offset:5120
	ds_read_b128 v[210:213], v171 offset:6144
	ds_read_b128 v[214:217], v171 offset:7168
	global_load_lds_dwordx4 v[164:165], off
	v_lshl_add_u64 v[164:165], s[50:51], 0, v[152:153]
	s_add_i32 m0, s37, 0xe000
	s_nop 0
	global_load_lds_dwordx4 v[164:165], off
	s_waitcnt vmcnt(8)
	s_waitcnt lgkmcnt(0)
	s_barrier
	s_setprio 1
	s_waitcnt lgkmcnt(0)
	v_mfma_f32_16x16x32_bf16 v[124:127], v[128:131], v[184:187], 0
	v_mfma_f32_16x16x32_bf16 v[120:123], v[136:139], v[184:187], 0
	v_mfma_f32_16x16x32_bf16 v[108:111], v[128:131], v[194:197], 0
	v_mfma_f32_16x16x32_bf16 v[104:107], v[136:139], v[194:197], 0
	v_mfma_f32_16x16x32_bf16 v[92:95], v[128:131], v[202:205], 0
	v_mfma_f32_16x16x32_bf16 v[88:91], v[136:139], v[202:205], 0
	v_mfma_f32_16x16x32_bf16 v[76:79], v[128:131], v[210:213], 0
	v_mfma_f32_16x16x32_bf16 v[72:75], v[136:139], v[210:213], 0
	v_mfma_f32_16x16x32_bf16 v[124:127], v[132:135], v[188:191], v[124:127]
	v_mfma_f32_16x16x32_bf16 v[120:123], v[140:143], v[188:191], v[120:123]
	v_mfma_f32_16x16x32_bf16 v[108:111], v[132:135], v[198:201], v[108:111]
	v_mfma_f32_16x16x32_bf16 v[104:107], v[140:143], v[198:201], v[104:107]
	v_mfma_f32_16x16x32_bf16 v[92:95], v[132:135], v[206:209], v[92:95]
	v_mfma_f32_16x16x32_bf16 v[88:91], v[140:143], v[206:209], v[88:91]
	v_mfma_f32_16x16x32_bf16 v[76:79], v[132:135], v[214:217], v[76:79]
	v_mfma_f32_16x16x32_bf16 v[72:75], v[140:143], v[214:217], v[72:75]
	s_setprio 0
	s_setprio 1
	v_mfma_f32_16x16x32_bf16 v[116:119], v[160:163], v[184:187], 0
	v_mfma_f32_16x16x32_bf16 v[112:115], v[176:179], v[184:187], 0
	v_mfma_f32_16x16x32_bf16 v[100:103], v[160:163], v[194:197], 0
	v_mfma_f32_16x16x32_bf16 v[96:99], v[176:179], v[194:197], 0
	v_mfma_f32_16x16x32_bf16 v[84:87], v[160:163], v[202:205], 0
	v_mfma_f32_16x16x32_bf16 v[80:83], v[176:179], v[202:205], 0
	v_mfma_f32_16x16x32_bf16 v[68:71], v[160:163], v[210:213], 0
	v_mfma_f32_16x16x32_bf16 v[64:67], v[176:179], v[210:213], 0
	v_mfma_f32_16x16x32_bf16 v[116:119], v[172:175], v[188:191], v[116:119]
	v_mfma_f32_16x16x32_bf16 v[112:115], v[180:183], v[188:191], v[112:115]
	v_mfma_f32_16x16x32_bf16 v[100:103], v[172:175], v[198:201], v[100:103]
	v_mfma_f32_16x16x32_bf16 v[96:99], v[180:183], v[198:201], v[96:99]
	v_mfma_f32_16x16x32_bf16 v[84:87], v[172:175], v[206:209], v[84:87]
	v_mfma_f32_16x16x32_bf16 v[80:83], v[180:183], v[206:209], v[80:83]
	v_mfma_f32_16x16x32_bf16 v[68:71], v[172:175], v[214:217], v[68:71]
	v_mfma_f32_16x16x32_bf16 v[64:67], v[180:183], v[214:217], v[64:67]
	s_setprio 0
	s_barrier
	s_add_i32 s78, s71, s62
	v_lshl_add_u64 v[164:165], s[52:53], 0, v[146:147]
	s_mov_b32 m0, s78
	ds_read_b128 v[184:187], v171 offset:16384
	ds_read_b128 v[188:191], v171 offset:17408
	ds_read_b128 v[194:197], v171 offset:18432
	ds_read_b128 v[198:201], v171 offset:19456
	ds_read_b128 v[202:205], v171 offset:20480
	ds_read_b128 v[206:209], v171 offset:21504
	ds_read_b128 v[210:213], v171 offset:22528
	ds_read_b128 v[214:217], v171 offset:23552
	global_load_lds_dwordx4 v[164:165], off
	s_add_i32 m0, s78, 0x2000
	s_add_u32 s78, s52, 0x80000
	v_lshl_add_u64 v[218:219], s[52:53], 0, v[150:151]
	s_addc_u32 s79, s53, 0
	s_add_i32 s80, s72, s62
	global_load_lds_dwordx4 v[218:219], off
	v_lshl_add_u64 v[220:221], s[78:79], 0, v[146:147]
	s_mov_b32 m0, s80
	v_lshl_add_u64 v[222:223], s[54:55], 0, v[148:149]
	global_load_lds_dwordx4 v[220:221], off
	v_lshl_add_u64 v[220:221], s[78:79], 0, v[150:151]
	s_add_i32 m0, s80, 0x2000
	s_nop 0
	global_load_lds_dwordx4 v[220:221], off
	v_lshl_add_u64 v[220:221], s[54:55], 0, v[144:145]
	s_mov_b32 m0, s37
	s_nop 0
	global_load_lds_dwordx4 v[220:221], off
	s_mov_b32 m0, s49
	s_nop 0
	global_load_lds_dwordx4 v[222:223], off
	s_waitcnt vmcnt(8)
	s_waitcnt lgkmcnt(0)
	s_barrier
; #define PG8_STAGE(bufoff, gbase, voff) do { _Pragma("unroll") for (int _i = 0; _i < 2; ++_i) \
;         __builtin_amdgcn_global_load_lds((const unsigned*)((const char*)(gbase) + (voff)[_i]), (PG8_LAS unsigned*)(lds + (bufoff) + ldsw + _i * 8192), 16, 0, 0); } while (0)
; #define PG8_LDA(dst, b, h) do { _Pragma("unroll") for (int m = 0; m < 4; ++m) _Pragma("unroll") for (int k = 0; k < 2; ++k) dst[m][k] = *(const PG8_LAS bf16x8*)(lds + PG8_SA(b, h) + aoff + m * 2048 + k * 1024); } while (0)
; #define PG8_LDB(dst, b, h) do { _Pragma("unroll") for (int n = 0; n < 2; ++n) _Pragma("unroll") for (int k = 0; k < 2; ++k) dst[n][k] = *(const PG8_LAS bf16x8*)(lds + PG8_SB(b, h) + boff + n * 2048 + k * 1024); } while (0)
; #define PG8_MMA(ai, bj, At, Bt) do { __builtin_amdgcn_s_setprio(1); _Pragma("unroll") for (int m = 0; m < 4; ++m) _Pragma("unroll") for (int n = 0; n < 2; ++n) _Pragma("unroll") for (int k = 0; k < 2; ++k) \
;         acc[ai][bj][m][n] = __builtin_amdgcn_mfma_f32_16x16x32_bf16(Bt[n][k], At[m][k], acc[ai][bj][m][n], 0, 0, 0); __builtin_amdgcn_s_setprio(0); } while (0)
; #define PG8_WAIT_V(n) asm volatile("s_waitcnt vmcnt(" #n ")" ::: "memory")
; #define PG8_WAIT_L(n) asm volatile("s_waitcnt lgkmcnt(" #n ")" ::: "memory")
; #define PG8_BAR __builtin_amdgcn_s_barrier()
; #define PG8_SCHED __builtin_amdgcn_sched_barrier(0)
; template <class Epi, class Sched, bool ALIGN_EPI = false, bool SP2 = false>
; __device__ __forceinline__ void gemm_phase(PG8_LAS unsigned char* lds, const Gemm g, const Sched& S, const Epi& E) {
;     ...
;             PG8_WAIT_V(8); PG8_WAIT_L(0); PG8_BAR; PG8_MMA(1, 0, At, B0); PG8_MMA(1, 1, At, B1); PG8_BAR; PG8_SCHED;
;             PG8_LDB(B0, 1, 0); PG8_LDB(B1, 1, 1); PG8_SCHED; PG8_LDA(At, 1, 0); PG8_STAGE(PG8_SA(0, 1), a2 + hstep, voffA);
;             PG8_WAIT_V(8); PG8_WAIT_L(0); PG8_BAR; PG8_MMA(0, 0, At, B0); PG8_MMA(0, 1, At, B1); PG8_BAR; PG8_SCHED;
	s_setprio 1
	s_waitcnt lgkmcnt(0)
	v_mfma_f32_16x16x32_bf16 v[60:63], v[128:131], v[184:187], 0
	v_mfma_f32_16x16x32_bf16 v[56:59], v[136:139], v[184:187], 0
	v_mfma_f32_16x16x32_bf16 v[44:47], v[128:131], v[194:197], 0
	v_mfma_f32_16x16x32_bf16 v[40:43], v[136:139], v[194:197], 0
	v_mfma_f32_16x16x32_bf16 v[28:31], v[128:131], v[202:205], 0
	v_mfma_f32_16x16x32_bf16 v[24:27], v[136:139], v[202:205], 0
	v_mfma_f32_16x16x32_bf16 v[12:15], v[128:131], v[210:213], 0
	v_mfma_f32_16x16x32_bf16 v[8:11], v[136:139], v[210:213], 0
	v_mfma_f32_16x16x32_bf16 v[60:63], v[132:135], v[188:191], v[60:63]
	v_mfma_f32_16x16x32_bf16 v[56:59], v[140:143], v[188:191], v[56:59]
	v_mfma_f32_16x16x32_bf16 v[44:47], v[132:135], v[198:201], v[44:47]
	v_mfma_f32_16x16x32_bf16 v[40:43], v[140:143], v[198:201], v[40:43]
	v_mfma_f32_16x16x32_bf16 v[28:31], v[132:135], v[206:209], v[28:31]
	v_mfma_f32_16x16x32_bf16 v[24:27], v[140:143], v[206:209], v[24:27]
	v_mfma_f32_16x16x32_bf16 v[12:15], v[132:135], v[214:217], v[12:15]
	v_mfma_f32_16x16x32_bf16 v[8:11], v[140:143], v[214:217], v[8:11]
	s_setprio 0
	s_setprio 1
	v_mfma_f32_16x16x32_bf16 v[52:55], v[160:163], v[184:187], 0
	v_mfma_f32_16x16x32_bf16 v[48:51], v[176:179], v[184:187], 0
	v_mfma_f32_16x16x32_bf16 v[36:39], v[160:163], v[194:197], 0
	v_mfma_f32_16x16x32_bf16 v[32:35], v[176:179], v[194:197], 0
	v_mfma_f32_16x16x32_bf16 v[20:23], v[160:163], v[202:205], 0
	v_mfma_f32_16x16x32_bf16 v[16:19], v[176:179], v[202:205], 0
	v_mfma_f32_16x16x32_bf16 v[4:7], v[160:163], v[210:213], 0
	v_mfma_f32_16x16x32_bf16 v[0:3], v[176:179], v[210:213], 0
	v_mfma_f32_16x16x32_bf16 v[52:55], v[172:175], v[188:191], v[52:55]
	v_mfma_f32_16x16x32_bf16 v[48:51], v[180:183], v[188:191], v[48:51]
	v_mfma_f32_16x16x32_bf16 v[36:39], v[172:175], v[198:201], v[36:39]
	v_mfma_f32_16x16x32_bf16 v[32:35], v[180:183], v[198:201], v[32:35]
	v_mfma_f32_16x16x32_bf16 v[20:23], v[172:175], v[206:209], v[20:23]
	v_mfma_f32_16x16x32_bf16 v[16:19], v[180:183], v[206:209], v[16:19]
	v_mfma_f32_16x16x32_bf16 v[4:7], v[172:175], v[214:217], v[4:7]
	v_mfma_f32_16x16x32_bf16 v[0:3], v[180:183], v[214:217], v[0:3]
	s_setprio 0
	s_barrier
	s_add_i32 s78, 0, 0x18000
	s_add_i32 s79, 0, 0x1c000
	v_add_u32_e32 v140, s78, v167
	v_add_u32_e32 v180, s79, v167
	ds_read_b128 v[128:131], v140
	ds_read_b128 v[132:135], v140 offset:1024
	ds_read_b128 v[136:139], v140 offset:2048
	ds_read_b128 v[140:143], v140 offset:3072
	ds_read_b128 v[160:163], v180
	ds_read_b128 v[172:175], v180 offset:1024
	ds_read_b128 v[176:179], v180 offset:2048
	ds_read_b128 v[180:183], v180 offset:3072
	s_add_u32 s54, s54, 0x80000
	s_addc_u32 s55, s55, 0
	s_mov_b32 m0, s63
	v_lshl_add_u64 v[224:225], s[54:55], 0, v[144:145]
	ds_read_b128 v[184:187], v171 offset:32768
	ds_read_b128 v[188:191], v171 offset:33792
	ds_read_b128 v[194:197], v171 offset:34816
	ds_read_b128 v[198:201], v171 offset:35840
	ds_read_b128 v[202:205], v171 offset:36864
	ds_read_b128 v[206:209], v171 offset:37888
	ds_read_b128 v[210:213], v171 offset:38912
	ds_read_b128 v[214:217], v171 offset:39936
	global_load_lds_dwordx4 v[224:225], off
	v_lshl_add_u64 v[224:225], s[54:55], 0, v[148:149]
	s_mov_b32 m0, s64
	s_nop 0
	global_load_lds_dwordx4 v[224:225], off
	s_waitcnt vmcnt(8)
	s_waitcnt lgkmcnt(0)
	s_barrier
	s_setprio 1
	s_waitcnt lgkmcnt(0)
	v_mfma_f32_16x16x32_bf16 v[124:127], v[128:131], v[184:187], v[124:127]
	v_mfma_f32_16x16x32_bf16 v[120:123], v[136:139], v[184:187], v[120:123]
	v_mfma_f32_16x16x32_bf16 v[108:111], v[128:131], v[194:197], v[108:111]
	v_mfma_f32_16x16x32_bf16 v[104:107], v[136:139], v[194:197], v[104:107]
	v_mfma_f32_16x16x32_bf16 v[92:95], v[128:131], v[202:205], v[92:95]
	v_mfma_f32_16x16x32_bf16 v[88:91], v[136:139], v[202:205], v[88:91]
	v_mfma_f32_16x16x32_bf16 v[76:79], v[128:131], v[210:213], v[76:79]
	v_mfma_f32_16x16x32_bf16 v[72:75], v[136:139], v[210:213], v[72:75]
	v_mfma_f32_16x16x32_bf16 v[124:127], v[132:135], v[188:191], v[124:127]
	v_mfma_f32_16x16x32_bf16 v[120:123], v[140:143], v[188:191], v[120:123]
	v_mfma_f32_16x16x32_bf16 v[108:111], v[132:135], v[198:201], v[108:111]
	v_mfma_f32_16x16x32_bf16 v[104:107], v[140:143], v[198:201], v[104:107]
	v_mfma_f32_16x16x32_bf16 v[92:95], v[132:135], v[206:209], v[92:95]
	v_mfma_f32_16x16x32_bf16 v[88:91], v[140:143], v[206:209], v[88:91]
	v_mfma_f32_16x16x32_bf16 v[76:79], v[132:135], v[214:217], v[76:79]
	v_mfma_f32_16x16x32_bf16 v[72:75], v[140:143], v[214:217], v[72:75]
	s_setprio 0
	s_setprio 1
	v_mfma_f32_16x16x32_bf16 v[116:119], v[160:163], v[184:187], v[116:119]
	v_mfma_f32_16x16x32_bf16 v[112:115], v[176:179], v[184:187], v[112:115]
	v_mfma_f32_16x16x32_bf16 v[100:103], v[160:163], v[194:197], v[100:103]
	v_mfma_f32_16x16x32_bf16 v[96:99], v[176:179], v[194:197], v[96:99]
	v_mfma_f32_16x16x32_bf16 v[84:87], v[160:163], v[202:205], v[84:87]
	v_mfma_f32_16x16x32_bf16 v[80:83], v[176:179], v[202:205], v[80:83]
	v_mfma_f32_16x16x32_bf16 v[68:71], v[160:163], v[210:213], v[68:71]
	v_mfma_f32_16x16x32_bf16 v[64:67], v[176:179], v[210:213], v[64:67]
	v_mfma_f32_16x16x32_bf16 v[116:119], v[172:175], v[188:191], v[116:119]
	v_mfma_f32_16x16x32_bf16 v[112:115], v[180:183], v[188:191], v[112:115]
	v_mfma_f32_16x16x32_bf16 v[100:103], v[172:175], v[198:201], v[100:103]
	v_mfma_f32_16x16x32_bf16 v[96:99], v[180:183], v[198:201], v[96:99]
	v_mfma_f32_16x16x32_bf16 v[84:87], v[172:175], v[206:209], v[84:87]
	v_mfma_f32_16x16x32_bf16 v[80:83], v[180:183], v[206:209], v[80:83]
	v_mfma_f32_16x16x32_bf16 v[68:71], v[172:175], v[214:217], v[68:71]
	v_mfma_f32_16x16x32_bf16 v[64:67], v[180:183], v[214:217], v[64:67]
	s_setprio 0
	s_barrier
; #define PG8_STAGE(bufoff, gbase, voff) do { _Pragma("unroll") for (int _i = 0; _i < 2; ++_i) \
;         __builtin_amdgcn_global_load_lds((const unsigned*)((const char*)(gbase) + (voff)[_i]), (PG8_LAS unsigned*)(lds + (bufoff) + ldsw + _i * 8192), 16, 0, 0); } while (0)
; #define PG8_LDA(dst, b, h) do { _Pragma("unroll") for (int m = 0; m < 4; ++m) _Pragma("unroll") for (int k = 0; k < 2; ++k) dst[m][k] = *(const PG8_LAS bf16x8*)(lds + PG8_SA(b, h) + aoff + m * 2048 + k * 1024); } while (0)
; #define PG8_MMA(ai, bj, At, Bt) do { __builtin_amdgcn_s_setprio(1); _Pragma("unroll") for (int m = 0; m < 4; ++m) _Pragma("unroll") for (int n = 0; n < 2; ++n) _Pragma("unroll") for (int k = 0; k < 2; ++k) \
;         acc[ai][bj][m][n] = __builtin_amdgcn_mfma_f32_16x16x32_bf16(Bt[n][k], At[m][k], acc[ai][bj][m][n], 0, 0, 0); __builtin_amdgcn_s_setprio(0); } while (0)
; #define PG8_WAIT_V(n) asm volatile("s_waitcnt vmcnt(" #n ")" ::: "memory")
; #define PG8_WAIT_L(n) asm volatile("s_waitcnt lgkmcnt(" #n ")" ::: "memory")
; #define PG8_BAR __builtin_amdgcn_s_barrier()
; #define PG8_SCHED __builtin_amdgcn_sched_barrier(0)
; template <class Epi, class Sched, bool ALIGN_EPI = false, bool SP2 = false>
; __device__ __forceinline__ void gemm_phase(PG8_LAS unsigned char* lds, const Gemm g, const Sched& S, const Epi& E) {
;     ...
;         for (int t = 0; t < nt; t += 2) {
;             const bool last = (t == nt - 2);
;     ...
;             PG8_LDA(At, 1, 1); PG8_STAGE(PG8_SB(1, 0), b3, voffB); PG8_STAGE(PG8_SB(1, 1), b3 + hstep, voffB); PG8_STAGE(PG8_SA(1, 0), a3, voffA);
;             PG8_WAIT_V(8); PG8_WAIT_L(0); PG8_BAR; PG8_MMA(1, 0, At, B0); PG8_MMA(1, 1, At, B1); PG8_BAR; PG8_SCHED;
	s_add_i32 s54, s78, s62
	v_lshl_add_u64 v[164:165], v[164:165], 0, s[14:15]
	s_mov_b32 m0, s54
	ds_read_b128 v[184:187], v171 offset:49152
	ds_read_b128 v[188:191], v171 offset:50176
	ds_read_b128 v[194:197], v171 offset:51200
	ds_read_b128 v[198:201], v171 offset:52224
	ds_read_b128 v[202:205], v171 offset:53248
	ds_read_b128 v[206:209], v171 offset:54272
	ds_read_b128 v[210:213], v171 offset:55296
	ds_read_b128 v[214:217], v171 offset:56320
	global_load_lds_dwordx4 v[164:165], off
	s_add_i32 m0, s54, 0x2000
	s_add_u32 s52, s52, 0x80080
	v_lshl_add_u64 v[164:165], v[218:219], 0, s[14:15]
	s_addc_u32 s53, s53, 0
	s_add_i32 s54, s79, s62
	global_load_lds_dwordx4 v[164:165], off
	v_lshl_add_u64 v[164:165], s[52:53], 0, v[146:147]
	s_mov_b32 m0, s54
	s_nop 0
	global_load_lds_dwordx4 v[164:165], off
	v_lshl_add_u64 v[164:165], s[52:53], 0, v[150:151]
	s_add_i32 m0, s54, 0x2000
	s_nop 0
	global_load_lds_dwordx4 v[164:165], off
	v_lshl_add_u64 v[164:165], v[220:221], 0, s[14:15]
	s_mov_b32 m0, s68
	s_nop 0
	global_load_lds_dwordx4 v[164:165], off
	v_lshl_add_u64 v[164:165], v[222:223], 0, s[14:15]
	s_mov_b32 m0, s69
	s_nop 0
	global_load_lds_dwordx4 v[164:165], off
	s_waitcnt vmcnt(8)
	s_waitcnt lgkmcnt(0)
	s_barrier
	s_setprio 1
	s_waitcnt lgkmcnt(0)
	v_mfma_f32_16x16x32_bf16 v[60:63], v[128:131], v[184:187], v[60:63]
	v_mfma_f32_16x16x32_bf16 v[56:59], v[136:139], v[184:187], v[56:59]
	v_mfma_f32_16x16x32_bf16 v[44:47], v[128:131], v[194:197], v[44:47]
	v_mfma_f32_16x16x32_bf16 v[40:43], v[136:139], v[194:197], v[40:43]
	v_mfma_f32_16x16x32_bf16 v[28:31], v[128:131], v[202:205], v[28:31]
	v_mfma_f32_16x16x32_bf16 v[24:27], v[136:139], v[202:205], v[24:27]
	v_mfma_f32_16x16x32_bf16 v[12:15], v[128:131], v[210:213], v[12:15]
	v_mfma_f32_16x16x32_bf16 v[8:11], v[136:139], v[210:213], v[8:11]
	v_mfma_f32_16x16x32_bf16 v[60:63], v[132:135], v[188:191], v[60:63]
	v_mfma_f32_16x16x32_bf16 v[56:59], v[140:143], v[188:191], v[56:59]
	v_mfma_f32_16x16x32_bf16 v[44:47], v[132:135], v[198:201], v[44:47]
	v_mfma_f32_16x16x32_bf16 v[40:43], v[140:143], v[198:201], v[40:43]
	v_mfma_f32_16x16x32_bf16 v[28:31], v[132:135], v[206:209], v[28:31]
	v_mfma_f32_16x16x32_bf16 v[24:27], v[140:143], v[206:209], v[24:27]
	v_mfma_f32_16x16x32_bf16 v[12:15], v[132:135], v[214:217], v[12:15]
	v_mfma_f32_16x16x32_bf16 v[8:11], v[140:143], v[214:217], v[8:11]
	s_setprio 0
	s_setprio 1
	v_mfma_f32_16x16x32_bf16 v[52:55], v[160:163], v[184:187], v[52:55]
	v_mfma_f32_16x16x32_bf16 v[48:51], v[176:179], v[184:187], v[48:51]
	v_mfma_f32_16x16x32_bf16 v[36:39], v[160:163], v[194:197], v[36:39]
	v_mfma_f32_16x16x32_bf16 v[32:35], v[176:179], v[194:197], v[32:35]
	v_mfma_f32_16x16x32_bf16 v[20:23], v[160:163], v[202:205], v[20:23]
	v_mfma_f32_16x16x32_bf16 v[16:19], v[176:179], v[202:205], v[16:19]
	v_mfma_f32_16x16x32_bf16 v[4:7], v[160:163], v[210:213], v[4:7]
	v_mfma_f32_16x16x32_bf16 v[0:3], v[176:179], v[210:213], v[0:3]
	v_mfma_f32_16x16x32_bf16 v[52:55], v[172:175], v[188:191], v[52:55]
	v_mfma_f32_16x16x32_bf16 v[48:51], v[180:183], v[188:191], v[48:51]
	v_mfma_f32_16x16x32_bf16 v[36:39], v[172:175], v[198:201], v[36:39]
	v_mfma_f32_16x16x32_bf16 v[32:35], v[180:183], v[198:201], v[32:35]
	v_mfma_f32_16x16x32_bf16 v[20:23], v[172:175], v[206:209], v[20:23]
	v_mfma_f32_16x16x32_bf16 v[16:19], v[180:183], v[206:209], v[16:19]
	v_mfma_f32_16x16x32_bf16 v[4:7], v[172:175], v[214:217], v[4:7]
	v_mfma_f32_16x16x32_bf16 v[0:3], v[180:183], v[214:217], v[0:3]
	s_setprio 0
	s_barrier
	s_add_i32 s77, s77, 2
	s_add_u32 s75, s75, 0x100
	s_addc_u32 s76, s76, 0
	s_add_u32 s50, s50, 0x100
	s_addc_u32 s51, s51, 0
	s_cmp_gt_u32 s77, 29
	s_cbranch_scc1 .Lpeel_exit_1
	.p2align	6

; #define PG8_STAGE(bufoff, gbase, voff) do { _Pragma("unroll") for (int _i = 0; _i < 2; ++_i) \
;         __builtin_amdgcn_global_load_lds((const unsigned*)((const char*)(gbase) + (voff)[_i]), (PG8_LAS unsigned*)(lds + (bufoff) + ldsw + _i * 8192), 16, 0, 0); } while (0)
; #define PG8_LDA(dst, b, h) do { _Pragma("unroll") for (int m = 0; m < 4; ++m) _Pragma("unroll") for (int k = 0; k < 2; ++k) dst[m][k] = *(const PG8_LAS bf16x8*)(lds + PG8_SA(b, h) + aoff + m * 2048 + k * 1024); } while (0)
; #define PG8_LDB(dst, b, h) do { _Pragma("unroll") for (int n = 0; n < 2; ++n) _Pragma("unroll") for (int k = 0; k < 2; ++k) dst[n][k] = *(const PG8_LAS bf16x8*)(lds + PG8_SB(b, h) + boff + n * 2048 + k * 1024); } while (0)
; #define PG8_MMA(ai, bj, At, Bt) do { __builtin_amdgcn_s_setprio(1); _Pragma("unroll") for (int m = 0; m < 4; ++m) _Pragma("unroll") for (int n = 0; n < 2; ++n) _Pragma("unroll") for (int k = 0; k < 2; ++k) \
;         acc[ai][bj][m][n] = __builtin_amdgcn_mfma_f32_16x16x32_bf16(Bt[n][k], At[m][k], acc[ai][bj][m][n], 0, 0, 0); __builtin_amdgcn_s_setprio(0); } while (0)
; #define PG8_WAIT_V(n) asm volatile("s_waitcnt vmcnt(" #n ")" ::: "memory")
; #define PG8_WAIT_L(n) asm volatile("s_waitcnt lgkmcnt(" #n ")" ::: "memory")
; template <class Epi, class Sched, bool ALIGN_EPI = false, bool SP2 = false>
; __device__ __forceinline__ void gemm_phase(PG8_LAS unsigned char* lds, const Gemm g, const Sched& S, const Epi& E) {
;     ...
;             const bool last = (t == nt - 2);
;             const char* a1 = cA + (size_t)(t + 1) * kstep;
;             const char* a2 = last ? nA : cA + (size_t)(t + 2) * kstep; const char* b2 = last ? nB : cB + (size_t)(t + 2) * kstep;
;             const char* a3 = a2 + kstep; const char* b3 = b2 + kstep;
;             if (last && has_next) S.a_ready(nxt);
;             if constexpr (SP2) {
;             PG8_LDB(B0, 0, 0); PG8_LDB(B1, 0, 1); PG8_SCHED; PG8_LDA(At, 0, 0); PG8_STAGE(PG8_SA(1, 1), a1 + hstep, voffA);
;             PG8_WAIT_V(8); PG8_WAIT_L(0); PG8_BAR; PG8_MMA(0, 0, At, B0); PG8_MMA(0, 1, At, B1); PG8_BAR; PG8_SCHED;
;             PG8_LDA(At, 0, 1); PG8_STAGE(PG8_SB(0, 0), b2, voffB); PG8_STAGE(PG8_SB(0, 1), b2 + hstep, voffB); PG8_STAGE(PG8_SA(0, 0), a2, voffA);
;             PG8_WAIT_V(8); PG8_WAIT_L(0); PG8_BAR; PG8_MMA(1, 0, At, B0); PG8_MMA(1, 1, At, B1); PG8_BAR; PG8_SCHED;
.LBB0_480:
	s_ashr_i32 s17, s16, 31
	s_lshl_b64 s[20:21], s[16:17], 20
	s_add_u32 s20, s49, s20
	s_addc_u32 s21, s50, s21
	s_and_b64 s[22:23], s[6:7], exec
	s_cselect_b32 s17, s21, s31
	s_cselect_b32 s63, s20, s30
	s_ashr_i32 s19, s18, 31
	s_lshl_b64 s[22:23], s[18:19], 20
	s_add_u32 s22, s37, s22
	s_addc_u32 s23, s48, s23
	s_and_b64 s[34:35], s[6:7], exec
	s_cselect_b32 s19, s23, s29
	s_cselect_b32 s64, s22, s28
	s_add_u32 s65, s28, 0x100
	s_addc_u32 s66, s29, 0
	s_add_u32 s28, s30, 0x80080
	s_addc_u32 s29, s31, 0
	s_mov_b32 s67, -2
	ds_read_b128 v[144:147], v151
	ds_read_b128 v[154:157], v151 offset:1024
	ds_read_b128 v[158:161], v151 offset:2048
	ds_read_b128 v[162:165], v151 offset:3072
	ds_read_b128 v[166:169], v152
	ds_read_b128 v[170:173], v152 offset:1024
	ds_read_b128 v[174:177], v152 offset:2048
	ds_read_b128 v[178:181], v152 offset:3072
	s_add_u32 s30, s28, 0xfff80080
	s_addc_u32 s31, s29, -1
	s_cmp_eq_u32 s67, 28
	s_cselect_b32 s35, s17, s31
	s_cselect_b32 s34, s63, s30
	s_cselect_b32 s31, s19, s66
	s_cselect_b32 s30, s64, s65
	v_lshl_add_u64 v[190:191], s[28:29], 0, v[138:139]
	s_add_i32 m0, s25, 0xc000
	ds_read_b128 v[182:185], v153
	ds_read_b128 v[186:189], v153 offset:1024
	ds_read_b128 v[194:197], v153 offset:2048
	ds_read_b128 v[198:201], v153 offset:3072
	ds_read_b128 v[202:205], v153 offset:4096
	ds_read_b128 v[206:209], v153 offset:5120
	ds_read_b128 v[210:213], v153 offset:6144
	ds_read_b128 v[214:217], v153 offset:7168
	global_load_lds_dwordx4 v[190:191], off
	v_lshl_add_u64 v[190:191], s[28:29], 0, v[136:137]
	s_add_i32 m0, s25, 0xe000
	s_nop 0
	global_load_lds_dwordx4 v[190:191], off
	s_waitcnt vmcnt(8)
	s_waitcnt lgkmcnt(0)
	s_barrier
	s_setprio 1
	s_waitcnt lgkmcnt(0)
	v_mfma_f32_16x16x32_bf16 v[124:127], v[144:147], v[182:185], 0
	v_mfma_f32_16x16x32_bf16 v[120:123], v[158:161], v[182:185], 0
	v_mfma_f32_16x16x32_bf16 v[108:111], v[144:147], v[194:197], 0
	v_mfma_f32_16x16x32_bf16 v[104:107], v[158:161], v[194:197], 0
	v_mfma_f32_16x16x32_bf16 v[92:95], v[144:147], v[202:205], 0
	v_mfma_f32_16x16x32_bf16 v[88:91], v[158:161], v[202:205], 0
	v_mfma_f32_16x16x32_bf16 v[76:79], v[144:147], v[210:213], 0
	v_mfma_f32_16x16x32_bf16 v[72:75], v[158:161], v[210:213], 0
	v_mfma_f32_16x16x32_bf16 v[124:127], v[154:157], v[186:189], v[124:127]
	v_mfma_f32_16x16x32_bf16 v[120:123], v[162:165], v[186:189], v[120:123]
	v_mfma_f32_16x16x32_bf16 v[108:111], v[154:157], v[198:201], v[108:111]
	v_mfma_f32_16x16x32_bf16 v[104:107], v[162:165], v[198:201], v[104:107]
	v_mfma_f32_16x16x32_bf16 v[92:95], v[154:157], v[206:209], v[92:95]
	v_mfma_f32_16x16x32_bf16 v[88:91], v[162:165], v[206:209], v[88:91]
	v_mfma_f32_16x16x32_bf16 v[76:79], v[154:157], v[214:217], v[76:79]
	v_mfma_f32_16x16x32_bf16 v[72:75], v[162:165], v[214:217], v[72:75]
	s_setprio 0
	s_setprio 1
	v_mfma_f32_16x16x32_bf16 v[116:119], v[166:169], v[182:185], 0
	v_mfma_f32_16x16x32_bf16 v[112:115], v[174:177], v[182:185], 0
	v_mfma_f32_16x16x32_bf16 v[100:103], v[166:169], v[194:197], 0
	v_mfma_f32_16x16x32_bf16 v[96:99], v[174:177], v[194:197], 0
	v_mfma_f32_16x16x32_bf16 v[84:87], v[166:169], v[202:205], 0
	v_mfma_f32_16x16x32_bf16 v[80:83], v[174:177], v[202:205], 0
	v_mfma_f32_16x16x32_bf16 v[68:71], v[166:169], v[210:213], 0
	v_mfma_f32_16x16x32_bf16 v[64:67], v[174:177], v[210:213], 0
	v_mfma_f32_16x16x32_bf16 v[116:119], v[170:173], v[186:189], v[116:119]
	v_mfma_f32_16x16x32_bf16 v[112:115], v[178:181], v[186:189], v[112:115]
	v_mfma_f32_16x16x32_bf16 v[100:103], v[170:173], v[198:201], v[100:103]
	v_mfma_f32_16x16x32_bf16 v[96:99], v[178:181], v[198:201], v[96:99]
	v_mfma_f32_16x16x32_bf16 v[84:87], v[170:173], v[206:209], v[84:87]
	v_mfma_f32_16x16x32_bf16 v[80:83], v[178:181], v[206:209], v[80:83]
	v_mfma_f32_16x16x32_bf16 v[68:71], v[170:173], v[214:217], v[68:71]
	v_mfma_f32_16x16x32_bf16 v[64:67], v[178:181], v[214:217], v[64:67]
	s_setprio 0
	s_barrier
	s_add_i32 s68, s60, s51
	v_lshl_add_u64 v[190:191], s[30:31], 0, v[132:133]
	s_mov_b32 m0, s68
	ds_read_b128 v[182:185], v153 offset:16384
	ds_read_b128 v[186:189], v153 offset:17408
	ds_read_b128 v[194:197], v153 offset:18432
	ds_read_b128 v[198:201], v153 offset:19456
	ds_read_b128 v[202:205], v153 offset:20480
	ds_read_b128 v[206:209], v153 offset:21504
	ds_read_b128 v[210:213], v153 offset:22528
	ds_read_b128 v[214:217], v153 offset:23552
	global_load_lds_dwordx4 v[190:191], off
	s_add_i32 m0, s68, 0x2000
	s_add_u32 s68, s30, 0x80000
	v_lshl_add_u64 v[218:219], s[30:31], 0, v[128:129]
	s_addc_u32 s69, s31, 0
	s_add_i32 s70, s61, s51
	global_load_lds_dwordx4 v[218:219], off
	v_lshl_add_u64 v[220:221], s[68:69], 0, v[132:133]
	s_mov_b32 m0, s70
	v_lshl_add_u64 v[222:223], s[34:35], 0, v[130:131]
	global_load_lds_dwordx4 v[220:221], off
	v_lshl_add_u64 v[220:221], s[68:69], 0, v[128:129]
	s_add_i32 m0, s70, 0x2000
	s_nop 0
	global_load_lds_dwordx4 v[220:221], off
	v_lshl_add_u64 v[220:221], s[34:35], 0, v[134:135]
	s_mov_b32 m0, s25
	s_nop 0
	global_load_lds_dwordx4 v[220:221], off
	s_mov_b32 m0, s27
	s_nop 0
	global_load_lds_dwordx4 v[222:223], off
	s_waitcnt vmcnt(8)
	s_waitcnt lgkmcnt(0)
	s_barrier
; #define PG8_STAGE(bufoff, gbase, voff) do { _Pragma("unroll") for (int _i = 0; _i < 2; ++_i) \
;         __builtin_amdgcn_global_load_lds((const unsigned*)((const char*)(gbase) + (voff)[_i]), (PG8_LAS unsigned*)(lds + (bufoff) + ldsw + _i * 8192), 16, 0, 0); } while (0)
; #define PG8_LDA(dst, b, h) do { _Pragma("unroll") for (int m = 0; m < 4; ++m) _Pragma("unroll") for (int k = 0; k < 2; ++k) dst[m][k] = *(const PG8_LAS bf16x8*)(lds + PG8_SA(b, h) + aoff + m * 2048 + k * 1024); } while (0)
; #define PG8_LDB(dst, b, h) do { _Pragma("unroll") for (int n = 0; n < 2; ++n) _Pragma("unroll") for (int k = 0; k < 2; ++k) dst[n][k] = *(const PG8_LAS bf16x8*)(lds + PG8_SB(b, h) + boff + n * 2048 + k * 1024); } while (0)
; #define PG8_MMA(ai, bj, At, Bt) do { __builtin_amdgcn_s_setprio(1); _Pragma("unroll") for (int m = 0; m < 4; ++m) _Pragma("unroll") for (int n = 0; n < 2; ++n) _Pragma("unroll") for (int k = 0; k < 2; ++k) \
;         acc[ai][bj][m][n] = __builtin_amdgcn_mfma_f32_16x16x32_bf16(Bt[n][k], At[m][k], acc[ai][bj][m][n], 0, 0, 0); __builtin_amdgcn_s_setprio(0); } while (0)
; #define PG8_WAIT_V(n) asm volatile("s_waitcnt vmcnt(" #n ")" ::: "memory")
; #define PG8_WAIT_L(n) asm volatile("s_waitcnt lgkmcnt(" #n ")" ::: "memory")
; #define PG8_BAR __builtin_amdgcn_s_barrier()
; #define PG8_SCHED __builtin_amdgcn_sched_barrier(0)
; template <class Epi, class Sched, bool ALIGN_EPI = false, bool SP2 = false>
; __device__ __forceinline__ void gemm_phase(PG8_LAS unsigned char* lds, const Gemm g, const Sched& S, const Epi& E) {
;     ...
;             PG8_WAIT_V(8); PG8_WAIT_L(0); PG8_BAR; PG8_MMA(1, 0, At, B0); PG8_MMA(1, 1, At, B1); PG8_BAR; PG8_SCHED;
;             PG8_LDB(B0, 1, 0); PG8_LDB(B1, 1, 1); PG8_SCHED; PG8_LDA(At, 1, 0); PG8_STAGE(PG8_SA(0, 1), a2 + hstep, voffA);
;             PG8_WAIT_V(8); PG8_WAIT_L(0); PG8_BAR; PG8_MMA(0, 0, At, B0); PG8_MMA(0, 1, At, B1); PG8_BAR; PG8_SCHED;
	s_setprio 1
	s_waitcnt lgkmcnt(0)
	v_mfma_f32_16x16x32_bf16 v[60:63], v[144:147], v[182:185], 0
	v_mfma_f32_16x16x32_bf16 v[56:59], v[158:161], v[182:185], 0
	v_mfma_f32_16x16x32_bf16 v[44:47], v[144:147], v[194:197], 0
	v_mfma_f32_16x16x32_bf16 v[40:43], v[158:161], v[194:197], 0
	v_mfma_f32_16x16x32_bf16 v[28:31], v[144:147], v[202:205], 0
	v_mfma_f32_16x16x32_bf16 v[24:27], v[158:161], v[202:205], 0
	v_mfma_f32_16x16x32_bf16 v[12:15], v[144:147], v[210:213], 0
	v_mfma_f32_16x16x32_bf16 v[8:11], v[158:161], v[210:213], 0
	v_mfma_f32_16x16x32_bf16 v[60:63], v[154:157], v[186:189], v[60:63]
	v_mfma_f32_16x16x32_bf16 v[56:59], v[162:165], v[186:189], v[56:59]
	v_mfma_f32_16x16x32_bf16 v[44:47], v[154:157], v[198:201], v[44:47]
	v_mfma_f32_16x16x32_bf16 v[40:43], v[162:165], v[198:201], v[40:43]
	v_mfma_f32_16x16x32_bf16 v[28:31], v[154:157], v[206:209], v[28:31]
	v_mfma_f32_16x16x32_bf16 v[24:27], v[162:165], v[206:209], v[24:27]
	v_mfma_f32_16x16x32_bf16 v[12:15], v[154:157], v[214:217], v[12:15]
	v_mfma_f32_16x16x32_bf16 v[8:11], v[162:165], v[214:217], v[8:11]
	s_setprio 0
	s_setprio 1
	v_mfma_f32_16x16x32_bf16 v[52:55], v[166:169], v[182:185], 0
	v_mfma_f32_16x16x32_bf16 v[48:51], v[174:177], v[182:185], 0
	v_mfma_f32_16x16x32_bf16 v[36:39], v[166:169], v[194:197], 0
	v_mfma_f32_16x16x32_bf16 v[32:35], v[174:177], v[194:197], 0
	v_mfma_f32_16x16x32_bf16 v[20:23], v[166:169], v[202:205], 0
	v_mfma_f32_16x16x32_bf16 v[16:19], v[174:177], v[202:205], 0
	v_mfma_f32_16x16x32_bf16 v[4:7], v[166:169], v[210:213], 0
	v_mfma_f32_16x16x32_bf16 v[0:3], v[174:177], v[210:213], 0
	v_mfma_f32_16x16x32_bf16 v[52:55], v[170:173], v[186:189], v[52:55]
	v_mfma_f32_16x16x32_bf16 v[48:51], v[178:181], v[186:189], v[48:51]
	v_mfma_f32_16x16x32_bf16 v[36:39], v[170:173], v[198:201], v[36:39]
	v_mfma_f32_16x16x32_bf16 v[32:35], v[178:181], v[198:201], v[32:35]
	v_mfma_f32_16x16x32_bf16 v[20:23], v[170:173], v[206:209], v[20:23]
	v_mfma_f32_16x16x32_bf16 v[16:19], v[178:181], v[206:209], v[16:19]
	v_mfma_f32_16x16x32_bf16 v[4:7], v[170:173], v[214:217], v[4:7]
	v_mfma_f32_16x16x32_bf16 v[0:3], v[178:181], v[214:217], v[0:3]
	s_setprio 0
	s_barrier
	s_add_i32 s68, 0, 0x18000
	s_add_i32 s69, 0, 0x1c000
	v_add_u32_e32 v162, s68, v149
	v_add_u32_e32 v178, s69, v149
	ds_read_b128 v[144:147], v162
	ds_read_b128 v[154:157], v162 offset:1024
	ds_read_b128 v[158:161], v162 offset:2048
	ds_read_b128 v[162:165], v162 offset:3072
	ds_read_b128 v[166:169], v178
	ds_read_b128 v[170:173], v178 offset:1024
	ds_read_b128 v[174:177], v178 offset:2048
	ds_read_b128 v[178:181], v178 offset:3072
	s_add_u32 s34, s34, 0x80000
	s_addc_u32 s35, s35, 0
	s_mov_b32 m0, s54
	v_lshl_add_u64 v[224:225], s[34:35], 0, v[134:135]
	ds_read_b128 v[182:185], v153 offset:32768
	ds_read_b128 v[186:189], v153 offset:33792
	ds_read_b128 v[194:197], v153 offset:34816
	ds_read_b128 v[198:201], v153 offset:35840
	ds_read_b128 v[202:205], v153 offset:36864
	ds_read_b128 v[206:209], v153 offset:37888
	ds_read_b128 v[210:213], v153 offset:38912
	ds_read_b128 v[214:217], v153 offset:39936
	global_load_lds_dwordx4 v[224:225], off
	v_lshl_add_u64 v[224:225], s[34:35], 0, v[130:131]
	s_mov_b32 m0, s55
	s_nop 0
	global_load_lds_dwordx4 v[224:225], off
	s_waitcnt vmcnt(8)
	s_waitcnt lgkmcnt(0)
	s_barrier
	s_setprio 1
	s_waitcnt lgkmcnt(0)
	v_mfma_f32_16x16x32_bf16 v[124:127], v[144:147], v[182:185], v[124:127]
	v_mfma_f32_16x16x32_bf16 v[120:123], v[158:161], v[182:185], v[120:123]
	v_mfma_f32_16x16x32_bf16 v[108:111], v[144:147], v[194:197], v[108:111]
	v_mfma_f32_16x16x32_bf16 v[104:107], v[158:161], v[194:197], v[104:107]
	v_mfma_f32_16x16x32_bf16 v[92:95], v[144:147], v[202:205], v[92:95]
	v_mfma_f32_16x16x32_bf16 v[88:91], v[158:161], v[202:205], v[88:91]
	v_mfma_f32_16x16x32_bf16 v[76:79], v[144:147], v[210:213], v[76:79]
	v_mfma_f32_16x16x32_bf16 v[72:75], v[158:161], v[210:213], v[72:75]
	v_mfma_f32_16x16x32_bf16 v[124:127], v[154:157], v[186:189], v[124:127]
	v_mfma_f32_16x16x32_bf16 v[120:123], v[162:165], v[186:189], v[120:123]
	v_mfma_f32_16x16x32_bf16 v[108:111], v[154:157], v[198:201], v[108:111]
	v_mfma_f32_16x16x32_bf16 v[104:107], v[162:165], v[198:201], v[104:107]
	v_mfma_f32_16x16x32_bf16 v[92:95], v[154:157], v[206:209], v[92:95]
	v_mfma_f32_16x16x32_bf16 v[88:91], v[162:165], v[206:209], v[88:91]
	v_mfma_f32_16x16x32_bf16 v[76:79], v[154:157], v[214:217], v[76:79]
	v_mfma_f32_16x16x32_bf16 v[72:75], v[162:165], v[214:217], v[72:75]
	s_setprio 0
	s_setprio 1
	v_mfma_f32_16x16x32_bf16 v[116:119], v[166:169], v[182:185], v[116:119]
	v_mfma_f32_16x16x32_bf16 v[112:115], v[174:177], v[182:185], v[112:115]
	v_mfma_f32_16x16x32_bf16 v[100:103], v[166:169], v[194:197], v[100:103]
	v_mfma_f32_16x16x32_bf16 v[96:99], v[174:177], v[194:197], v[96:99]
	v_mfma_f32_16x16x32_bf16 v[84:87], v[166:169], v[202:205], v[84:87]
	v_mfma_f32_16x16x32_bf16 v[80:83], v[174:177], v[202:205], v[80:83]
	v_mfma_f32_16x16x32_bf16 v[68:71], v[166:169], v[210:213], v[68:71]
	v_mfma_f32_16x16x32_bf16 v[64:67], v[174:177], v[210:213], v[64:67]
	v_mfma_f32_16x16x32_bf16 v[116:119], v[170:173], v[186:189], v[116:119]
	v_mfma_f32_16x16x32_bf16 v[112:115], v[178:181], v[186:189], v[112:115]
	v_mfma_f32_16x16x32_bf16 v[100:103], v[170:173], v[198:201], v[100:103]
	v_mfma_f32_16x16x32_bf16 v[96:99], v[178:181], v[198:201], v[96:99]
	v_mfma_f32_16x16x32_bf16 v[84:87], v[170:173], v[206:209], v[84:87]
	v_mfma_f32_16x16x32_bf16 v[80:83], v[178:181], v[206:209], v[80:83]
	v_mfma_f32_16x16x32_bf16 v[68:71], v[170:173], v[214:217], v[68:71]
	v_mfma_f32_16x16x32_bf16 v[64:67], v[178:181], v[214:217], v[64:67]
	s_setprio 0
	s_barrier
; #define PG8_STAGE(bufoff, gbase, voff) do { _Pragma("unroll") for (int _i = 0; _i < 2; ++_i) \
;         __builtin_amdgcn_global_load_lds((const unsigned*)((const char*)(gbase) + (voff)[_i]), (PG8_LAS unsigned*)(lds + (bufoff) + ldsw + _i * 8192), 16, 0, 0); } while (0)
; #define PG8_LDA(dst, b, h) do { _Pragma("unroll") for (int m = 0; m < 4; ++m) _Pragma("unroll") for (int k = 0; k < 2; ++k) dst[m][k] = *(const PG8_LAS bf16x8*)(lds + PG8_SA(b, h) + aoff + m * 2048 + k * 1024); } while (0)
; #define PG8_MMA(ai, bj, At, Bt) do { __builtin_amdgcn_s_setprio(1); _Pragma("unroll") for (int m = 0; m < 4; ++m) _Pragma("unroll") for (int n = 0; n < 2; ++n) _Pragma("unroll") for (int k = 0; k < 2; ++k) \
;         acc[ai][bj][m][n] = __builtin_amdgcn_mfma_f32_16x16x32_bf16(Bt[n][k], At[m][k], acc[ai][bj][m][n], 0, 0, 0); __builtin_amdgcn_s_setprio(0); } while (0)
; #define PG8_WAIT_V(n) asm volatile("s_waitcnt vmcnt(" #n ")" ::: "memory")
; #define PG8_WAIT_L(n) asm volatile("s_waitcnt lgkmcnt(" #n ")" ::: "memory")
; #define PG8_BAR __builtin_amdgcn_s_barrier()
; #define PG8_SCHED __builtin_amdgcn_sched_barrier(0)
; template <class Epi, class Sched, bool ALIGN_EPI = false, bool SP2 = false>
; __device__ __forceinline__ void gemm_phase(PG8_LAS unsigned char* lds, const Gemm g, const Sched& S, const Epi& E) {
;     ...
;         for (int t = 0; t < nt; t += 2) {
;             const bool last = (t == nt - 2);
;     ...
;             PG8_LDA(At, 1, 1); PG8_STAGE(PG8_SB(1, 0), b3, voffB); PG8_STAGE(PG8_SB(1, 1), b3 + hstep, voffB); PG8_STAGE(PG8_SA(1, 0), a3, voffA);
;             PG8_WAIT_V(8); PG8_WAIT_L(0); PG8_BAR; PG8_MMA(1, 0, At, B0); PG8_MMA(1, 1, At, B1); PG8_BAR; PG8_SCHED;
	s_add_i32 s34, s68, s51
	v_lshl_add_u64 v[190:191], v[190:191], 0, s[12:13]
	s_mov_b32 m0, s34
	ds_read_b128 v[182:185], v153 offset:49152
	ds_read_b128 v[186:189], v153 offset:50176
	ds_read_b128 v[194:197], v153 offset:51200
	ds_read_b128 v[198:201], v153 offset:52224
	ds_read_b128 v[202:205], v153 offset:53248
	ds_read_b128 v[206:209], v153 offset:54272
	ds_read_b128 v[210:213], v153 offset:55296
	ds_read_b128 v[214:217], v153 offset:56320
	global_load_lds_dwordx4 v[190:191], off
	s_add_i32 m0, s34, 0x2000
	s_add_u32 s30, s30, 0x80080
	v_lshl_add_u64 v[190:191], v[218:219], 0, s[12:13]
	s_addc_u32 s31, s31, 0
	s_add_i32 s34, s69, s51
	global_load_lds_dwordx4 v[190:191], off
	v_lshl_add_u64 v[190:191], s[30:31], 0, v[132:133]
	s_mov_b32 m0, s34
	s_nop 0
	global_load_lds_dwordx4 v[190:191], off
	v_lshl_add_u64 v[190:191], s[30:31], 0, v[128:129]
	s_add_i32 m0, s34, 0x2000
	s_nop 0
	global_load_lds_dwordx4 v[190:191], off
	v_lshl_add_u64 v[190:191], v[220:221], 0, s[12:13]
	s_mov_b32 m0, s57
	s_nop 0
	global_load_lds_dwordx4 v[190:191], off
	v_lshl_add_u64 v[190:191], v[222:223], 0, s[12:13]
	s_mov_b32 m0, s58
	s_nop 0
	global_load_lds_dwordx4 v[190:191], off
	s_waitcnt vmcnt(8)
	s_waitcnt lgkmcnt(0)
	s_barrier
	s_setprio 1
	s_waitcnt lgkmcnt(0)
	v_mfma_f32_16x16x32_bf16 v[60:63], v[144:147], v[182:185], v[60:63]
	v_mfma_f32_16x16x32_bf16 v[56:59], v[158:161], v[182:185], v[56:59]
	v_mfma_f32_16x16x32_bf16 v[44:47], v[144:147], v[194:197], v[44:47]
	v_mfma_f32_16x16x32_bf16 v[40:43], v[158:161], v[194:197], v[40:43]
	v_mfma_f32_16x16x32_bf16 v[28:31], v[144:147], v[202:205], v[28:31]
	v_mfma_f32_16x16x32_bf16 v[24:27], v[158:161], v[202:205], v[24:27]
	v_mfma_f32_16x16x32_bf16 v[12:15], v[144:147], v[210:213], v[12:15]
	v_mfma_f32_16x16x32_bf16 v[8:11], v[158:161], v[210:213], v[8:11]
	v_mfma_f32_16x16x32_bf16 v[60:63], v[154:157], v[186:189], v[60:63]
	v_mfma_f32_16x16x32_bf16 v[56:59], v[162:165], v[186:189], v[56:59]
	v_mfma_f32_16x16x32_bf16 v[44:47], v[154:157], v[198:201], v[44:47]
	v_mfma_f32_16x16x32_bf16 v[40:43], v[162:165], v[198:201], v[40:43]
	v_mfma_f32_16x16x32_bf16 v[28:31], v[154:157], v[206:209], v[28:31]
	v_mfma_f32_16x16x32_bf16 v[24:27], v[162:165], v[206:209], v[24:27]
	v_mfma_f32_16x16x32_bf16 v[12:15], v[154:157], v[214:217], v[12:15]
	v_mfma_f32_16x16x32_bf16 v[8:11], v[162:165], v[214:217], v[8:11]
	s_setprio 0
	s_setprio 1
	v_mfma_f32_16x16x32_bf16 v[52:55], v[166:169], v[182:185], v[52:55]
	v_mfma_f32_16x16x32_bf16 v[48:51], v[174:177], v[182:185], v[48:51]
	v_mfma_f32_16x16x32_bf16 v[36:39], v[166:169], v[194:197], v[36:39]
	v_mfma_f32_16x16x32_bf16 v[32:35], v[174:177], v[194:197], v[32:35]
	v_mfma_f32_16x16x32_bf16 v[20:23], v[166:169], v[202:205], v[20:23]
	v_mfma_f32_16x16x32_bf16 v[16:19], v[174:177], v[202:205], v[16:19]
	v_mfma_f32_16x16x32_bf16 v[4:7], v[166:169], v[210:213], v[4:7]
	v_mfma_f32_16x16x32_bf16 v[0:3], v[174:177], v[210:213], v[0:3]
	v_mfma_f32_16x16x32_bf16 v[52:55], v[170:173], v[186:189], v[52:55]
	v_mfma_f32_16x16x32_bf16 v[48:51], v[178:181], v[186:189], v[48:51]
	v_mfma_f32_16x16x32_bf16 v[36:39], v[170:173], v[198:201], v[36:39]
	v_mfma_f32_16x16x32_bf16 v[32:35], v[178:181], v[198:201], v[32:35]
	v_mfma_f32_16x16x32_bf16 v[20:23], v[170:173], v[206:209], v[20:23]
	v_mfma_f32_16x16x32_bf16 v[16:19], v[178:181], v[206:209], v[16:19]
	v_mfma_f32_16x16x32_bf16 v[4:7], v[170:173], v[214:217], v[4:7]
	v_mfma_f32_16x16x32_bf16 v[0:3], v[178:181], v[214:217], v[0:3]
	s_setprio 0
	s_barrier
	s_add_i32 s67, s67, 2
	s_add_u32 s65, s65, 0x100
	s_addc_u32 s66, s66, 0
	s_add_u32 s28, s28, 0x100
	s_addc_u32 s29, s29, 0
	s_cmp_gt_u32 s67, 29
	s_cbranch_scc1 .Lpeel_exit_2
	.p2align	6

; #define PG8_STAGE(bufoff, gbase, voff) do { _Pragma("unroll") for (int _i = 0; _i < 2; ++_i) \
;         __builtin_amdgcn_global_load_lds((const unsigned*)((const char*)(gbase) + (voff)[_i]), (PG8_LAS unsigned*)(lds + (bufoff) + ldsw + _i * 8192), 16, 0, 0); } while (0)
; #define PG8_LDA(dst, b, h) do { _Pragma("unroll") for (int m = 0; m < 4; ++m) _Pragma("unroll") for (int k = 0; k < 2; ++k) dst[m][k] = *(const PG8_LAS bf16x8*)(lds + PG8_SA(b, h) + aoff + m * 2048 + k * 1024); } while (0)
; #define PG8_LDB(dst, b, h) do { _Pragma("unroll") for (int n = 0; n < 2; ++n) _Pragma("unroll") for (int k = 0; k < 2; ++k) dst[n][k] = *(const PG8_LAS bf16x8*)(lds + PG8_SB(b, h) + boff + n * 2048 + k * 1024); } while (0)
; #define PG8_MMA(ai, bj, At, Bt) do { __builtin_amdgcn_s_setprio(1); _Pragma("unroll") for (int m = 0; m < 4; ++m) _Pragma("unroll") for (int n = 0; n < 2; ++n) _Pragma("unroll") for (int k = 0; k < 2; ++k) \
;         acc[ai][bj][m][n] = __builtin_amdgcn_mfma_f32_16x16x32_bf16(Bt[n][k], At[m][k], acc[ai][bj][m][n], 0, 0, 0); __builtin_amdgcn_s_setprio(0); } while (0)
; #define PG8_WAIT_V(n) asm volatile("s_waitcnt vmcnt(" #n ")" ::: "memory")
; #define PG8_WAIT_L(n) asm volatile("s_waitcnt lgkmcnt(" #n ")" ::: "memory")
; template <class Epi, class Sched, bool ALIGN_EPI = false, bool SP2 = false>
; __device__ __forceinline__ void gemm_phase(PG8_LAS unsigned char* lds, const Gemm g, const Sched& S, const Epi& E) {
;     ...
;             const bool last = (t == nt - 2);
;             const char* a1 = cA + (size_t)(t + 1) * kstep;
;             const char* a2 = last ? nA : cA + (size_t)(t + 2) * kstep; const char* b2 = last ? nB : cB + (size_t)(t + 2) * kstep;
;             const char* a3 = a2 + kstep; const char* b3 = b2 + kstep;
;             if (last && has_next) S.a_ready(nxt);
;             if constexpr (SP2) {
;             PG8_LDB(B0, 0, 0); PG8_LDB(B1, 0, 1); PG8_SCHED; PG8_LDA(At, 0, 0); PG8_STAGE(PG8_SA(1, 1), a1 + hstep, voffA);
;             PG8_WAIT_V(8); PG8_WAIT_L(0); PG8_BAR; PG8_MMA(0, 0, At, B0); PG8_MMA(0, 1, At, B1); PG8_BAR; PG8_SCHED;
;             PG8_LDA(At, 0, 1); PG8_STAGE(PG8_SB(0, 0), b2, voffB); PG8_STAGE(PG8_SB(0, 1), b2 + hstep, voffB); PG8_STAGE(PG8_SA(0, 0), a2, voffA);
;             PG8_WAIT_V(8); PG8_WAIT_L(0); PG8_BAR; PG8_MMA(1, 0, At, B0); PG8_MMA(1, 1, At, B1); PG8_BAR; PG8_SCHED;
.LBB0_560:
	s_add_u32 s75, s30, 0x100
	s_addc_u32 s76, s31, 0
	s_mov_b32 s77, -2
	ds_read_b128 v[120:123], v169
	ds_read_b128 v[124:127], v169 offset:1024
	ds_read_b128 v[128:131], v169 offset:2048
	ds_read_b128 v[132:135], v169 offset:3072
	ds_read_b128 v[160:163], v170
	ds_read_b128 v[172:175], v170 offset:1024
	ds_read_b128 v[176:179], v170 offset:2048
	ds_read_b128 v[180:183], v170 offset:3072
	s_add_u32 s30, s28, 0x100
	s_addc_u32 s31, s29, 0
	s_cmpk_eq_i32 s77, 0x54
	s_cselect_b32 s37, s9, s31
	s_cselect_b32 s36, s8, s30
	s_cselect_b32 s35, s27, s76
	s_cselect_b32 s34, s26, s75
	v_lshl_add_u64 v[164:165], s[28:29], 0, v[154:155]
	s_add_i32 m0, s55, 0xc000
	ds_read_b128 v[184:187], v171
	ds_read_b128 v[188:191], v171 offset:1024
	ds_read_b128 v[194:197], v171 offset:2048
	ds_read_b128 v[198:201], v171 offset:3072
	ds_read_b128 v[202:205], v171 offset:4096
	ds_read_b128 v[206:209], v171 offset:5120
	ds_read_b128 v[210:213], v171 offset:6144
	ds_read_b128 v[214:217], v171 offset:7168
	global_load_lds_dwordx4 v[164:165], off
	v_lshl_add_u64 v[164:165], s[28:29], 0, v[152:153]
	s_add_i32 m0, s55, 0xe000
	s_nop 0
	global_load_lds_dwordx4 v[164:165], off
	s_waitcnt vmcnt(8)
	s_waitcnt lgkmcnt(0)
	s_barrier
	s_setprio 1
	s_waitcnt lgkmcnt(0)
	v_mfma_f32_16x16x32_bf16 v[140:143], v[120:123], v[184:187], 0
	v_mfma_f32_16x16x32_bf16 v[136:139], v[128:131], v[184:187], 0
	v_mfma_f32_16x16x32_bf16 v[112:115], v[120:123], v[194:197], 0
	v_mfma_f32_16x16x32_bf16 v[104:107], v[128:131], v[194:197], 0
	v_mfma_f32_16x16x32_bf16 v[96:99], v[120:123], v[202:205], 0
	v_mfma_f32_16x16x32_bf16 v[88:91], v[128:131], v[202:205], 0
	v_mfma_f32_16x16x32_bf16 v[80:83], v[120:123], v[210:213], 0
	v_mfma_f32_16x16x32_bf16 v[72:75], v[128:131], v[210:213], 0
	v_mfma_f32_16x16x32_bf16 v[140:143], v[124:127], v[188:191], v[140:143]
	v_mfma_f32_16x16x32_bf16 v[136:139], v[132:135], v[188:191], v[136:139]
	v_mfma_f32_16x16x32_bf16 v[112:115], v[124:127], v[198:201], v[112:115]
	v_mfma_f32_16x16x32_bf16 v[104:107], v[132:135], v[198:201], v[104:107]
	v_mfma_f32_16x16x32_bf16 v[96:99], v[124:127], v[206:209], v[96:99]
	v_mfma_f32_16x16x32_bf16 v[88:91], v[132:135], v[206:209], v[88:91]
	v_mfma_f32_16x16x32_bf16 v[80:83], v[124:127], v[214:217], v[80:83]
	v_mfma_f32_16x16x32_bf16 v[72:75], v[132:135], v[214:217], v[72:75]
	s_setprio 0
	s_setprio 1
	v_mfma_f32_16x16x32_bf16 v[116:119], v[160:163], v[184:187], 0
	v_mfma_f32_16x16x32_bf16 v[108:111], v[176:179], v[184:187], 0
	v_mfma_f32_16x16x32_bf16 v[100:103], v[160:163], v[194:197], 0
	v_mfma_f32_16x16x32_bf16 v[92:95], v[176:179], v[194:197], 0
	v_mfma_f32_16x16x32_bf16 v[84:87], v[160:163], v[202:205], 0
	v_mfma_f32_16x16x32_bf16 v[76:79], v[176:179], v[202:205], 0
	v_mfma_f32_16x16x32_bf16 v[68:71], v[160:163], v[210:213], 0
	v_mfma_f32_16x16x32_bf16 v[64:67], v[176:179], v[210:213], 0
	v_mfma_f32_16x16x32_bf16 v[116:119], v[172:175], v[188:191], v[116:119]
	v_mfma_f32_16x16x32_bf16 v[108:111], v[180:183], v[188:191], v[108:111]
	v_mfma_f32_16x16x32_bf16 v[100:103], v[172:175], v[198:201], v[100:103]
	v_mfma_f32_16x16x32_bf16 v[92:95], v[180:183], v[198:201], v[92:95]
	v_mfma_f32_16x16x32_bf16 v[84:87], v[172:175], v[206:209], v[84:87]
	v_mfma_f32_16x16x32_bf16 v[76:79], v[180:183], v[206:209], v[76:79]
	v_mfma_f32_16x16x32_bf16 v[68:71], v[172:175], v[214:217], v[68:71]
	v_mfma_f32_16x16x32_bf16 v[64:67], v[180:183], v[214:217], v[64:67]
	s_setprio 0
	s_barrier
	s_add_i32 s28, s65, s54
	v_lshl_add_u64 v[164:165], s[34:35], 0, v[146:147]
	s_mov_b32 m0, s28
	ds_read_b128 v[184:187], v171 offset:16384
	ds_read_b128 v[188:191], v171 offset:17408
	ds_read_b128 v[194:197], v171 offset:18432
	ds_read_b128 v[198:201], v171 offset:19456
	ds_read_b128 v[202:205], v171 offset:20480
	ds_read_b128 v[206:209], v171 offset:21504
	ds_read_b128 v[210:213], v171 offset:22528
	ds_read_b128 v[214:217], v171 offset:23552
	global_load_lds_dwordx4 v[164:165], off
	s_add_i32 m0, s28, 0x2000
	s_add_u32 s28, s34, 0x160000
	v_lshl_add_u64 v[218:219], s[34:35], 0, v[150:151]
	s_addc_u32 s29, s35, 0
	s_add_i32 s78, s66, s54
	global_load_lds_dwordx4 v[218:219], off
	v_lshl_add_u64 v[220:221], s[28:29], 0, v[146:147]
	s_mov_b32 m0, s78
	v_lshl_add_u64 v[222:223], s[36:37], 0, v[148:149]
	global_load_lds_dwordx4 v[220:221], off
	v_lshl_add_u64 v[220:221], s[28:29], 0, v[150:151]
	s_add_i32 m0, s78, 0x2000
	s_nop 0
	global_load_lds_dwordx4 v[220:221], off
	v_lshl_add_u64 v[220:221], s[36:37], 0, v[144:145]
	s_mov_b32 m0, s55
	s_nop 0
	global_load_lds_dwordx4 v[220:221], off
	s_mov_b32 m0, s56
	s_nop 0
	global_load_lds_dwordx4 v[222:223], off
	s_waitcnt vmcnt(8)
	s_waitcnt lgkmcnt(0)
	s_barrier
; #define PG8_STAGE(bufoff, gbase, voff) do { _Pragma("unroll") for (int _i = 0; _i < 2; ++_i) \
;         __builtin_amdgcn_global_load_lds((const unsigned*)((const char*)(gbase) + (voff)[_i]), (PG8_LAS unsigned*)(lds + (bufoff) + ldsw + _i * 8192), 16, 0, 0); } while (0)
; #define PG8_LDA(dst, b, h) do { _Pragma("unroll") for (int m = 0; m < 4; ++m) _Pragma("unroll") for (int k = 0; k < 2; ++k) dst[m][k] = *(const PG8_LAS bf16x8*)(lds + PG8_SA(b, h) + aoff + m * 2048 + k * 1024); } while (0)
; #define PG8_LDB(dst, b, h) do { _Pragma("unroll") for (int n = 0; n < 2; ++n) _Pragma("unroll") for (int k = 0; k < 2; ++k) dst[n][k] = *(const PG8_LAS bf16x8*)(lds + PG8_SB(b, h) + boff + n * 2048 + k * 1024); } while (0)
; #define PG8_MMA(ai, bj, At, Bt) do { __builtin_amdgcn_s_setprio(1); _Pragma("unroll") for (int m = 0; m < 4; ++m) _Pragma("unroll") for (int n = 0; n < 2; ++n) _Pragma("unroll") for (int k = 0; k < 2; ++k) \
;         acc[ai][bj][m][n] = __builtin_amdgcn_mfma_f32_16x16x32_bf16(Bt[n][k], At[m][k], acc[ai][bj][m][n], 0, 0, 0); __builtin_amdgcn_s_setprio(0); } while (0)
; #define PG8_WAIT_V(n) asm volatile("s_waitcnt vmcnt(" #n ")" ::: "memory")
; #define PG8_WAIT_L(n) asm volatile("s_waitcnt lgkmcnt(" #n ")" ::: "memory")
; #define PG8_BAR __builtin_amdgcn_s_barrier()
; #define PG8_SCHED __builtin_amdgcn_sched_barrier(0)
; template <class Epi, class Sched, bool ALIGN_EPI = false, bool SP2 = false>
; __device__ __forceinline__ void gemm_phase(PG8_LAS unsigned char* lds, const Gemm g, const Sched& S, const Epi& E) {
;     ...
;             PG8_WAIT_V(8); PG8_WAIT_L(0); PG8_BAR; PG8_MMA(1, 0, At, B0); PG8_MMA(1, 1, At, B1); PG8_BAR; PG8_SCHED;
;             PG8_LDB(B0, 1, 0); PG8_LDB(B1, 1, 1); PG8_SCHED; PG8_LDA(At, 1, 0); PG8_STAGE(PG8_SA(0, 1), a2 + hstep, voffA);
;             PG8_WAIT_V(8); PG8_WAIT_L(0); PG8_BAR; PG8_MMA(0, 0, At, B0); PG8_MMA(0, 1, At, B1); PG8_BAR; PG8_SCHED;
	s_setprio 1
	s_waitcnt lgkmcnt(0)
	v_mfma_f32_16x16x32_bf16 v[60:63], v[120:123], v[184:187], 0
	v_mfma_f32_16x16x32_bf16 v[56:59], v[128:131], v[184:187], 0
	v_mfma_f32_16x16x32_bf16 v[48:51], v[120:123], v[194:197], 0
	v_mfma_f32_16x16x32_bf16 v[40:43], v[128:131], v[194:197], 0
	v_mfma_f32_16x16x32_bf16 v[32:35], v[120:123], v[202:205], 0
	v_mfma_f32_16x16x32_bf16 v[24:27], v[128:131], v[202:205], 0
	v_mfma_f32_16x16x32_bf16 v[16:19], v[120:123], v[210:213], 0
	v_mfma_f32_16x16x32_bf16 v[8:11], v[128:131], v[210:213], 0
	v_mfma_f32_16x16x32_bf16 v[60:63], v[124:127], v[188:191], v[60:63]
	v_mfma_f32_16x16x32_bf16 v[56:59], v[132:135], v[188:191], v[56:59]
	v_mfma_f32_16x16x32_bf16 v[48:51], v[124:127], v[198:201], v[48:51]
	v_mfma_f32_16x16x32_bf16 v[40:43], v[132:135], v[198:201], v[40:43]
	v_mfma_f32_16x16x32_bf16 v[32:35], v[124:127], v[206:209], v[32:35]
	v_mfma_f32_16x16x32_bf16 v[24:27], v[132:135], v[206:209], v[24:27]
	v_mfma_f32_16x16x32_bf16 v[16:19], v[124:127], v[214:217], v[16:19]
	v_mfma_f32_16x16x32_bf16 v[8:11], v[132:135], v[214:217], v[8:11]
	s_setprio 0
	s_setprio 1
	v_mfma_f32_16x16x32_bf16 v[52:55], v[160:163], v[184:187], 0
	v_mfma_f32_16x16x32_bf16 v[44:47], v[176:179], v[184:187], 0
	v_mfma_f32_16x16x32_bf16 v[36:39], v[160:163], v[194:197], 0
	v_mfma_f32_16x16x32_bf16 v[28:31], v[176:179], v[194:197], 0
	v_mfma_f32_16x16x32_bf16 v[20:23], v[160:163], v[202:205], 0
	v_mfma_f32_16x16x32_bf16 v[12:15], v[176:179], v[202:205], 0
	v_mfma_f32_16x16x32_bf16 v[4:7], v[160:163], v[210:213], 0
	v_mfma_f32_16x16x32_bf16 v[0:3], v[176:179], v[210:213], 0
	v_mfma_f32_16x16x32_bf16 v[52:55], v[172:175], v[188:191], v[52:55]
	v_mfma_f32_16x16x32_bf16 v[44:47], v[180:183], v[188:191], v[44:47]
	v_mfma_f32_16x16x32_bf16 v[36:39], v[172:175], v[198:201], v[36:39]
	v_mfma_f32_16x16x32_bf16 v[28:31], v[180:183], v[198:201], v[28:31]
	v_mfma_f32_16x16x32_bf16 v[20:23], v[172:175], v[206:209], v[20:23]
	v_mfma_f32_16x16x32_bf16 v[12:15], v[180:183], v[206:209], v[12:15]
	v_mfma_f32_16x16x32_bf16 v[4:7], v[172:175], v[214:217], v[4:7]
	v_mfma_f32_16x16x32_bf16 v[0:3], v[180:183], v[214:217], v[0:3]
	s_setprio 0
	s_barrier
	s_add_i32 s78, 0, 0x18000
	s_add_i32 s79, 0, 0x1c000
	v_add_u32_e32 v132, s78, v167
	v_add_u32_e32 v180, s79, v167
	ds_read_b128 v[120:123], v132
	ds_read_b128 v[124:127], v132 offset:1024
	ds_read_b128 v[128:131], v132 offset:2048
	ds_read_b128 v[132:135], v132 offset:3072
	ds_read_b128 v[160:163], v180
	ds_read_b128 v[172:175], v180 offset:1024
	ds_read_b128 v[176:179], v180 offset:2048
	ds_read_b128 v[180:183], v180 offset:3072
	s_add_u32 s28, s36, 0x160000
	s_addc_u32 s29, s37, 0
	s_mov_b32 m0, s57
	v_lshl_add_u64 v[224:225], s[28:29], 0, v[144:145]
	ds_read_b128 v[184:187], v171 offset:32768
	ds_read_b128 v[188:191], v171 offset:33792
	ds_read_b128 v[194:197], v171 offset:34816
	ds_read_b128 v[198:201], v171 offset:35840
	ds_read_b128 v[202:205], v171 offset:36864
	ds_read_b128 v[206:209], v171 offset:37888
	ds_read_b128 v[210:213], v171 offset:38912
	ds_read_b128 v[214:217], v171 offset:39936
	global_load_lds_dwordx4 v[224:225], off
	v_lshl_add_u64 v[224:225], s[28:29], 0, v[148:149]
	s_mov_b32 m0, s58
	s_nop 0
	global_load_lds_dwordx4 v[224:225], off
	s_waitcnt vmcnt(8)
	s_waitcnt lgkmcnt(0)
	s_barrier
	s_setprio 1
	s_waitcnt lgkmcnt(0)
	v_mfma_f32_16x16x32_bf16 v[140:143], v[120:123], v[184:187], v[140:143]
	v_mfma_f32_16x16x32_bf16 v[136:139], v[128:131], v[184:187], v[136:139]
	v_mfma_f32_16x16x32_bf16 v[112:115], v[120:123], v[194:197], v[112:115]
	v_mfma_f32_16x16x32_bf16 v[104:107], v[128:131], v[194:197], v[104:107]
	v_mfma_f32_16x16x32_bf16 v[96:99], v[120:123], v[202:205], v[96:99]
	v_mfma_f32_16x16x32_bf16 v[88:91], v[128:131], v[202:205], v[88:91]
	v_mfma_f32_16x16x32_bf16 v[80:83], v[120:123], v[210:213], v[80:83]
	v_mfma_f32_16x16x32_bf16 v[72:75], v[128:131], v[210:213], v[72:75]
	v_mfma_f32_16x16x32_bf16 v[140:143], v[124:127], v[188:191], v[140:143]
	v_mfma_f32_16x16x32_bf16 v[136:139], v[132:135], v[188:191], v[136:139]
	v_mfma_f32_16x16x32_bf16 v[112:115], v[124:127], v[198:201], v[112:115]
	v_mfma_f32_16x16x32_bf16 v[104:107], v[132:135], v[198:201], v[104:107]
	v_mfma_f32_16x16x32_bf16 v[96:99], v[124:127], v[206:209], v[96:99]
	v_mfma_f32_16x16x32_bf16 v[88:91], v[132:135], v[206:209], v[88:91]
	v_mfma_f32_16x16x32_bf16 v[80:83], v[124:127], v[214:217], v[80:83]
	v_mfma_f32_16x16x32_bf16 v[72:75], v[132:135], v[214:217], v[72:75]
	s_setprio 0
	s_setprio 1
	v_mfma_f32_16x16x32_bf16 v[116:119], v[160:163], v[184:187], v[116:119]
	v_mfma_f32_16x16x32_bf16 v[108:111], v[176:179], v[184:187], v[108:111]
	v_mfma_f32_16x16x32_bf16 v[100:103], v[160:163], v[194:197], v[100:103]
	v_mfma_f32_16x16x32_bf16 v[92:95], v[176:179], v[194:197], v[92:95]
	v_mfma_f32_16x16x32_bf16 v[84:87], v[160:163], v[202:205], v[84:87]
	v_mfma_f32_16x16x32_bf16 v[76:79], v[176:179], v[202:205], v[76:79]
	v_mfma_f32_16x16x32_bf16 v[68:71], v[160:163], v[210:213], v[68:71]
	v_mfma_f32_16x16x32_bf16 v[64:67], v[176:179], v[210:213], v[64:67]
	v_mfma_f32_16x16x32_bf16 v[116:119], v[172:175], v[188:191], v[116:119]
	v_mfma_f32_16x16x32_bf16 v[108:111], v[180:183], v[188:191], v[108:111]
	v_mfma_f32_16x16x32_bf16 v[100:103], v[172:175], v[198:201], v[100:103]
	v_mfma_f32_16x16x32_bf16 v[92:95], v[180:183], v[198:201], v[92:95]
	v_mfma_f32_16x16x32_bf16 v[84:87], v[172:175], v[206:209], v[84:87]
	v_mfma_f32_16x16x32_bf16 v[76:79], v[180:183], v[206:209], v[76:79]
	v_mfma_f32_16x16x32_bf16 v[68:71], v[172:175], v[214:217], v[68:71]
	v_mfma_f32_16x16x32_bf16 v[64:67], v[180:183], v[214:217], v[64:67]
	s_setprio 0
	s_barrier
; #define PG8_STAGE(bufoff, gbase, voff) do { _Pragma("unroll") for (int _i = 0; _i < 2; ++_i) \
;         __builtin_amdgcn_global_load_lds((const unsigned*)((const char*)(gbase) + (voff)[_i]), (PG8_LAS unsigned*)(lds + (bufoff) + ldsw + _i * 8192), 16, 0, 0); } while (0)
; #define PG8_LDA(dst, b, h) do { _Pragma("unroll") for (int m = 0; m < 4; ++m) _Pragma("unroll") for (int k = 0; k < 2; ++k) dst[m][k] = *(const PG8_LAS bf16x8*)(lds + PG8_SA(b, h) + aoff + m * 2048 + k * 1024); } while (0)
; #define PG8_MMA(ai, bj, At, Bt) do { __builtin_amdgcn_s_setprio(1); _Pragma("unroll") for (int m = 0; m < 4; ++m) _Pragma("unroll") for (int n = 0; n < 2; ++n) _Pragma("unroll") for (int k = 0; k < 2; ++k) \
;         acc[ai][bj][m][n] = __builtin_amdgcn_mfma_f32_16x16x32_bf16(Bt[n][k], At[m][k], acc[ai][bj][m][n], 0, 0, 0); __builtin_amdgcn_s_setprio(0); } while (0)
; #define PG8_WAIT_V(n) asm volatile("s_waitcnt vmcnt(" #n ")" ::: "memory")
; #define PG8_WAIT_L(n) asm volatile("s_waitcnt lgkmcnt(" #n ")" ::: "memory")
; #define PG8_BAR __builtin_amdgcn_s_barrier()
; #define PG8_SCHED __builtin_amdgcn_sched_barrier(0)
; template <class Epi, class Sched, bool ALIGN_EPI = false, bool SP2 = false>
; __device__ __forceinline__ void gemm_phase(PG8_LAS unsigned char* lds, const Gemm g, const Sched& S, const Epi& E) {
;     ...
;         for (int t = 0; t < nt; t += 2) {
;             const bool last = (t == nt - 2);
;     ...
;             PG8_LDA(At, 1, 1); PG8_STAGE(PG8_SB(1, 0), b3, voffB); PG8_STAGE(PG8_SB(1, 1), b3 + hstep, voffB); PG8_STAGE(PG8_SA(1, 0), a3, voffA);
;             PG8_WAIT_V(8); PG8_WAIT_L(0); PG8_BAR; PG8_MMA(1, 0, At, B0); PG8_MMA(1, 1, At, B1); PG8_BAR; PG8_SCHED;
	s_add_i32 s28, s78, s54
	v_lshl_add_u64 v[164:165], v[164:165], 0, s[14:15]
	s_mov_b32 m0, s28
	ds_read_b128 v[184:187], v171 offset:49152
	ds_read_b128 v[188:191], v171 offset:50176
	ds_read_b128 v[194:197], v171 offset:51200
	ds_read_b128 v[198:201], v171 offset:52224
	ds_read_b128 v[202:205], v171 offset:53248
	ds_read_b128 v[206:209], v171 offset:54272
	ds_read_b128 v[210:213], v171 offset:55296
	ds_read_b128 v[214:217], v171 offset:56320
	global_load_lds_dwordx4 v[164:165], off
	s_add_i32 m0, s28, 0x2000
	s_add_u32 s28, s34, 0x160080
	v_lshl_add_u64 v[164:165], v[218:219], 0, s[14:15]
	s_addc_u32 s29, s35, 0
	s_add_i32 s34, s79, s54
	global_load_lds_dwordx4 v[164:165], off
	v_lshl_add_u64 v[164:165], s[28:29], 0, v[146:147]
	s_mov_b32 m0, s34
	s_nop 0
	global_load_lds_dwordx4 v[164:165], off
	v_lshl_add_u64 v[164:165], s[28:29], 0, v[150:151]
	s_add_i32 m0, s34, 0x2000
	s_nop 0
	global_load_lds_dwordx4 v[164:165], off
	v_lshl_add_u64 v[164:165], v[220:221], 0, s[14:15]
	s_mov_b32 m0, s62
	s_nop 0
	global_load_lds_dwordx4 v[164:165], off
	v_lshl_add_u64 v[164:165], v[222:223], 0, s[14:15]
	s_mov_b32 m0, s63
	s_nop 0
	global_load_lds_dwordx4 v[164:165], off
	s_waitcnt vmcnt(8)
	s_waitcnt lgkmcnt(0)
	s_barrier
	s_setprio 1
	s_waitcnt lgkmcnt(0)
	v_mfma_f32_16x16x32_bf16 v[60:63], v[120:123], v[184:187], v[60:63]
	v_mfma_f32_16x16x32_bf16 v[56:59], v[128:131], v[184:187], v[56:59]
	v_mfma_f32_16x16x32_bf16 v[48:51], v[120:123], v[194:197], v[48:51]
	v_mfma_f32_16x16x32_bf16 v[40:43], v[128:131], v[194:197], v[40:43]
	v_mfma_f32_16x16x32_bf16 v[32:35], v[120:123], v[202:205], v[32:35]
	v_mfma_f32_16x16x32_bf16 v[24:27], v[128:131], v[202:205], v[24:27]
	v_mfma_f32_16x16x32_bf16 v[16:19], v[120:123], v[210:213], v[16:19]
	v_mfma_f32_16x16x32_bf16 v[8:11], v[128:131], v[210:213], v[8:11]
	v_mfma_f32_16x16x32_bf16 v[60:63], v[124:127], v[188:191], v[60:63]
	v_mfma_f32_16x16x32_bf16 v[56:59], v[132:135], v[188:191], v[56:59]
	v_mfma_f32_16x16x32_bf16 v[48:51], v[124:127], v[198:201], v[48:51]
	v_mfma_f32_16x16x32_bf16 v[40:43], v[132:135], v[198:201], v[40:43]
	v_mfma_f32_16x16x32_bf16 v[32:35], v[124:127], v[206:209], v[32:35]
	v_mfma_f32_16x16x32_bf16 v[24:27], v[132:135], v[206:209], v[24:27]
	v_mfma_f32_16x16x32_bf16 v[16:19], v[124:127], v[214:217], v[16:19]
	v_mfma_f32_16x16x32_bf16 v[8:11], v[132:135], v[214:217], v[8:11]
	s_setprio 0
	s_setprio 1
	v_mfma_f32_16x16x32_bf16 v[52:55], v[160:163], v[184:187], v[52:55]
	v_mfma_f32_16x16x32_bf16 v[44:47], v[176:179], v[184:187], v[44:47]
	v_mfma_f32_16x16x32_bf16 v[36:39], v[160:163], v[194:197], v[36:39]
	v_mfma_f32_16x16x32_bf16 v[28:31], v[176:179], v[194:197], v[28:31]
	v_mfma_f32_16x16x32_bf16 v[20:23], v[160:163], v[202:205], v[20:23]
	v_mfma_f32_16x16x32_bf16 v[12:15], v[176:179], v[202:205], v[12:15]
	v_mfma_f32_16x16x32_bf16 v[4:7], v[160:163], v[210:213], v[4:7]
	v_mfma_f32_16x16x32_bf16 v[0:3], v[176:179], v[210:213], v[0:3]
	v_mfma_f32_16x16x32_bf16 v[52:55], v[172:175], v[188:191], v[52:55]
	v_mfma_f32_16x16x32_bf16 v[44:47], v[180:183], v[188:191], v[44:47]
	v_mfma_f32_16x16x32_bf16 v[36:39], v[172:175], v[198:201], v[36:39]
	v_mfma_f32_16x16x32_bf16 v[28:31], v[180:183], v[198:201], v[28:31]
	v_mfma_f32_16x16x32_bf16 v[20:23], v[172:175], v[206:209], v[20:23]
	v_mfma_f32_16x16x32_bf16 v[12:15], v[180:183], v[206:209], v[12:15]
	v_mfma_f32_16x16x32_bf16 v[4:7], v[172:175], v[214:217], v[4:7]
	v_mfma_f32_16x16x32_bf16 v[0:3], v[180:183], v[214:217], v[0:3]
	s_setprio 0
	s_barrier
	s_add_i32 s77, s77, 2
	s_add_u32 s75, s75, 0x100
	s_addc_u32 s76, s76, 0
	s_cmpk_gt_u32 s77, 0x55
	s_mov_b64 s[28:29], s[30:31]
	s_cbranch_scc1 .Lpeel_exit_3
	.p2align	6

; #define PG8_STAGE(bufoff, gbase, voff) do { _Pragma("unroll") for (int _i = 0; _i < 2; ++_i) \
;         __builtin_amdgcn_global_load_lds((const unsigned*)((const char*)(gbase) + (voff)[_i]), (PG8_LAS unsigned*)(lds + (bufoff) + ldsw + _i * 8192), 16, 0, 0); } while (0)
; #define PG8_LDA(dst, b, h) do { _Pragma("unroll") for (int m = 0; m < 4; ++m) _Pragma("unroll") for (int k = 0; k < 2; ++k) dst[m][k] = *(const PG8_LAS bf16x8*)(lds + PG8_SA(b, h) + aoff + m * 2048 + k * 1024); } while (0)
; #define PG8_LDB(dst, b, h) do { _Pragma("unroll") for (int n = 0; n < 2; ++n) _Pragma("unroll") for (int k = 0; k < 2; ++k) dst[n][k] = *(const PG8_LAS bf16x8*)(lds + PG8_SB(b, h) + boff + n * 2048 + k * 1024); } while (0)
; #define PG8_MMA(ai, bj, At, Bt) do { __builtin_amdgcn_s_setprio(1); _Pragma("unroll") for (int m = 0; m < 4; ++m) _Pragma("unroll") for (int n = 0; n < 2; ++n) _Pragma("unroll") for (int k = 0; k < 2; ++k) \
;         acc[ai][bj][m][n] = __builtin_amdgcn_mfma_f32_16x16x32_bf16(Bt[n][k], At[m][k], acc[ai][bj][m][n], 0, 0, 0); __builtin_amdgcn_s_setprio(0); } while (0)
; #define PG8_WAIT_V(n) asm volatile("s_waitcnt vmcnt(" #n ")" ::: "memory")
; #define PG8_WAIT_L(n) asm volatile("s_waitcnt lgkmcnt(" #n ")" ::: "memory")
; template <class Epi, class Sched, bool ALIGN_EPI = false, bool SP2 = false>
; __device__ __forceinline__ void gemm_phase(PG8_LAS unsigned char* lds, const Gemm g, const Sched& S, const Epi& E) {
;     ...
;             const bool last = (t == nt - 2);
;             const char* a1 = cA + (size_t)(t + 1) * kstep;
;             const char* a2 = last ? nA : cA + (size_t)(t + 2) * kstep; const char* b2 = last ? nB : cB + (size_t)(t + 2) * kstep;
;             const char* a3 = a2 + kstep; const char* b3 = b2 + kstep;
;             if (last && has_next) S.a_ready(nxt);
;             if constexpr (SP2) {
;             PG8_LDB(B0, 0, 0); PG8_LDB(B1, 0, 1); PG8_SCHED; PG8_LDA(At, 0, 0); PG8_STAGE(PG8_SA(1, 1), a1 + hstep, voffA);
;             PG8_WAIT_V(8); PG8_WAIT_L(0); PG8_BAR; PG8_MMA(0, 0, At, B0); PG8_MMA(0, 1, At, B1); PG8_BAR; PG8_SCHED;
;             PG8_LDA(At, 0, 1); PG8_STAGE(PG8_SB(0, 0), b2, voffB); PG8_STAGE(PG8_SB(0, 1), b2 + hstep, voffB); PG8_STAGE(PG8_SA(0, 0), a2, voffA);
;             PG8_WAIT_V(8); PG8_WAIT_L(0); PG8_BAR; PG8_MMA(1, 0, At, B0); PG8_MMA(1, 1, At, B1); PG8_BAR; PG8_SCHED;
.LBB0_725:
	s_ashr_i32 s17, s16, 31
	s_lshl_b64 s[20:21], s[16:17], 20
	s_add_u32 s20, s52, s20
	s_addc_u32 s21, s53, s21
	s_and_b64 s[22:23], s[6:7], exec
	s_cselect_b32 s17, s21, s31
	s_cselect_b32 s78, s20, s30
	s_ashr_i32 s19, s18, 31
	s_lshl_b64 s[22:23], s[18:19], 20
	s_add_u32 s22, s37, s22
	s_addc_u32 s23, s50, s23
	s_and_b64 s[34:35], s[6:7], exec
	s_cselect_b32 s19, s23, s29
	s_cselect_b32 s79, s22, s28
	s_add_u32 s80, s28, 0x100
	s_addc_u32 s81, s29, 0
	s_add_u32 s28, s30, 0x80080
	s_addc_u32 s29, s31, 0
	s_mov_b32 s82, -2
	ds_read_b128 v[154:157], v150
	ds_read_b128 v[158:161], v150 offset:1024
	ds_read_b128 v[162:165], v150 offset:2048
	ds_read_b128 v[166:169], v150 offset:3072
	ds_read_b128 v[170:173], v151
	ds_read_b128 v[174:177], v151 offset:1024
	ds_read_b128 v[178:181], v151 offset:2048
	ds_read_b128 v[182:185], v151 offset:3072
	s_add_u32 s30, s28, 0xfff80080
	s_addc_u32 s31, s29, -1
	s_cmp_eq_u32 s82, 28
	s_cselect_b32 s35, s17, s31
	s_cselect_b32 s34, s78, s30
	s_cselect_b32 s31, s19, s81
	s_cselect_b32 s30, s79, s80
	v_lshl_add_u64 v[146:147], s[28:29], 0, v[140:141]
	s_add_i32 m0, s25, 0xc000
	ds_read_b128 v[186:189], v152
	ds_read_b128 v[194:197], v152 offset:1024
	ds_read_b128 v[198:201], v152 offset:2048
	ds_read_b128 v[202:205], v152 offset:3072
	ds_read_b128 v[206:209], v152 offset:4096
	ds_read_b128 v[210:213], v152 offset:5120
	ds_read_b128 v[214:217], v152 offset:6144
	ds_read_b128 v[218:221], v152 offset:7168
	global_load_lds_dwordx4 v[146:147], off
	v_lshl_add_u64 v[146:147], s[28:29], 0, v[138:139]
	s_add_i32 m0, s25, 0xe000
	s_nop 0
	global_load_lds_dwordx4 v[146:147], off
	s_waitcnt vmcnt(8)
	s_waitcnt lgkmcnt(0)
	s_barrier
	s_setprio 1
	s_waitcnt lgkmcnt(0)
	v_mfma_f32_16x16x32_bf16 v[124:127], v[154:157], v[186:189], 0
	v_mfma_f32_16x16x32_bf16 v[120:123], v[162:165], v[186:189], 0
	v_mfma_f32_16x16x32_bf16 v[116:119], v[154:157], v[198:201], 0
	v_mfma_f32_16x16x32_bf16 v[108:111], v[162:165], v[198:201], 0
	v_mfma_f32_16x16x32_bf16 v[100:103], v[154:157], v[206:209], 0
	v_mfma_f32_16x16x32_bf16 v[92:95], v[162:165], v[206:209], 0
	v_mfma_f32_16x16x32_bf16 v[84:87], v[154:157], v[214:217], 0
	v_mfma_f32_16x16x32_bf16 v[76:79], v[162:165], v[214:217], 0
	v_mfma_f32_16x16x32_bf16 v[124:127], v[158:161], v[194:197], v[124:127]
	v_mfma_f32_16x16x32_bf16 v[120:123], v[166:169], v[194:197], v[120:123]
	v_mfma_f32_16x16x32_bf16 v[116:119], v[158:161], v[202:205], v[116:119]
	v_mfma_f32_16x16x32_bf16 v[108:111], v[166:169], v[202:205], v[108:111]
	v_mfma_f32_16x16x32_bf16 v[100:103], v[158:161], v[210:213], v[100:103]
	v_mfma_f32_16x16x32_bf16 v[92:95], v[166:169], v[210:213], v[92:95]
	v_mfma_f32_16x16x32_bf16 v[84:87], v[158:161], v[218:221], v[84:87]
	v_mfma_f32_16x16x32_bf16 v[76:79], v[166:169], v[218:221], v[76:79]
	s_setprio 0
	s_setprio 1
	v_mfma_f32_16x16x32_bf16 v[112:115], v[170:173], v[186:189], 0
	v_mfma_f32_16x16x32_bf16 v[104:107], v[178:181], v[186:189], 0
	v_mfma_f32_16x16x32_bf16 v[96:99], v[170:173], v[198:201], 0
	v_mfma_f32_16x16x32_bf16 v[88:91], v[178:181], v[198:201], 0
	v_mfma_f32_16x16x32_bf16 v[80:83], v[170:173], v[206:209], 0
	v_mfma_f32_16x16x32_bf16 v[72:75], v[178:181], v[206:209], 0
	v_mfma_f32_16x16x32_bf16 v[68:71], v[170:173], v[214:217], 0
	v_mfma_f32_16x16x32_bf16 v[64:67], v[178:181], v[214:217], 0
	v_mfma_f32_16x16x32_bf16 v[112:115], v[174:177], v[194:197], v[112:115]
	v_mfma_f32_16x16x32_bf16 v[104:107], v[182:185], v[194:197], v[104:107]
	v_mfma_f32_16x16x32_bf16 v[96:99], v[174:177], v[202:205], v[96:99]
	v_mfma_f32_16x16x32_bf16 v[88:91], v[182:185], v[202:205], v[88:91]
	v_mfma_f32_16x16x32_bf16 v[80:83], v[174:177], v[210:213], v[80:83]
	v_mfma_f32_16x16x32_bf16 v[72:75], v[182:185], v[210:213], v[72:75]
	v_mfma_f32_16x16x32_bf16 v[68:71], v[174:177], v[218:221], v[68:71]
	v_mfma_f32_16x16x32_bf16 v[64:67], v[182:185], v[218:221], v[64:67]
	s_setprio 0
	s_barrier
	s_add_i32 s83, s64, s36
	v_lshl_add_u64 v[146:147], s[30:31], 0, v[132:133]
	s_mov_b32 m0, s83
	ds_read_b128 v[186:189], v152 offset:16384
	ds_read_b128 v[194:197], v152 offset:17408
	ds_read_b128 v[198:201], v152 offset:18432
	ds_read_b128 v[202:205], v152 offset:19456
	ds_read_b128 v[206:209], v152 offset:20480
	ds_read_b128 v[210:213], v152 offset:21504
	ds_read_b128 v[214:217], v152 offset:22528
	ds_read_b128 v[218:221], v152 offset:23552
	global_load_lds_dwordx4 v[146:147], off
	s_add_i32 m0, s83, 0x2000
	s_add_u32 s84, s30, 0x80000
	v_lshl_add_u64 v[190:191], s[30:31], 0, v[128:129]
	s_addc_u32 s85, s31, 0
	s_add_i32 s83, s65, s36
	global_load_lds_dwordx4 v[190:191], off
	v_lshl_add_u64 v[222:223], s[84:85], 0, v[132:133]
	s_mov_b32 m0, s83
	v_lshl_add_u64 v[224:225], s[34:35], 0, v[130:131]
	global_load_lds_dwordx4 v[222:223], off
	v_lshl_add_u64 v[222:223], s[84:85], 0, v[128:129]
	s_add_i32 m0, s83, 0x2000
	s_nop 0
	global_load_lds_dwordx4 v[222:223], off
	v_lshl_add_u64 v[222:223], s[34:35], 0, v[134:135]
	s_mov_b32 m0, s25
	s_nop 0
	global_load_lds_dwordx4 v[222:223], off
	s_mov_b32 m0, s27
	s_nop 0
	global_load_lds_dwordx4 v[224:225], off
	s_waitcnt vmcnt(8)
	s_waitcnt lgkmcnt(0)
	s_barrier
; #define PG8_STAGE(bufoff, gbase, voff) do { _Pragma("unroll") for (int _i = 0; _i < 2; ++_i) \
;         __builtin_amdgcn_global_load_lds((const unsigned*)((const char*)(gbase) + (voff)[_i]), (PG8_LAS unsigned*)(lds + (bufoff) + ldsw + _i * 8192), 16, 0, 0); } while (0)
; #define PG8_LDA(dst, b, h) do { _Pragma("unroll") for (int m = 0; m < 4; ++m) _Pragma("unroll") for (int k = 0; k < 2; ++k) dst[m][k] = *(const PG8_LAS bf16x8*)(lds + PG8_SA(b, h) + aoff + m * 2048 + k * 1024); } while (0)
; #define PG8_LDB(dst, b, h) do { _Pragma("unroll") for (int n = 0; n < 2; ++n) _Pragma("unroll") for (int k = 0; k < 2; ++k) dst[n][k] = *(const PG8_LAS bf16x8*)(lds + PG8_SB(b, h) + boff + n * 2048 + k * 1024); } while (0)
; #define PG8_MMA(ai, bj, At, Bt) do { __builtin_amdgcn_s_setprio(1); _Pragma("unroll") for (int m = 0; m < 4; ++m) _Pragma("unroll") for (int n = 0; n < 2; ++n) _Pragma("unroll") for (int k = 0; k < 2; ++k) \
;         acc[ai][bj][m][n] = __builtin_amdgcn_mfma_f32_16x16x32_bf16(Bt[n][k], At[m][k], acc[ai][bj][m][n], 0, 0, 0); __builtin_amdgcn_s_setprio(0); } while (0)
; #define PG8_WAIT_V(n) asm volatile("s_waitcnt vmcnt(" #n ")" ::: "memory")
; #define PG8_WAIT_L(n) asm volatile("s_waitcnt lgkmcnt(" #n ")" ::: "memory")
; #define PG8_BAR __builtin_amdgcn_s_barrier()
; #define PG8_SCHED __builtin_amdgcn_sched_barrier(0)
; template <class Epi, class Sched, bool ALIGN_EPI = false, bool SP2 = false>
; __device__ __forceinline__ void gemm_phase(PG8_LAS unsigned char* lds, const Gemm g, const Sched& S, const Epi& E) {
;     ...
;             PG8_WAIT_V(8); PG8_WAIT_L(0); PG8_BAR; PG8_MMA(1, 0, At, B0); PG8_MMA(1, 1, At, B1); PG8_BAR; PG8_SCHED;
;             PG8_LDB(B0, 1, 0); PG8_LDB(B1, 1, 1); PG8_SCHED; PG8_LDA(At, 1, 0); PG8_STAGE(PG8_SA(0, 1), a2 + hstep, voffA);
;             PG8_WAIT_V(8); PG8_WAIT_L(0); PG8_BAR; PG8_MMA(0, 0, At, B0); PG8_MMA(0, 1, At, B1); PG8_BAR; PG8_SCHED;
	s_setprio 1
	s_waitcnt lgkmcnt(0)
	v_mfma_f32_16x16x32_bf16 v[60:63], v[154:157], v[186:189], 0
	v_mfma_f32_16x16x32_bf16 v[56:59], v[162:165], v[186:189], 0
	v_mfma_f32_16x16x32_bf16 v[52:55], v[154:157], v[198:201], 0
	v_mfma_f32_16x16x32_bf16 v[44:47], v[162:165], v[198:201], 0
	v_mfma_f32_16x16x32_bf16 v[36:39], v[154:157], v[206:209], 0
	v_mfma_f32_16x16x32_bf16 v[28:31], v[162:165], v[206:209], 0
	v_mfma_f32_16x16x32_bf16 v[20:23], v[154:157], v[214:217], 0
	v_mfma_f32_16x16x32_bf16 v[12:15], v[162:165], v[214:217], 0
	v_mfma_f32_16x16x32_bf16 v[60:63], v[158:161], v[194:197], v[60:63]
	v_mfma_f32_16x16x32_bf16 v[56:59], v[166:169], v[194:197], v[56:59]
	v_mfma_f32_16x16x32_bf16 v[52:55], v[158:161], v[202:205], v[52:55]
	v_mfma_f32_16x16x32_bf16 v[44:47], v[166:169], v[202:205], v[44:47]
	v_mfma_f32_16x16x32_bf16 v[36:39], v[158:161], v[210:213], v[36:39]
	v_mfma_f32_16x16x32_bf16 v[28:31], v[166:169], v[210:213], v[28:31]
	v_mfma_f32_16x16x32_bf16 v[20:23], v[158:161], v[218:221], v[20:23]
	v_mfma_f32_16x16x32_bf16 v[12:15], v[166:169], v[218:221], v[12:15]
	s_setprio 0
	s_setprio 1
	v_mfma_f32_16x16x32_bf16 v[48:51], v[170:173], v[186:189], 0
	v_mfma_f32_16x16x32_bf16 v[40:43], v[178:181], v[186:189], 0
	v_mfma_f32_16x16x32_bf16 v[32:35], v[170:173], v[198:201], 0
	v_mfma_f32_16x16x32_bf16 v[24:27], v[178:181], v[198:201], 0
	v_mfma_f32_16x16x32_bf16 v[16:19], v[170:173], v[206:209], 0
	v_mfma_f32_16x16x32_bf16 v[8:11], v[178:181], v[206:209], 0
	v_mfma_f32_16x16x32_bf16 v[4:7], v[170:173], v[214:217], 0
	v_mfma_f32_16x16x32_bf16 v[0:3], v[178:181], v[214:217], 0
	v_mfma_f32_16x16x32_bf16 v[48:51], v[174:177], v[194:197], v[48:51]
	v_mfma_f32_16x16x32_bf16 v[40:43], v[182:185], v[194:197], v[40:43]
	v_mfma_f32_16x16x32_bf16 v[32:35], v[174:177], v[202:205], v[32:35]
	v_mfma_f32_16x16x32_bf16 v[24:27], v[182:185], v[202:205], v[24:27]
	v_mfma_f32_16x16x32_bf16 v[16:19], v[174:177], v[210:213], v[16:19]
	v_mfma_f32_16x16x32_bf16 v[8:11], v[182:185], v[210:213], v[8:11]
	v_mfma_f32_16x16x32_bf16 v[4:7], v[174:177], v[218:221], v[4:7]
	v_mfma_f32_16x16x32_bf16 v[0:3], v[182:185], v[218:221], v[0:3]
	s_setprio 0
	s_barrier
	s_add_i32 s83, 0, 0x18000
	v_add_u32_e32 v153, s83, v149
	s_add_i32 s84, 0, 0x1c000
	ds_read_b128 v[154:157], v153
	ds_read_b128 v[158:161], v153 offset:1024
	ds_read_b128 v[162:165], v153 offset:2048
	ds_read_b128 v[166:169], v153 offset:3072
	v_add_u32_e32 v153, s84, v149
	ds_read_b128 v[170:173], v153
	ds_read_b128 v[174:177], v153 offset:1024
	ds_read_b128 v[178:181], v153 offset:2048
	ds_read_b128 v[182:185], v153 offset:3072
	s_add_u32 s34, s34, 0x80000
	s_addc_u32 s35, s35, 0
	s_mov_b32 m0, s56
	v_lshl_add_u64 v[226:227], s[34:35], 0, v[134:135]
	ds_read_b128 v[186:189], v152 offset:32768
	ds_read_b128 v[194:197], v152 offset:33792
	ds_read_b128 v[198:201], v152 offset:34816
	ds_read_b128 v[202:205], v152 offset:35840
	ds_read_b128 v[206:209], v152 offset:36864
	ds_read_b128 v[210:213], v152 offset:37888
	ds_read_b128 v[214:217], v152 offset:38912
	ds_read_b128 v[218:221], v152 offset:39936
	global_load_lds_dwordx4 v[226:227], off
	v_lshl_add_u64 v[226:227], s[34:35], 0, v[130:131]
	s_mov_b32 m0, s57
	s_nop 0
	global_load_lds_dwordx4 v[226:227], off
	s_waitcnt vmcnt(8)
	s_waitcnt lgkmcnt(0)
	s_barrier
	s_setprio 1
	s_waitcnt lgkmcnt(0)
	v_mfma_f32_16x16x32_bf16 v[124:127], v[154:157], v[186:189], v[124:127]
	v_mfma_f32_16x16x32_bf16 v[120:123], v[162:165], v[186:189], v[120:123]
	v_mfma_f32_16x16x32_bf16 v[116:119], v[154:157], v[198:201], v[116:119]
	v_mfma_f32_16x16x32_bf16 v[108:111], v[162:165], v[198:201], v[108:111]
	v_mfma_f32_16x16x32_bf16 v[100:103], v[154:157], v[206:209], v[100:103]
	v_mfma_f32_16x16x32_bf16 v[92:95], v[162:165], v[206:209], v[92:95]
	v_mfma_f32_16x16x32_bf16 v[84:87], v[154:157], v[214:217], v[84:87]
	v_mfma_f32_16x16x32_bf16 v[76:79], v[162:165], v[214:217], v[76:79]
	v_mfma_f32_16x16x32_bf16 v[124:127], v[158:161], v[194:197], v[124:127]
	v_mfma_f32_16x16x32_bf16 v[120:123], v[166:169], v[194:197], v[120:123]
	v_mfma_f32_16x16x32_bf16 v[116:119], v[158:161], v[202:205], v[116:119]
	v_mfma_f32_16x16x32_bf16 v[108:111], v[166:169], v[202:205], v[108:111]
	v_mfma_f32_16x16x32_bf16 v[100:103], v[158:161], v[210:213], v[100:103]
	v_mfma_f32_16x16x32_bf16 v[92:95], v[166:169], v[210:213], v[92:95]
	v_mfma_f32_16x16x32_bf16 v[84:87], v[158:161], v[218:221], v[84:87]
	v_mfma_f32_16x16x32_bf16 v[76:79], v[166:169], v[218:221], v[76:79]
	s_setprio 0
	s_setprio 1
	v_mfma_f32_16x16x32_bf16 v[112:115], v[170:173], v[186:189], v[112:115]
	v_mfma_f32_16x16x32_bf16 v[104:107], v[178:181], v[186:189], v[104:107]
	v_mfma_f32_16x16x32_bf16 v[96:99], v[170:173], v[198:201], v[96:99]
	v_mfma_f32_16x16x32_bf16 v[88:91], v[178:181], v[198:201], v[88:91]
	v_mfma_f32_16x16x32_bf16 v[80:83], v[170:173], v[206:209], v[80:83]
	v_mfma_f32_16x16x32_bf16 v[72:75], v[178:181], v[206:209], v[72:75]
	v_mfma_f32_16x16x32_bf16 v[68:71], v[170:173], v[214:217], v[68:71]
	v_mfma_f32_16x16x32_bf16 v[64:67], v[178:181], v[214:217], v[64:67]
	v_mfma_f32_16x16x32_bf16 v[112:115], v[174:177], v[194:197], v[112:115]
	v_mfma_f32_16x16x32_bf16 v[104:107], v[182:185], v[194:197], v[104:107]
	v_mfma_f32_16x16x32_bf16 v[96:99], v[174:177], v[202:205], v[96:99]
	v_mfma_f32_16x16x32_bf16 v[88:91], v[182:185], v[202:205], v[88:91]
	v_mfma_f32_16x16x32_bf16 v[80:83], v[174:177], v[210:213], v[80:83]
	v_mfma_f32_16x16x32_bf16 v[72:75], v[182:185], v[210:213], v[72:75]
	v_mfma_f32_16x16x32_bf16 v[68:71], v[174:177], v[218:221], v[68:71]
	v_mfma_f32_16x16x32_bf16 v[64:67], v[182:185], v[218:221], v[64:67]
	s_setprio 0
	s_barrier
; #define PG8_STAGE(bufoff, gbase, voff) do { _Pragma("unroll") for (int _i = 0; _i < 2; ++_i) \
;         __builtin_amdgcn_global_load_lds((const unsigned*)((const char*)(gbase) + (voff)[_i]), (PG8_LAS unsigned*)(lds + (bufoff) + ldsw + _i * 8192), 16, 0, 0); } while (0)
; #define PG8_LDA(dst, b, h) do { _Pragma("unroll") for (int m = 0; m < 4; ++m) _Pragma("unroll") for (int k = 0; k < 2; ++k) dst[m][k] = *(const PG8_LAS bf16x8*)(lds + PG8_SA(b, h) + aoff + m * 2048 + k * 1024); } while (0)
; #define PG8_MMA(ai, bj, At, Bt) do { __builtin_amdgcn_s_setprio(1); _Pragma("unroll") for (int m = 0; m < 4; ++m) _Pragma("unroll") for (int n = 0; n < 2; ++n) _Pragma("unroll") for (int k = 0; k < 2; ++k) \
;         acc[ai][bj][m][n] = __builtin_amdgcn_mfma_f32_16x16x32_bf16(Bt[n][k], At[m][k], acc[ai][bj][m][n], 0, 0, 0); __builtin_amdgcn_s_setprio(0); } while (0)
; #define PG8_WAIT_V(n) asm volatile("s_waitcnt vmcnt(" #n ")" ::: "memory")
; #define PG8_WAIT_L(n) asm volatile("s_waitcnt lgkmcnt(" #n ")" ::: "memory")
; #define PG8_BAR __builtin_amdgcn_s_barrier()
; #define PG8_SCHED __builtin_amdgcn_sched_barrier(0)
; template <class Epi, class Sched, bool ALIGN_EPI = false, bool SP2 = false>
; __device__ __forceinline__ void gemm_phase(PG8_LAS unsigned char* lds, const Gemm g, const Sched& S, const Epi& E) {
;     ...
;         for (int t = 0; t < nt; t += 2) {
;             const bool last = (t == nt - 2);
;     ...
;             PG8_LDA(At, 1, 1); PG8_STAGE(PG8_SB(1, 0), b3, voffB); PG8_STAGE(PG8_SB(1, 1), b3 + hstep, voffB); PG8_STAGE(PG8_SA(1, 0), a3, voffA);
;             PG8_WAIT_V(8); PG8_WAIT_L(0); PG8_BAR; PG8_MMA(1, 0, At, B0); PG8_MMA(1, 1, At, B1); PG8_BAR; PG8_SCHED;
	s_add_i32 s34, s83, s36
	v_lshl_add_u64 v[146:147], v[146:147], 0, s[12:13]
	s_mov_b32 m0, s34
	ds_read_b128 v[186:189], v152 offset:49152
	ds_read_b128 v[194:197], v152 offset:50176
	ds_read_b128 v[198:201], v152 offset:51200
	ds_read_b128 v[202:205], v152 offset:52224
	ds_read_b128 v[206:209], v152 offset:53248
	ds_read_b128 v[210:213], v152 offset:54272
	ds_read_b128 v[214:217], v152 offset:55296
	ds_read_b128 v[218:221], v152 offset:56320
	global_load_lds_dwordx4 v[146:147], off
	s_add_i32 m0, s34, 0x2000
	s_add_u32 s30, s30, 0x80080
	v_lshl_add_u64 v[146:147], v[190:191], 0, s[12:13]
	s_addc_u32 s31, s31, 0
	s_add_i32 s34, s84, s36
	global_load_lds_dwordx4 v[146:147], off
	v_lshl_add_u64 v[146:147], s[30:31], 0, v[132:133]
	s_mov_b32 m0, s34
	s_nop 0
	global_load_lds_dwordx4 v[146:147], off
	v_lshl_add_u64 v[146:147], s[30:31], 0, v[128:129]
	s_add_i32 m0, s34, 0x2000
	s_nop 0
	global_load_lds_dwordx4 v[146:147], off
	v_lshl_add_u64 v[146:147], v[222:223], 0, s[12:13]
	s_mov_b32 m0, s59
	s_nop 0
	global_load_lds_dwordx4 v[146:147], off
	v_lshl_add_u64 v[146:147], v[224:225], 0, s[12:13]
	s_mov_b32 m0, s60
	s_nop 0
	global_load_lds_dwordx4 v[146:147], off
	s_waitcnt vmcnt(8)
	s_waitcnt lgkmcnt(0)
	s_barrier
	s_setprio 1
	s_waitcnt lgkmcnt(0)
	v_mfma_f32_16x16x32_bf16 v[60:63], v[154:157], v[186:189], v[60:63]
	v_mfma_f32_16x16x32_bf16 v[56:59], v[162:165], v[186:189], v[56:59]
	v_mfma_f32_16x16x32_bf16 v[52:55], v[154:157], v[198:201], v[52:55]
	v_mfma_f32_16x16x32_bf16 v[44:47], v[162:165], v[198:201], v[44:47]
	v_mfma_f32_16x16x32_bf16 v[36:39], v[154:157], v[206:209], v[36:39]
	v_mfma_f32_16x16x32_bf16 v[28:31], v[162:165], v[206:209], v[28:31]
	v_mfma_f32_16x16x32_bf16 v[20:23], v[154:157], v[214:217], v[20:23]
	v_mfma_f32_16x16x32_bf16 v[12:15], v[162:165], v[214:217], v[12:15]
	v_mfma_f32_16x16x32_bf16 v[60:63], v[158:161], v[194:197], v[60:63]
	v_mfma_f32_16x16x32_bf16 v[56:59], v[166:169], v[194:197], v[56:59]
	v_mfma_f32_16x16x32_bf16 v[52:55], v[158:161], v[202:205], v[52:55]
	v_mfma_f32_16x16x32_bf16 v[44:47], v[166:169], v[202:205], v[44:47]
	v_mfma_f32_16x16x32_bf16 v[36:39], v[158:161], v[210:213], v[36:39]
	v_mfma_f32_16x16x32_bf16 v[28:31], v[166:169], v[210:213], v[28:31]
	v_mfma_f32_16x16x32_bf16 v[20:23], v[158:161], v[218:221], v[20:23]
	v_mfma_f32_16x16x32_bf16 v[12:15], v[166:169], v[218:221], v[12:15]
	s_setprio 0
	s_setprio 1
	v_mfma_f32_16x16x32_bf16 v[48:51], v[170:173], v[186:189], v[48:51]
	v_mfma_f32_16x16x32_bf16 v[40:43], v[178:181], v[186:189], v[40:43]
	v_mfma_f32_16x16x32_bf16 v[32:35], v[170:173], v[198:201], v[32:35]
	v_mfma_f32_16x16x32_bf16 v[24:27], v[178:181], v[198:201], v[24:27]
	v_mfma_f32_16x16x32_bf16 v[16:19], v[170:173], v[206:209], v[16:19]
	v_mfma_f32_16x16x32_bf16 v[8:11], v[178:181], v[206:209], v[8:11]
	v_mfma_f32_16x16x32_bf16 v[4:7], v[170:173], v[214:217], v[4:7]
	v_mfma_f32_16x16x32_bf16 v[0:3], v[178:181], v[214:217], v[0:3]
	v_mfma_f32_16x16x32_bf16 v[48:51], v[174:177], v[194:197], v[48:51]
	v_mfma_f32_16x16x32_bf16 v[40:43], v[182:185], v[194:197], v[40:43]
	v_mfma_f32_16x16x32_bf16 v[32:35], v[174:177], v[202:205], v[32:35]
	v_mfma_f32_16x16x32_bf16 v[24:27], v[182:185], v[202:205], v[24:27]
	v_mfma_f32_16x16x32_bf16 v[16:19], v[174:177], v[210:213], v[16:19]
	v_mfma_f32_16x16x32_bf16 v[8:11], v[182:185], v[210:213], v[8:11]
	v_mfma_f32_16x16x32_bf16 v[4:7], v[174:177], v[218:221], v[4:7]
	v_mfma_f32_16x16x32_bf16 v[0:3], v[182:185], v[218:221], v[0:3]
	s_setprio 0
	s_barrier
	s_add_i32 s82, s82, 2
	s_add_u32 s80, s80, 0x100
	s_addc_u32 s81, s81, 0
	s_add_u32 s28, s28, 0x100
	s_addc_u32 s29, s29, 0
	s_cmp_gt_u32 s82, 29
	s_cbranch_scc1 .Lpeel_exit_4
	.p2align	6

; #define SBAR() __builtin_amdgcn_sched_barrier(0)
; __device__ __forceinline__ int v_st(int k, int c) { const int kk = (k & ~0xC) | ((k & 4) << 1) | ((k & 8) >> 1); return ((kk >> 3) * 4 + (c >> 5)) * 512 + ((kk & 7) * 32 + (c & 31)) * 2; }
; __device__ __forceinline__ int v_rd_base(int lane) { return ((lane & 3) << 3) | (((lane >> 2) & 3) << 6) | (((lane >> 4) & 1) << 5) | (((lane >> 5) & 1) << 8); }
; #define VMW() asm volatile("s_waitcnt vmcnt(0)" ::: "memory")
; #define SWRITE_HV(bf) do { *(bf16x8*)(V_lds + (bf) * SHM_V + vst0) = S.st_v0; *(bf16x8*)(V_lds + (bf) * SHM_V + vst1) = S.st_v1; } while (0)
; #define SWRITE_H(bf) do { SWRITE_HV(bf); SWRITE_HK(bf); } while (0)
; #define SWRITE_KF(bf) do { *(bf16x8*)(K_lds + (bf) * SHM_K + kws) = pack8(S.sf0, S.sf1); *(bf16x8*)(K_lds + (bf) * SHM_K + kws + 32 * 256) = pack8(S.sf2, S.sf3); } while (0)
; template <class TIn, class TOut, bool NB = false>
; __device__ __forceinline__ void causal_swa_block(const BlockRef<TIn, TOut>& cur, const BlockRef<TIn, TOut>& nxt, int skv, int W, char* lds, Seam<TIn>& S) {
;     ...
;     float* ws = (float*)(lds + 2 * SHM_V + 2 * SHM_K) + wid * 64; float* li_l = ws, * al_l = ws + 32;
;     float m_reg = -1e30f, l_reg = 0; f32x16 o[4] = {};
;     const int sr = tid >> 4, sc = (tid & 15) * 8, vst0 = v_st(sr, sc), vst1 = v_st(32 + sr, sc), kws = KSWZ(sr, sc * 2);
;     const int vb0 = (int)(uintptr_t)V_lds + v_rd_base(lane);
;     const TIn* Kh = cur.K; const TIn* Vh = cur.V; const float* Gh = cur.G; const float* g_lds = (const float*)(K_lds + 2 * SHM_K + NW * 256);
;     ...
;     constexpr int NQL = F32 ? 16 : 8;
;     constexpr bool SK = WSKIP && !F32;
;     ...
;     f32x16 pA0, pA1, pB0, pB1; float mnA, mnB, alA, alB; bf16x8 pa0, pa1, pa2, pa3;
;     if constexpr (F32) { VMW(); SWRITE_VF(0); SBAR(); } else { SWRITE_HV(0); SBAR(); }
;     if (NT > 1) { if constexpr (F32) SLOAD_F((const float*)Kh, KBASE(1)); else SLOAD_H(Kh, Vh, Gh, KBASE(1)); }
;     SBAR(); qkt<0, SK, NB>(pA0, pA1, K_lds, r32, hi, S.qr, ACT(0), g_lds, S.gt);
;     if constexpr (F32) { if (NT > 1) { VMW(); SWRITE_KF(1); SBAR(); SLOAD_F((const float*)Vh, KBASE(1)); } }
;     MASKT(pA0, pA1, 0); partialSM(pA0, pA1, m_reg, mnA, alA);
;     if (NT > 1) { VMW(); if constexpr (F32) { SWRITE_VF(1); SBAR(); if (NT > 2) SLOAD_F((const float*)Kh, KBASE(2)); } else SWRITE_H(1); }
;     __syncthreads();
.LBB0_802:
	v_max_f32_e32 v41, 0xf149f2ca, v52
	v_cndmask_b32_e64 v176, v41, v204, s[8:9]
	v_mul_f32_e32 v40, 0xbe0293ee, v176
	v_fmamk_f32 v16, v16, 0x3e0293ee, v40
	v_exp_f32_e32 v173, v16
	v_sub_f32_e32 v16, 0xf149f2ca, v41
	v_mul_f32_e32 v16, 0x3e0293ee, v16
	v_exp_f32_e32 v16, v16
	v_pk_fma_f32 v[122:123], v[2:3], s[16:17], v[40:41] op_sel_hi:[1,0,0]
	v_pk_fma_f32 v[124:125], v[0:1], s[16:17], v[40:41] op_sel_hi:[1,0,0]
	v_lshlrev_b32_e32 v0, 8, v48
	v_cndmask_b32_e64 v223, v16, 1.0, s[8:9]
	s_and_b32 s8, s49, 0x3fffffc0
	s_lshl_b32 s8, s8, 2
	s_add_i32 s8, s8, 0
	s_add_i32 s46, s8, 0x10000
	v_and_b32_e32 v1, 0x70, v206
	v_lshlrev_b32_e32 v2, 4, v51
	v_bitop3_b32 v0, v49, v0, v1 bitop3:0xde
	v_lshlrev_b32_e32 v1, 3, v51
	v_and_b32_e32 v2, 0xc0, v2
	v_lshlrev_b32_e32 v3, 1, v51
	s_cmp_lg_u32 0, -1
	v_mov_b32_e32 v197, v195
	v_fmamk_f32 v17, v17, 0x3e0293ee, v40
	v_fmamk_f32 v18, v18, 0x3e0293ee, v40
	v_fmamk_f32 v19, v19, 0x3e0293ee, v40
	v_fmamk_f32 v20, v20, 0x3e0293ee, v40
	v_fmamk_f32 v21, v21, 0x3e0293ee, v40
	v_fmamk_f32 v22, v22, 0x3e0293ee, v40
	v_fmamk_f32 v23, v23, 0x3e0293ee, v40
	v_fmamk_f32 v24, v24, 0x3e0293ee, v40
	v_fmamk_f32 v25, v25, 0x3e0293ee, v40
	v_fmamk_f32 v26, v26, 0x3e0293ee, v40
	v_fmamk_f32 v27, v27, 0x3e0293ee, v40
	v_fmamk_f32 v28, v28, 0x3e0293ee, v40
	v_fmamk_f32 v29, v29, 0x3e0293ee, v40
	v_fmamk_f32 v30, v30, 0x3e0293ee, v40
	v_fmamk_f32 v31, v31, 0x3e0293ee, v40
	v_and_or_b32 v2, v1, 24, v2
	v_and_b32_e32 v3, 32, v3
	v_and_b32_e32 v1, 0x100, v1
	s_cselect_b32 s8, 0, 0
	v_lshl_add_u64 v[200:201], s[10:11], 0, v[196:197]
	s_add_i32 s10, s31, 0xc0
	v_exp_f32_e32 v175, v17
	v_exp_f32_e32 v171, v18
	v_exp_f32_e32 v174, v19
	v_exp_f32_e32 v170, v20
	v_exp_f32_e32 v172, v21
	v_exp_f32_e32 v168, v22
	v_exp_f32_e32 v169, v23
	v_exp_f32_e32 v163, v24
	v_exp_f32_e32 v166, v25
	v_exp_f32_e32 v161, v26
	v_exp_f32_e32 v164, v27
	v_exp_f32_e32 v160, v28
	v_exp_f32_e32 v167, v29
	v_exp_f32_e32 v162, v30
	v_exp_f32_e32 v165, v31
	v_or3_b32 v1, v2, v3, v1
	v_add_u32_e32 v210, 0, v0
	v_add_u32_e32 v0, s10, v208
	v_add_u32_e32 v213, s8, v1
	ds_write_b128 v210, v[32:35] offset:49152
	ds_write_b128 v210, v[36:39] offset:57344
	s_add_i32 s8, 0, 0x10800
	v_sub_u32_e32 v0, v0, v50
	v_mov_b32_e32 v32, v195
	v_mov_b32_e32 v33, v195
	v_mov_b32_e32 v46, v195
	v_mov_b32_e32 v47, v195
	v_pk_fma_f32 v[116:117], v[14:15], s[16:17], v[40:41] op_sel_hi:[1,0,0]
	v_pk_fma_f32 v[120:121], v[12:13], s[16:17], v[40:41] op_sel_hi:[1,0,0]
	v_pk_fma_f32 v[126:127], v[10:11], s[16:17], v[40:41] op_sel_hi:[1,0,0]
	v_pk_fma_f32 v[112:113], v[8:9], s[16:17], v[40:41] op_sel_hi:[1,0,0]
	v_pk_fma_f32 v[114:115], v[6:7], s[16:17], v[40:41] op_sel_hi:[1,0,0]
	v_pk_fma_f32 v[118:119], v[4:5], s[16:17], v[40:41] op_sel_hi:[1,0,0]
	v_lshl_add_u32 v212, v51, 2, s8
	v_cmp_gt_u32_e64 s[8:9], 32, v51
	v_lshl_add_u32 v209, v50, 2, s46
	v_subrev_u32_e32 v224, s48, v0
	v_mov_b32_e32 v34, v195
	v_mov_b32_e32 v35, v195
	v_mov_b32_e32 v36, v195
	v_mov_b32_e32 v37, v195
	v_mov_b32_e32 v38, v195
	v_mov_b32_e32 v39, v195
	v_mov_b32_e32 v40, v195
	v_mov_b32_e32 v41, v195
	v_mov_b32_e32 v42, v195
	v_mov_b32_e32 v43, v195
	v_mov_b32_e32 v44, v195
	v_mov_b32_e32 v45, v195
	v_mov_b64_e32 v[62:63], v[46:47]
	v_mov_b64_e32 v[16:17], v[32:33]
	v_mov_b64_e32 v[0:1], v[32:33]
	s_mov_b32 s68, 2
	v_lshl_add_u32 v211, v208, 2, s46
	v_mov_b32_e32 v222, 0
	v_mov_b64_e32 v[60:61], v[44:45]
	v_mov_b64_e32 v[58:59], v[42:43]
	v_mov_b64_e32 v[56:57], v[40:41]
	v_mov_b64_e32 v[54:55], v[38:39]
	v_mov_b64_e32 v[52:53], v[36:37]
	v_mov_b64_e32 v[50:51], v[34:35]
	v_mov_b64_e32 v[48:49], v[32:33]
	v_mov_b64_e32 v[18:19], v[34:35]
	v_mov_b64_e32 v[20:21], v[36:37]
	v_mov_b64_e32 v[22:23], v[38:39]
	v_mov_b64_e32 v[24:25], v[40:41]
	v_mov_b64_e32 v[26:27], v[42:43]
	v_mov_b64_e32 v[28:29], v[44:45]
	v_mov_b64_e32 v[30:31], v[46:47]
	v_mov_b64_e32 v[2:3], v[34:35]
	v_mov_b64_e32 v[4:5], v[36:37]
	v_mov_b64_e32 v[6:7], v[38:39]
	v_mov_b64_e32 v[8:9], v[40:41]
	v_mov_b64_e32 v[10:11], v[42:43]
	v_mov_b64_e32 v[12:13], v[44:45]
	v_mov_b64_e32 v[14:15], v[46:47]
	s_waitcnt lgkmcnt(0)
	s_barrier
	.p2align	6

; #define PG8_STAGE(bufoff, gbase, voff) do { _Pragma("unroll") for (int _i = 0; _i < 2; ++_i) \
;         __builtin_amdgcn_global_load_lds((const unsigned*)((const char*)(gbase) + (voff)[_i]), (PG8_LAS unsigned*)(lds + (bufoff) + ldsw + _i * 8192), 16, 0, 0); } while (0)
; #define PG8_LDA(dst, b, h) do { _Pragma("unroll") for (int m = 0; m < 4; ++m) _Pragma("unroll") for (int k = 0; k < 2; ++k) dst[m][k] = *(const PG8_LAS bf16x8*)(lds + PG8_SA(b, h) + aoff + m * 2048 + k * 1024); } while (0)
; #define PG8_LDB(dst, b, h) do { _Pragma("unroll") for (int n = 0; n < 2; ++n) _Pragma("unroll") for (int k = 0; k < 2; ++k) dst[n][k] = *(const PG8_LAS bf16x8*)(lds + PG8_SB(b, h) + boff + n * 2048 + k * 1024); } while (0)
; #define PG8_MMA(ai, bj, At, Bt) do { __builtin_amdgcn_s_setprio(1); _Pragma("unroll") for (int m = 0; m < 4; ++m) _Pragma("unroll") for (int n = 0; n < 2; ++n) _Pragma("unroll") for (int k = 0; k < 2; ++k) \
;         acc[ai][bj][m][n] = __builtin_amdgcn_mfma_f32_16x16x32_bf16(Bt[n][k], At[m][k], acc[ai][bj][m][n], 0, 0, 0); __builtin_amdgcn_s_setprio(0); } while (0)
; #define PG8_WAIT_V(n) asm volatile("s_waitcnt vmcnt(" #n ")" ::: "memory")
; #define PG8_WAIT_L(n) asm volatile("s_waitcnt lgkmcnt(" #n ")" ::: "memory")
; template <class Epi, class Sched, bool ALIGN_EPI = false, bool SP2 = false>
; __device__ __forceinline__ void gemm_phase(PG8_LAS unsigned char* lds, const Gemm g, const Sched& S, const Epi& E) {
;     ...
;             const bool last = (t == nt - 2);
;             const char* a1 = cA + (size_t)(t + 1) * kstep;
;             const char* a2 = last ? nA : cA + (size_t)(t + 2) * kstep; const char* b2 = last ? nB : cB + (size_t)(t + 2) * kstep;
;             const char* a3 = a2 + kstep; const char* b3 = b2 + kstep;
;             if (last && has_next) S.a_ready(nxt);
;             if constexpr (SP2) {
;             PG8_LDB(B0, 0, 0); PG8_LDB(B1, 0, 1); PG8_SCHED; PG8_LDA(At, 0, 0); PG8_STAGE(PG8_SA(1, 1), a1 + hstep, voffA);
;             PG8_WAIT_V(8); PG8_WAIT_L(0); PG8_BAR; PG8_MMA(0, 0, At, B0); PG8_MMA(0, 1, At, B1); PG8_BAR; PG8_SCHED;
;             PG8_LDA(At, 0, 1); PG8_STAGE(PG8_SB(0, 0), b2, voffB); PG8_STAGE(PG8_SB(0, 1), b2 + hstep, voffB); PG8_STAGE(PG8_SA(0, 0), a2, voffA);
;             PG8_WAIT_V(8); PG8_WAIT_L(0); PG8_BAR; PG8_MMA(1, 0, At, B0); PG8_MMA(1, 1, At, B1); PG8_BAR; PG8_SCHED;
.LBB0_1041:
	s_ashr_i32 s25, s24, 31
	s_lshl_b64 s[28:29], s[24:25], 20
	s_add_u32 s28, s56, s28
	s_addc_u32 s29, s57, s29
	s_and_b64 s[30:31], s[6:7], exec
	s_cselect_b32 s25, s29, s49
	s_cselect_b32 s73, s28, s48
	s_ashr_i32 s27, s26, 31
	s_lshl_b64 s[30:31], s[26:27], 20
	s_add_u32 s30, s54, s30
	s_addc_u32 s31, s55, s31
	s_and_b64 s[50:51], s[6:7], exec
	s_cselect_b32 s27, s31, s47
	s_cselect_b32 s74, s30, s46
	s_add_u32 s75, s46, 0x100
	s_addc_u32 s76, s47, 0
	s_add_u32 s46, s48, 0x80080
	s_addc_u32 s47, s49, 0
	s_mov_b32 s77, -2
	ds_read_b128 v[120:123], v169
	ds_read_b128 v[124:127], v169 offset:1024
	ds_read_b128 v[128:131], v169 offset:2048
	ds_read_b128 v[132:135], v169 offset:3072
	ds_read_b128 v[160:163], v170
	ds_read_b128 v[172:175], v170 offset:1024
	ds_read_b128 v[176:179], v170 offset:2048
	ds_read_b128 v[180:183], v170 offset:3072
	s_add_u32 s48, s46, 0xfff80080
	s_addc_u32 s49, s47, -1
	s_cmp_eq_u32 s77, 28
	s_cselect_b32 s51, s25, s49
	s_cselect_b32 s50, s73, s48
	s_cselect_b32 s49, s27, s76
	s_cselect_b32 s48, s74, s75
	v_lshl_add_u64 v[164:165], s[46:47], 0, v[154:155]
	s_add_i32 m0, s35, 0xc000
	ds_read_b128 v[184:187], v171
	ds_read_b128 v[188:191], v171 offset:1024
	ds_read_b128 v[194:197], v171 offset:2048
	ds_read_b128 v[198:201], v171 offset:3072
	ds_read_b128 v[202:205], v171 offset:4096
	ds_read_b128 v[206:209], v171 offset:5120
	ds_read_b128 v[210:213], v171 offset:6144
	ds_read_b128 v[214:217], v171 offset:7168
	global_load_lds_dwordx4 v[164:165], off
	v_lshl_add_u64 v[164:165], s[46:47], 0, v[152:153]
	s_add_i32 m0, s35, 0xe000
	s_nop 0
	global_load_lds_dwordx4 v[164:165], off
	s_waitcnt vmcnt(8)
	s_waitcnt lgkmcnt(0)
	s_barrier
	s_setprio 1
	s_waitcnt lgkmcnt(0)
	v_mfma_f32_16x16x32_bf16 v[140:143], v[120:123], v[184:187], 0
	v_mfma_f32_16x16x32_bf16 v[136:139], v[128:131], v[184:187], 0
	v_mfma_f32_16x16x32_bf16 v[112:115], v[120:123], v[194:197], 0
	v_mfma_f32_16x16x32_bf16 v[104:107], v[128:131], v[194:197], 0
	v_mfma_f32_16x16x32_bf16 v[96:99], v[120:123], v[202:205], 0
	v_mfma_f32_16x16x32_bf16 v[88:91], v[128:131], v[202:205], 0
	v_mfma_f32_16x16x32_bf16 v[80:83], v[120:123], v[210:213], 0
	v_mfma_f32_16x16x32_bf16 v[72:75], v[128:131], v[210:213], 0
	v_mfma_f32_16x16x32_bf16 v[140:143], v[124:127], v[188:191], v[140:143]
	v_mfma_f32_16x16x32_bf16 v[136:139], v[132:135], v[188:191], v[136:139]
	v_mfma_f32_16x16x32_bf16 v[112:115], v[124:127], v[198:201], v[112:115]
	v_mfma_f32_16x16x32_bf16 v[104:107], v[132:135], v[198:201], v[104:107]
	v_mfma_f32_16x16x32_bf16 v[96:99], v[124:127], v[206:209], v[96:99]
	v_mfma_f32_16x16x32_bf16 v[88:91], v[132:135], v[206:209], v[88:91]
	v_mfma_f32_16x16x32_bf16 v[80:83], v[124:127], v[214:217], v[80:83]
	v_mfma_f32_16x16x32_bf16 v[72:75], v[132:135], v[214:217], v[72:75]
	s_setprio 0
	s_setprio 1
	v_mfma_f32_16x16x32_bf16 v[116:119], v[160:163], v[184:187], 0
	v_mfma_f32_16x16x32_bf16 v[108:111], v[176:179], v[184:187], 0
	v_mfma_f32_16x16x32_bf16 v[100:103], v[160:163], v[194:197], 0
	v_mfma_f32_16x16x32_bf16 v[92:95], v[176:179], v[194:197], 0
	v_mfma_f32_16x16x32_bf16 v[84:87], v[160:163], v[202:205], 0
	v_mfma_f32_16x16x32_bf16 v[76:79], v[176:179], v[202:205], 0
	v_mfma_f32_16x16x32_bf16 v[68:71], v[160:163], v[210:213], 0
	v_mfma_f32_16x16x32_bf16 v[64:67], v[176:179], v[210:213], 0
	v_mfma_f32_16x16x32_bf16 v[116:119], v[172:175], v[188:191], v[116:119]
	v_mfma_f32_16x16x32_bf16 v[108:111], v[180:183], v[188:191], v[108:111]
	v_mfma_f32_16x16x32_bf16 v[100:103], v[172:175], v[198:201], v[100:103]
	v_mfma_f32_16x16x32_bf16 v[92:95], v[180:183], v[198:201], v[92:95]
	v_mfma_f32_16x16x32_bf16 v[84:87], v[172:175], v[206:209], v[84:87]
	v_mfma_f32_16x16x32_bf16 v[76:79], v[180:183], v[206:209], v[76:79]
	v_mfma_f32_16x16x32_bf16 v[68:71], v[172:175], v[214:217], v[68:71]
	v_mfma_f32_16x16x32_bf16 v[64:67], v[180:183], v[214:217], v[64:67]
	s_setprio 0
	s_barrier
	s_add_i32 s78, s67, s58
	v_lshl_add_u64 v[164:165], s[48:49], 0, v[146:147]
	s_mov_b32 m0, s78
	ds_read_b128 v[184:187], v171 offset:16384
	ds_read_b128 v[188:191], v171 offset:17408
	ds_read_b128 v[194:197], v171 offset:18432
	ds_read_b128 v[198:201], v171 offset:19456
	ds_read_b128 v[202:205], v171 offset:20480
	ds_read_b128 v[206:209], v171 offset:21504
	ds_read_b128 v[210:213], v171 offset:22528
	ds_read_b128 v[214:217], v171 offset:23552
	global_load_lds_dwordx4 v[164:165], off
	s_add_i32 m0, s78, 0x2000
	s_add_u32 s78, s48, 0x80000
	v_lshl_add_u64 v[218:219], s[48:49], 0, v[150:151]
	s_addc_u32 s79, s49, 0
	s_add_i32 s80, s68, s58
	global_load_lds_dwordx4 v[218:219], off
	v_lshl_add_u64 v[220:221], s[78:79], 0, v[146:147]
	s_mov_b32 m0, s80
	v_lshl_add_u64 v[222:223], s[50:51], 0, v[148:149]
	global_load_lds_dwordx4 v[220:221], off
	v_lshl_add_u64 v[220:221], s[78:79], 0, v[150:151]
	s_add_i32 m0, s80, 0x2000
	s_nop 0
	global_load_lds_dwordx4 v[220:221], off
	v_lshl_add_u64 v[220:221], s[50:51], 0, v[144:145]
	s_mov_b32 m0, s35
	s_nop 0
	global_load_lds_dwordx4 v[220:221], off
	s_mov_b32 m0, s37
	s_nop 0
	global_load_lds_dwordx4 v[222:223], off
	s_waitcnt vmcnt(8)
	s_waitcnt lgkmcnt(0)
	s_barrier
; #define PG8_STAGE(bufoff, gbase, voff) do { _Pragma("unroll") for (int _i = 0; _i < 2; ++_i) \
;         __builtin_amdgcn_global_load_lds((const unsigned*)((const char*)(gbase) + (voff)[_i]), (PG8_LAS unsigned*)(lds + (bufoff) + ldsw + _i * 8192), 16, 0, 0); } while (0)
; #define PG8_LDA(dst, b, h) do { _Pragma("unroll") for (int m = 0; m < 4; ++m) _Pragma("unroll") for (int k = 0; k < 2; ++k) dst[m][k] = *(const PG8_LAS bf16x8*)(lds + PG8_SA(b, h) + aoff + m * 2048 + k * 1024); } while (0)
; #define PG8_LDB(dst, b, h) do { _Pragma("unroll") for (int n = 0; n < 2; ++n) _Pragma("unroll") for (int k = 0; k < 2; ++k) dst[n][k] = *(const PG8_LAS bf16x8*)(lds + PG8_SB(b, h) + boff + n * 2048 + k * 1024); } while (0)
; #define PG8_MMA(ai, bj, At, Bt) do { __builtin_amdgcn_s_setprio(1); _Pragma("unroll") for (int m = 0; m < 4; ++m) _Pragma("unroll") for (int n = 0; n < 2; ++n) _Pragma("unroll") for (int k = 0; k < 2; ++k) \
;         acc[ai][bj][m][n] = __builtin_amdgcn_mfma_f32_16x16x32_bf16(Bt[n][k], At[m][k], acc[ai][bj][m][n], 0, 0, 0); __builtin_amdgcn_s_setprio(0); } while (0)
; #define PG8_WAIT_V(n) asm volatile("s_waitcnt vmcnt(" #n ")" ::: "memory")
; #define PG8_WAIT_L(n) asm volatile("s_waitcnt lgkmcnt(" #n ")" ::: "memory")
; #define PG8_BAR __builtin_amdgcn_s_barrier()
; #define PG8_SCHED __builtin_amdgcn_sched_barrier(0)
; template <class Epi, class Sched, bool ALIGN_EPI = false, bool SP2 = false>
; __device__ __forceinline__ void gemm_phase(PG8_LAS unsigned char* lds, const Gemm g, const Sched& S, const Epi& E) {
;     ...
;             PG8_WAIT_V(8); PG8_WAIT_L(0); PG8_BAR; PG8_MMA(1, 0, At, B0); PG8_MMA(1, 1, At, B1); PG8_BAR; PG8_SCHED;
;             PG8_LDB(B0, 1, 0); PG8_LDB(B1, 1, 1); PG8_SCHED; PG8_LDA(At, 1, 0); PG8_STAGE(PG8_SA(0, 1), a2 + hstep, voffA);
;             PG8_WAIT_V(8); PG8_WAIT_L(0); PG8_BAR; PG8_MMA(0, 0, At, B0); PG8_MMA(0, 1, At, B1); PG8_BAR; PG8_SCHED;
	s_setprio 1
	s_waitcnt lgkmcnt(0)
	v_mfma_f32_16x16x32_bf16 v[60:63], v[120:123], v[184:187], 0
	v_mfma_f32_16x16x32_bf16 v[56:59], v[128:131], v[184:187], 0
	v_mfma_f32_16x16x32_bf16 v[48:51], v[120:123], v[194:197], 0
	v_mfma_f32_16x16x32_bf16 v[40:43], v[128:131], v[194:197], 0
	v_mfma_f32_16x16x32_bf16 v[32:35], v[120:123], v[202:205], 0
	v_mfma_f32_16x16x32_bf16 v[24:27], v[128:131], v[202:205], 0
	v_mfma_f32_16x16x32_bf16 v[16:19], v[120:123], v[210:213], 0
	v_mfma_f32_16x16x32_bf16 v[8:11], v[128:131], v[210:213], 0
	v_mfma_f32_16x16x32_bf16 v[60:63], v[124:127], v[188:191], v[60:63]
	v_mfma_f32_16x16x32_bf16 v[56:59], v[132:135], v[188:191], v[56:59]
	v_mfma_f32_16x16x32_bf16 v[48:51], v[124:127], v[198:201], v[48:51]
	v_mfma_f32_16x16x32_bf16 v[40:43], v[132:135], v[198:201], v[40:43]
	v_mfma_f32_16x16x32_bf16 v[32:35], v[124:127], v[206:209], v[32:35]
	v_mfma_f32_16x16x32_bf16 v[24:27], v[132:135], v[206:209], v[24:27]
	v_mfma_f32_16x16x32_bf16 v[16:19], v[124:127], v[214:217], v[16:19]
	v_mfma_f32_16x16x32_bf16 v[8:11], v[132:135], v[214:217], v[8:11]
	s_setprio 0
	s_setprio 1
	v_mfma_f32_16x16x32_bf16 v[52:55], v[160:163], v[184:187], 0
	v_mfma_f32_16x16x32_bf16 v[44:47], v[176:179], v[184:187], 0
	v_mfma_f32_16x16x32_bf16 v[36:39], v[160:163], v[194:197], 0
	v_mfma_f32_16x16x32_bf16 v[28:31], v[176:179], v[194:197], 0
	v_mfma_f32_16x16x32_bf16 v[20:23], v[160:163], v[202:205], 0
	v_mfma_f32_16x16x32_bf16 v[12:15], v[176:179], v[202:205], 0
	v_mfma_f32_16x16x32_bf16 v[4:7], v[160:163], v[210:213], 0
	v_mfma_f32_16x16x32_bf16 v[0:3], v[176:179], v[210:213], 0
	v_mfma_f32_16x16x32_bf16 v[52:55], v[172:175], v[188:191], v[52:55]
	v_mfma_f32_16x16x32_bf16 v[44:47], v[180:183], v[188:191], v[44:47]
	v_mfma_f32_16x16x32_bf16 v[36:39], v[172:175], v[198:201], v[36:39]
	v_mfma_f32_16x16x32_bf16 v[28:31], v[180:183], v[198:201], v[28:31]
	v_mfma_f32_16x16x32_bf16 v[20:23], v[172:175], v[206:209], v[20:23]
	v_mfma_f32_16x16x32_bf16 v[12:15], v[180:183], v[206:209], v[12:15]
	v_mfma_f32_16x16x32_bf16 v[4:7], v[172:175], v[214:217], v[4:7]
	v_mfma_f32_16x16x32_bf16 v[0:3], v[180:183], v[214:217], v[0:3]
	s_setprio 0
	s_barrier
	s_add_i32 s78, 0, 0x18000
	s_add_i32 s79, 0, 0x1c000
	v_add_u32_e32 v132, s78, v167
	v_add_u32_e32 v180, s79, v167
	ds_read_b128 v[120:123], v132
	ds_read_b128 v[124:127], v132 offset:1024
	ds_read_b128 v[128:131], v132 offset:2048
	ds_read_b128 v[132:135], v132 offset:3072
	ds_read_b128 v[160:163], v180
	ds_read_b128 v[172:175], v180 offset:1024
	ds_read_b128 v[176:179], v180 offset:2048
	ds_read_b128 v[180:183], v180 offset:3072
	s_add_u32 s50, s50, 0x80000
	s_addc_u32 s51, s51, 0
	s_mov_b32 m0, s59
	v_lshl_add_u64 v[224:225], s[50:51], 0, v[144:145]
	ds_read_b128 v[184:187], v171 offset:32768
	ds_read_b128 v[188:191], v171 offset:33792
	ds_read_b128 v[194:197], v171 offset:34816
	ds_read_b128 v[198:201], v171 offset:35840
	ds_read_b128 v[202:205], v171 offset:36864
	ds_read_b128 v[206:209], v171 offset:37888
	ds_read_b128 v[210:213], v171 offset:38912
	ds_read_b128 v[214:217], v171 offset:39936
	global_load_lds_dwordx4 v[224:225], off
	v_lshl_add_u64 v[224:225], s[50:51], 0, v[148:149]
	s_mov_b32 m0, s60
	s_nop 0
	global_load_lds_dwordx4 v[224:225], off
	s_waitcnt vmcnt(8)
	s_waitcnt lgkmcnt(0)
	s_barrier
	s_setprio 1
	s_waitcnt lgkmcnt(0)
	v_mfma_f32_16x16x32_bf16 v[140:143], v[120:123], v[184:187], v[140:143]
	v_mfma_f32_16x16x32_bf16 v[136:139], v[128:131], v[184:187], v[136:139]
	v_mfma_f32_16x16x32_bf16 v[112:115], v[120:123], v[194:197], v[112:115]
	v_mfma_f32_16x16x32_bf16 v[104:107], v[128:131], v[194:197], v[104:107]
	v_mfma_f32_16x16x32_bf16 v[96:99], v[120:123], v[202:205], v[96:99]
	v_mfma_f32_16x16x32_bf16 v[88:91], v[128:131], v[202:205], v[88:91]
	v_mfma_f32_16x16x32_bf16 v[80:83], v[120:123], v[210:213], v[80:83]
	v_mfma_f32_16x16x32_bf16 v[72:75], v[128:131], v[210:213], v[72:75]
	v_mfma_f32_16x16x32_bf16 v[140:143], v[124:127], v[188:191], v[140:143]
	v_mfma_f32_16x16x32_bf16 v[136:139], v[132:135], v[188:191], v[136:139]
	v_mfma_f32_16x16x32_bf16 v[112:115], v[124:127], v[198:201], v[112:115]
	v_mfma_f32_16x16x32_bf16 v[104:107], v[132:135], v[198:201], v[104:107]
	v_mfma_f32_16x16x32_bf16 v[96:99], v[124:127], v[206:209], v[96:99]
	v_mfma_f32_16x16x32_bf16 v[88:91], v[132:135], v[206:209], v[88:91]
	v_mfma_f32_16x16x32_bf16 v[80:83], v[124:127], v[214:217], v[80:83]
	v_mfma_f32_16x16x32_bf16 v[72:75], v[132:135], v[214:217], v[72:75]
	s_setprio 0
	s_setprio 1
	v_mfma_f32_16x16x32_bf16 v[116:119], v[160:163], v[184:187], v[116:119]
	v_mfma_f32_16x16x32_bf16 v[108:111], v[176:179], v[184:187], v[108:111]
	v_mfma_f32_16x16x32_bf16 v[100:103], v[160:163], v[194:197], v[100:103]
	v_mfma_f32_16x16x32_bf16 v[92:95], v[176:179], v[194:197], v[92:95]
	v_mfma_f32_16x16x32_bf16 v[84:87], v[160:163], v[202:205], v[84:87]
	v_mfma_f32_16x16x32_bf16 v[76:79], v[176:179], v[202:205], v[76:79]
	v_mfma_f32_16x16x32_bf16 v[68:71], v[160:163], v[210:213], v[68:71]
	v_mfma_f32_16x16x32_bf16 v[64:67], v[176:179], v[210:213], v[64:67]
	v_mfma_f32_16x16x32_bf16 v[116:119], v[172:175], v[188:191], v[116:119]
	v_mfma_f32_16x16x32_bf16 v[108:111], v[180:183], v[188:191], v[108:111]
	v_mfma_f32_16x16x32_bf16 v[100:103], v[172:175], v[198:201], v[100:103]
	v_mfma_f32_16x16x32_bf16 v[92:95], v[180:183], v[198:201], v[92:95]
	v_mfma_f32_16x16x32_bf16 v[84:87], v[172:175], v[206:209], v[84:87]
	v_mfma_f32_16x16x32_bf16 v[76:79], v[180:183], v[206:209], v[76:79]
	v_mfma_f32_16x16x32_bf16 v[68:71], v[172:175], v[214:217], v[68:71]
	v_mfma_f32_16x16x32_bf16 v[64:67], v[180:183], v[214:217], v[64:67]
	s_setprio 0
	s_barrier
; #define PG8_STAGE(bufoff, gbase, voff) do { _Pragma("unroll") for (int _i = 0; _i < 2; ++_i) \
;         __builtin_amdgcn_global_load_lds((const unsigned*)((const char*)(gbase) + (voff)[_i]), (PG8_LAS unsigned*)(lds + (bufoff) + ldsw + _i * 8192), 16, 0, 0); } while (0)
; #define PG8_LDA(dst, b, h) do { _Pragma("unroll") for (int m = 0; m < 4; ++m) _Pragma("unroll") for (int k = 0; k < 2; ++k) dst[m][k] = *(const PG8_LAS bf16x8*)(lds + PG8_SA(b, h) + aoff + m * 2048 + k * 1024); } while (0)
; #define PG8_MMA(ai, bj, At, Bt) do { __builtin_amdgcn_s_setprio(1); _Pragma("unroll") for (int m = 0; m < 4; ++m) _Pragma("unroll") for (int n = 0; n < 2; ++n) _Pragma("unroll") for (int k = 0; k < 2; ++k) \
;         acc[ai][bj][m][n] = __builtin_amdgcn_mfma_f32_16x16x32_bf16(Bt[n][k], At[m][k], acc[ai][bj][m][n], 0, 0, 0); __builtin_amdgcn_s_setprio(0); } while (0)
; #define PG8_WAIT_V(n) asm volatile("s_waitcnt vmcnt(" #n ")" ::: "memory")
; #define PG8_WAIT_L(n) asm volatile("s_waitcnt lgkmcnt(" #n ")" ::: "memory")
; #define PG8_BAR __builtin_amdgcn_s_barrier()
; #define PG8_SCHED __builtin_amdgcn_sched_barrier(0)
; template <class Epi, class Sched, bool ALIGN_EPI = false, bool SP2 = false>
; __device__ __forceinline__ void gemm_phase(PG8_LAS unsigned char* lds, const Gemm g, const Sched& S, const Epi& E) {
;     ...
;         for (int t = 0; t < nt; t += 2) {
;             const bool last = (t == nt - 2);
;     ...
;             PG8_LDA(At, 1, 1); PG8_STAGE(PG8_SB(1, 0), b3, voffB); PG8_STAGE(PG8_SB(1, 1), b3 + hstep, voffB); PG8_STAGE(PG8_SA(1, 0), a3, voffA);
;             PG8_WAIT_V(8); PG8_WAIT_L(0); PG8_BAR; PG8_MMA(1, 0, At, B0); PG8_MMA(1, 1, At, B1); PG8_BAR; PG8_SCHED;
	s_add_i32 s50, s78, s58
	v_lshl_add_u64 v[164:165], v[164:165], 0, s[14:15]
	s_mov_b32 m0, s50
	ds_read_b128 v[184:187], v171 offset:49152
	ds_read_b128 v[188:191], v171 offset:50176
	ds_read_b128 v[194:197], v171 offset:51200
	ds_read_b128 v[198:201], v171 offset:52224
	ds_read_b128 v[202:205], v171 offset:53248
	ds_read_b128 v[206:209], v171 offset:54272
	ds_read_b128 v[210:213], v171 offset:55296
	ds_read_b128 v[214:217], v171 offset:56320
	global_load_lds_dwordx4 v[164:165], off
	s_add_i32 m0, s50, 0x2000
	s_add_u32 s48, s48, 0x80080
	v_lshl_add_u64 v[164:165], v[218:219], 0, s[14:15]
	s_addc_u32 s49, s49, 0
	s_add_i32 s50, s79, s58
	global_load_lds_dwordx4 v[164:165], off
	v_lshl_add_u64 v[164:165], s[48:49], 0, v[146:147]
	s_mov_b32 m0, s50
	s_nop 0
	global_load_lds_dwordx4 v[164:165], off
	v_lshl_add_u64 v[164:165], s[48:49], 0, v[150:151]
	s_add_i32 m0, s50, 0x2000
	s_nop 0
	global_load_lds_dwordx4 v[164:165], off
	v_lshl_add_u64 v[164:165], v[220:221], 0, s[14:15]
	s_mov_b32 m0, s64
	s_nop 0
	global_load_lds_dwordx4 v[164:165], off
	v_lshl_add_u64 v[164:165], v[222:223], 0, s[14:15]
	s_mov_b32 m0, s65
	s_nop 0
	global_load_lds_dwordx4 v[164:165], off
	s_waitcnt vmcnt(8)
	s_waitcnt lgkmcnt(0)
	s_barrier
	s_setprio 1
	s_waitcnt lgkmcnt(0)
	v_mfma_f32_16x16x32_bf16 v[60:63], v[120:123], v[184:187], v[60:63]
	v_mfma_f32_16x16x32_bf16 v[56:59], v[128:131], v[184:187], v[56:59]
	v_mfma_f32_16x16x32_bf16 v[48:51], v[120:123], v[194:197], v[48:51]
	v_mfma_f32_16x16x32_bf16 v[40:43], v[128:131], v[194:197], v[40:43]
	v_mfma_f32_16x16x32_bf16 v[32:35], v[120:123], v[202:205], v[32:35]
	v_mfma_f32_16x16x32_bf16 v[24:27], v[128:131], v[202:205], v[24:27]
	v_mfma_f32_16x16x32_bf16 v[16:19], v[120:123], v[210:213], v[16:19]
	v_mfma_f32_16x16x32_bf16 v[8:11], v[128:131], v[210:213], v[8:11]
	v_mfma_f32_16x16x32_bf16 v[60:63], v[124:127], v[188:191], v[60:63]
	v_mfma_f32_16x16x32_bf16 v[56:59], v[132:135], v[188:191], v[56:59]
	v_mfma_f32_16x16x32_bf16 v[48:51], v[124:127], v[198:201], v[48:51]
	v_mfma_f32_16x16x32_bf16 v[40:43], v[132:135], v[198:201], v[40:43]
	v_mfma_f32_16x16x32_bf16 v[32:35], v[124:127], v[206:209], v[32:35]
	v_mfma_f32_16x16x32_bf16 v[24:27], v[132:135], v[206:209], v[24:27]
	v_mfma_f32_16x16x32_bf16 v[16:19], v[124:127], v[214:217], v[16:19]
	v_mfma_f32_16x16x32_bf16 v[8:11], v[132:135], v[214:217], v[8:11]
	s_setprio 0
	s_setprio 1
	v_mfma_f32_16x16x32_bf16 v[52:55], v[160:163], v[184:187], v[52:55]
	v_mfma_f32_16x16x32_bf16 v[44:47], v[176:179], v[184:187], v[44:47]
	v_mfma_f32_16x16x32_bf16 v[36:39], v[160:163], v[194:197], v[36:39]
	v_mfma_f32_16x16x32_bf16 v[28:31], v[176:179], v[194:197], v[28:31]
	v_mfma_f32_16x16x32_bf16 v[20:23], v[160:163], v[202:205], v[20:23]
	v_mfma_f32_16x16x32_bf16 v[12:15], v[176:179], v[202:205], v[12:15]
	v_mfma_f32_16x16x32_bf16 v[4:7], v[160:163], v[210:213], v[4:7]
	v_mfma_f32_16x16x32_bf16 v[0:3], v[176:179], v[210:213], v[0:3]
	v_mfma_f32_16x16x32_bf16 v[52:55], v[172:175], v[188:191], v[52:55]
	v_mfma_f32_16x16x32_bf16 v[44:47], v[180:183], v[188:191], v[44:47]
	v_mfma_f32_16x16x32_bf16 v[36:39], v[172:175], v[198:201], v[36:39]
	v_mfma_f32_16x16x32_bf16 v[28:31], v[180:183], v[198:201], v[28:31]
	v_mfma_f32_16x16x32_bf16 v[20:23], v[172:175], v[206:209], v[20:23]
	v_mfma_f32_16x16x32_bf16 v[12:15], v[180:183], v[206:209], v[12:15]
	v_mfma_f32_16x16x32_bf16 v[4:7], v[172:175], v[214:217], v[4:7]
	v_mfma_f32_16x16x32_bf16 v[0:3], v[180:183], v[214:217], v[0:3]
	s_setprio 0
	s_barrier
	s_add_i32 s77, s77, 2
	s_add_u32 s75, s75, 0x100
	s_addc_u32 s76, s76, 0
	s_add_u32 s46, s46, 0x100
	s_addc_u32 s47, s47, 0
	s_cmp_gt_u32 s77, 29
	s_cbranch_scc1 .Lpeel_exit_5
	.p2align	6

; #define PG8_STAGE(bufoff, gbase, voff) do { _Pragma("unroll") for (int _i = 0; _i < 2; ++_i) \
;         __builtin_amdgcn_global_load_lds((const unsigned*)((const char*)(gbase) + (voff)[_i]), (PG8_LAS unsigned*)(lds + (bufoff) + ldsw + _i * 8192), 16, 0, 0); } while (0)
; #define PG8_LDA(dst, b, h) do { _Pragma("unroll") for (int m = 0; m < 4; ++m) _Pragma("unroll") for (int k = 0; k < 2; ++k) dst[m][k] = *(const PG8_LAS bf16x8*)(lds + PG8_SA(b, h) + aoff + m * 2048 + k * 1024); } while (0)
; #define PG8_LDB(dst, b, h) do { _Pragma("unroll") for (int n = 0; n < 2; ++n) _Pragma("unroll") for (int k = 0; k < 2; ++k) dst[n][k] = *(const PG8_LAS bf16x8*)(lds + PG8_SB(b, h) + boff + n * 2048 + k * 1024); } while (0)
; #define PG8_MMA(ai, bj, At, Bt) do { __builtin_amdgcn_s_setprio(1); _Pragma("unroll") for (int m = 0; m < 4; ++m) _Pragma("unroll") for (int n = 0; n < 2; ++n) _Pragma("unroll") for (int k = 0; k < 2; ++k) \
;         acc[ai][bj][m][n] = __builtin_amdgcn_mfma_f32_16x16x32_bf16(Bt[n][k], At[m][k], acc[ai][bj][m][n], 0, 0, 0); __builtin_amdgcn_s_setprio(0); } while (0)
; #define PG8_WAIT_V(n) asm volatile("s_waitcnt vmcnt(" #n ")" ::: "memory")
; #define PG8_WAIT_L(n) asm volatile("s_waitcnt lgkmcnt(" #n ")" ::: "memory")
; template <class Epi, class Sched, bool ALIGN_EPI = false, bool SP2 = false>
; __device__ __forceinline__ void gemm_phase(PG8_LAS unsigned char* lds, const Gemm g, const Sched& S, const Epi& E) {
;     ...
;             const bool last = (t == nt - 2);
;             const char* a1 = cA + (size_t)(t + 1) * kstep;
;             const char* a2 = last ? nA : cA + (size_t)(t + 2) * kstep; const char* b2 = last ? nB : cB + (size_t)(t + 2) * kstep;
;             const char* a3 = a2 + kstep; const char* b3 = b2 + kstep;
;             if (last && has_next) S.a_ready(nxt);
;             if constexpr (SP2) {
;             PG8_LDB(B0, 0, 0); PG8_LDB(B1, 0, 1); PG8_SCHED; PG8_LDA(At, 0, 0); PG8_STAGE(PG8_SA(1, 1), a1 + hstep, voffA);
;             PG8_WAIT_V(8); PG8_WAIT_L(0); PG8_BAR; PG8_MMA(0, 0, At, B0); PG8_MMA(0, 1, At, B1); PG8_BAR; PG8_SCHED;
;             PG8_LDA(At, 0, 1); PG8_STAGE(PG8_SB(0, 0), b2, voffB); PG8_STAGE(PG8_SB(0, 1), b2 + hstep, voffB); PG8_STAGE(PG8_SA(0, 0), a2, voffA);
;             PG8_WAIT_V(8); PG8_WAIT_L(0); PG8_BAR; PG8_MMA(1, 0, At, B0); PG8_MMA(1, 1, At, B1); PG8_BAR; PG8_SCHED;
.LBB0_1169:
	s_ashr_i32 s17, s16, 31
	s_lshl_b64 s[20:21], s[16:17], 20
	s_add_u32 s20, s37, s20
	s_addc_u32 s21, s46, s21
	s_and_b64 s[22:23], s[6:7], exec
	s_cselect_b32 s17, s21, s31
	s_cselect_b32 s61, s20, s30
	s_ashr_i32 s19, s18, 31
	s_lshl_b64 s[22:23], s[18:19], 20
	s_add_u32 s22, s47, s22
	s_addc_u32 s23, s48, s23
	s_and_b64 s[34:35], s[6:7], exec
	s_cselect_b32 s19, s23, s29
	s_cselect_b32 s62, s22, s28
	s_add_u32 s63, s28, 0x100
	s_addc_u32 s64, s29, 0
	s_add_u32 s28, s30, 0x80080
	s_addc_u32 s29, s31, 0
	s_mov_b32 s65, -2
	ds_read_b128 v[144:147], v151
	ds_read_b128 v[154:157], v151 offset:1024
	ds_read_b128 v[158:161], v151 offset:2048
	ds_read_b128 v[162:165], v151 offset:3072
	ds_read_b128 v[166:169], v152
	ds_read_b128 v[170:173], v152 offset:1024
	ds_read_b128 v[174:177], v152 offset:2048
	ds_read_b128 v[178:181], v152 offset:3072
	s_add_u32 s30, s28, 0xfff80080
	s_addc_u32 s31, s29, -1
	s_cmp_eq_u32 s65, 28
	s_cselect_b32 s35, s17, s31
	s_cselect_b32 s34, s61, s30
	s_cselect_b32 s31, s19, s64
	s_cselect_b32 s30, s62, s63
	v_lshl_add_u64 v[190:191], s[28:29], 0, v[138:139]
	s_add_i32 m0, s25, 0xc000
	ds_read_b128 v[182:185], v153
	ds_read_b128 v[186:189], v153 offset:1024
	ds_read_b128 v[194:197], v153 offset:2048
	ds_read_b128 v[198:201], v153 offset:3072
	ds_read_b128 v[202:205], v153 offset:4096
	ds_read_b128 v[206:209], v153 offset:5120
	ds_read_b128 v[210:213], v153 offset:6144
	ds_read_b128 v[214:217], v153 offset:7168
	global_load_lds_dwordx4 v[190:191], off
	v_lshl_add_u64 v[190:191], s[28:29], 0, v[136:137]
	s_add_i32 m0, s25, 0xe000
	s_nop 0
	global_load_lds_dwordx4 v[190:191], off
	s_waitcnt vmcnt(8)
	s_waitcnt lgkmcnt(0)
	s_barrier
	s_setprio 1
	s_waitcnt lgkmcnt(0)
	v_mfma_f32_16x16x32_bf16 v[124:127], v[144:147], v[182:185], 0
	v_mfma_f32_16x16x32_bf16 v[120:123], v[158:161], v[182:185], 0
	v_mfma_f32_16x16x32_bf16 v[108:111], v[144:147], v[194:197], 0
	v_mfma_f32_16x16x32_bf16 v[104:107], v[158:161], v[194:197], 0
	v_mfma_f32_16x16x32_bf16 v[92:95], v[144:147], v[202:205], 0
	v_mfma_f32_16x16x32_bf16 v[88:91], v[158:161], v[202:205], 0
	v_mfma_f32_16x16x32_bf16 v[76:79], v[144:147], v[210:213], 0
	v_mfma_f32_16x16x32_bf16 v[72:75], v[158:161], v[210:213], 0
	v_mfma_f32_16x16x32_bf16 v[124:127], v[154:157], v[186:189], v[124:127]
	v_mfma_f32_16x16x32_bf16 v[120:123], v[162:165], v[186:189], v[120:123]
	v_mfma_f32_16x16x32_bf16 v[108:111], v[154:157], v[198:201], v[108:111]
	v_mfma_f32_16x16x32_bf16 v[104:107], v[162:165], v[198:201], v[104:107]
	v_mfma_f32_16x16x32_bf16 v[92:95], v[154:157], v[206:209], v[92:95]
	v_mfma_f32_16x16x32_bf16 v[88:91], v[162:165], v[206:209], v[88:91]
	v_mfma_f32_16x16x32_bf16 v[76:79], v[154:157], v[214:217], v[76:79]
	v_mfma_f32_16x16x32_bf16 v[72:75], v[162:165], v[214:217], v[72:75]
	s_setprio 0
	s_setprio 1
	v_mfma_f32_16x16x32_bf16 v[116:119], v[166:169], v[182:185], 0
	v_mfma_f32_16x16x32_bf16 v[112:115], v[174:177], v[182:185], 0
	v_mfma_f32_16x16x32_bf16 v[100:103], v[166:169], v[194:197], 0
	v_mfma_f32_16x16x32_bf16 v[96:99], v[174:177], v[194:197], 0
	v_mfma_f32_16x16x32_bf16 v[84:87], v[166:169], v[202:205], 0
	v_mfma_f32_16x16x32_bf16 v[80:83], v[174:177], v[202:205], 0
	v_mfma_f32_16x16x32_bf16 v[68:71], v[166:169], v[210:213], 0
	v_mfma_f32_16x16x32_bf16 v[64:67], v[174:177], v[210:213], 0
	v_mfma_f32_16x16x32_bf16 v[116:119], v[170:173], v[186:189], v[116:119]
	v_mfma_f32_16x16x32_bf16 v[112:115], v[178:181], v[186:189], v[112:115]
	v_mfma_f32_16x16x32_bf16 v[100:103], v[170:173], v[198:201], v[100:103]
	v_mfma_f32_16x16x32_bf16 v[96:99], v[178:181], v[198:201], v[96:99]
	v_mfma_f32_16x16x32_bf16 v[84:87], v[170:173], v[206:209], v[84:87]
	v_mfma_f32_16x16x32_bf16 v[80:83], v[178:181], v[206:209], v[80:83]
	v_mfma_f32_16x16x32_bf16 v[68:71], v[170:173], v[214:217], v[68:71]
	v_mfma_f32_16x16x32_bf16 v[64:67], v[178:181], v[214:217], v[64:67]
	s_setprio 0
	s_barrier
	s_add_i32 s66, s58, s49
	v_lshl_add_u64 v[190:191], s[30:31], 0, v[132:133]
	s_mov_b32 m0, s66
	ds_read_b128 v[182:185], v153 offset:16384
	ds_read_b128 v[186:189], v153 offset:17408
	ds_read_b128 v[194:197], v153 offset:18432
	ds_read_b128 v[198:201], v153 offset:19456
	ds_read_b128 v[202:205], v153 offset:20480
	ds_read_b128 v[206:209], v153 offset:21504
	ds_read_b128 v[210:213], v153 offset:22528
	ds_read_b128 v[214:217], v153 offset:23552
	global_load_lds_dwordx4 v[190:191], off
	s_add_i32 m0, s66, 0x2000
	s_add_u32 s66, s30, 0x80000
	v_lshl_add_u64 v[218:219], s[30:31], 0, v[128:129]
	s_addc_u32 s67, s31, 0
	s_add_i32 s68, s59, s49
	global_load_lds_dwordx4 v[218:219], off
	v_lshl_add_u64 v[220:221], s[66:67], 0, v[132:133]
	s_mov_b32 m0, s68
	v_lshl_add_u64 v[222:223], s[34:35], 0, v[130:131]
	global_load_lds_dwordx4 v[220:221], off
	v_lshl_add_u64 v[220:221], s[66:67], 0, v[128:129]
	s_add_i32 m0, s68, 0x2000
	s_nop 0
	global_load_lds_dwordx4 v[220:221], off
	v_lshl_add_u64 v[220:221], s[34:35], 0, v[134:135]
	s_mov_b32 m0, s25
	s_nop 0
	global_load_lds_dwordx4 v[220:221], off
	s_mov_b32 m0, s27
	s_nop 0
	global_load_lds_dwordx4 v[222:223], off
	s_waitcnt vmcnt(8)
	s_waitcnt lgkmcnt(0)
	s_barrier
; #define PG8_STAGE(bufoff, gbase, voff) do { _Pragma("unroll") for (int _i = 0; _i < 2; ++_i) \
;         __builtin_amdgcn_global_load_lds((const unsigned*)((const char*)(gbase) + (voff)[_i]), (PG8_LAS unsigned*)(lds + (bufoff) + ldsw + _i * 8192), 16, 0, 0); } while (0)
; #define PG8_LDA(dst, b, h) do { _Pragma("unroll") for (int m = 0; m < 4; ++m) _Pragma("unroll") for (int k = 0; k < 2; ++k) dst[m][k] = *(const PG8_LAS bf16x8*)(lds + PG8_SA(b, h) + aoff + m * 2048 + k * 1024); } while (0)
; #define PG8_LDB(dst, b, h) do { _Pragma("unroll") for (int n = 0; n < 2; ++n) _Pragma("unroll") for (int k = 0; k < 2; ++k) dst[n][k] = *(const PG8_LAS bf16x8*)(lds + PG8_SB(b, h) + boff + n * 2048 + k * 1024); } while (0)
; #define PG8_MMA(ai, bj, At, Bt) do { __builtin_amdgcn_s_setprio(1); _Pragma("unroll") for (int m = 0; m < 4; ++m) _Pragma("unroll") for (int n = 0; n < 2; ++n) _Pragma("unroll") for (int k = 0; k < 2; ++k) \
;         acc[ai][bj][m][n] = __builtin_amdgcn_mfma_f32_16x16x32_bf16(Bt[n][k], At[m][k], acc[ai][bj][m][n], 0, 0, 0); __builtin_amdgcn_s_setprio(0); } while (0)
; #define PG8_WAIT_V(n) asm volatile("s_waitcnt vmcnt(" #n ")" ::: "memory")
; #define PG8_WAIT_L(n) asm volatile("s_waitcnt lgkmcnt(" #n ")" ::: "memory")
; #define PG8_BAR __builtin_amdgcn_s_barrier()
; #define PG8_SCHED __builtin_amdgcn_sched_barrier(0)
; template <class Epi, class Sched, bool ALIGN_EPI = false, bool SP2 = false>
; __device__ __forceinline__ void gemm_phase(PG8_LAS unsigned char* lds, const Gemm g, const Sched& S, const Epi& E) {
;     ...
;             PG8_WAIT_V(8); PG8_WAIT_L(0); PG8_BAR; PG8_MMA(1, 0, At, B0); PG8_MMA(1, 1, At, B1); PG8_BAR; PG8_SCHED;
;             PG8_LDB(B0, 1, 0); PG8_LDB(B1, 1, 1); PG8_SCHED; PG8_LDA(At, 1, 0); PG8_STAGE(PG8_SA(0, 1), a2 + hstep, voffA);
;             PG8_WAIT_V(8); PG8_WAIT_L(0); PG8_BAR; PG8_MMA(0, 0, At, B0); PG8_MMA(0, 1, At, B1); PG8_BAR; PG8_SCHED;
	s_setprio 1
	s_waitcnt lgkmcnt(0)
	v_mfma_f32_16x16x32_bf16 v[60:63], v[144:147], v[182:185], 0
	v_mfma_f32_16x16x32_bf16 v[56:59], v[158:161], v[182:185], 0
	v_mfma_f32_16x16x32_bf16 v[44:47], v[144:147], v[194:197], 0
	v_mfma_f32_16x16x32_bf16 v[40:43], v[158:161], v[194:197], 0
	v_mfma_f32_16x16x32_bf16 v[28:31], v[144:147], v[202:205], 0
	v_mfma_f32_16x16x32_bf16 v[24:27], v[158:161], v[202:205], 0
	v_mfma_f32_16x16x32_bf16 v[12:15], v[144:147], v[210:213], 0
	v_mfma_f32_16x16x32_bf16 v[8:11], v[158:161], v[210:213], 0
	v_mfma_f32_16x16x32_bf16 v[60:63], v[154:157], v[186:189], v[60:63]
	v_mfma_f32_16x16x32_bf16 v[56:59], v[162:165], v[186:189], v[56:59]
	v_mfma_f32_16x16x32_bf16 v[44:47], v[154:157], v[198:201], v[44:47]
	v_mfma_f32_16x16x32_bf16 v[40:43], v[162:165], v[198:201], v[40:43]
	v_mfma_f32_16x16x32_bf16 v[28:31], v[154:157], v[206:209], v[28:31]
	v_mfma_f32_16x16x32_bf16 v[24:27], v[162:165], v[206:209], v[24:27]
	v_mfma_f32_16x16x32_bf16 v[12:15], v[154:157], v[214:217], v[12:15]
	v_mfma_f32_16x16x32_bf16 v[8:11], v[162:165], v[214:217], v[8:11]
	s_setprio 0
	s_setprio 1
	v_mfma_f32_16x16x32_bf16 v[52:55], v[166:169], v[182:185], 0
	v_mfma_f32_16x16x32_bf16 v[48:51], v[174:177], v[182:185], 0
	v_mfma_f32_16x16x32_bf16 v[36:39], v[166:169], v[194:197], 0
	v_mfma_f32_16x16x32_bf16 v[32:35], v[174:177], v[194:197], 0
	v_mfma_f32_16x16x32_bf16 v[20:23], v[166:169], v[202:205], 0
	v_mfma_f32_16x16x32_bf16 v[16:19], v[174:177], v[202:205], 0
	v_mfma_f32_16x16x32_bf16 v[4:7], v[166:169], v[210:213], 0
	v_mfma_f32_16x16x32_bf16 v[0:3], v[174:177], v[210:213], 0
	v_mfma_f32_16x16x32_bf16 v[52:55], v[170:173], v[186:189], v[52:55]
	v_mfma_f32_16x16x32_bf16 v[48:51], v[178:181], v[186:189], v[48:51]
	v_mfma_f32_16x16x32_bf16 v[36:39], v[170:173], v[198:201], v[36:39]
	v_mfma_f32_16x16x32_bf16 v[32:35], v[178:181], v[198:201], v[32:35]
	v_mfma_f32_16x16x32_bf16 v[20:23], v[170:173], v[206:209], v[20:23]
	v_mfma_f32_16x16x32_bf16 v[16:19], v[178:181], v[206:209], v[16:19]
	v_mfma_f32_16x16x32_bf16 v[4:7], v[170:173], v[214:217], v[4:7]
	v_mfma_f32_16x16x32_bf16 v[0:3], v[178:181], v[214:217], v[0:3]
	s_setprio 0
	s_barrier
	s_add_i32 s66, 0, 0x18000
	s_add_i32 s67, 0, 0x1c000
	v_add_u32_e32 v162, s66, v149
	v_add_u32_e32 v178, s67, v149
	ds_read_b128 v[144:147], v162
	ds_read_b128 v[154:157], v162 offset:1024
	ds_read_b128 v[158:161], v162 offset:2048
	ds_read_b128 v[162:165], v162 offset:3072
	ds_read_b128 v[166:169], v178
	ds_read_b128 v[170:173], v178 offset:1024
	ds_read_b128 v[174:177], v178 offset:2048
	ds_read_b128 v[178:181], v178 offset:3072
	s_add_u32 s34, s34, 0x80000
	s_addc_u32 s35, s35, 0
	s_mov_b32 m0, s52
	v_lshl_add_u64 v[224:225], s[34:35], 0, v[134:135]
	ds_read_b128 v[182:185], v153 offset:32768
	ds_read_b128 v[186:189], v153 offset:33792
	ds_read_b128 v[194:197], v153 offset:34816
	ds_read_b128 v[198:201], v153 offset:35840
	ds_read_b128 v[202:205], v153 offset:36864
	ds_read_b128 v[206:209], v153 offset:37888
	ds_read_b128 v[210:213], v153 offset:38912
	ds_read_b128 v[214:217], v153 offset:39936
	global_load_lds_dwordx4 v[224:225], off
	v_lshl_add_u64 v[224:225], s[34:35], 0, v[130:131]
	s_mov_b32 m0, s53
	s_nop 0
	global_load_lds_dwordx4 v[224:225], off
	s_waitcnt vmcnt(8)
	s_waitcnt lgkmcnt(0)
	s_barrier
	s_setprio 1
	s_waitcnt lgkmcnt(0)
	v_mfma_f32_16x16x32_bf16 v[124:127], v[144:147], v[182:185], v[124:127]
	v_mfma_f32_16x16x32_bf16 v[120:123], v[158:161], v[182:185], v[120:123]
	v_mfma_f32_16x16x32_bf16 v[108:111], v[144:147], v[194:197], v[108:111]
	v_mfma_f32_16x16x32_bf16 v[104:107], v[158:161], v[194:197], v[104:107]
	v_mfma_f32_16x16x32_bf16 v[92:95], v[144:147], v[202:205], v[92:95]
	v_mfma_f32_16x16x32_bf16 v[88:91], v[158:161], v[202:205], v[88:91]
	v_mfma_f32_16x16x32_bf16 v[76:79], v[144:147], v[210:213], v[76:79]
	v_mfma_f32_16x16x32_bf16 v[72:75], v[158:161], v[210:213], v[72:75]
	v_mfma_f32_16x16x32_bf16 v[124:127], v[154:157], v[186:189], v[124:127]
	v_mfma_f32_16x16x32_bf16 v[120:123], v[162:165], v[186:189], v[120:123]
	v_mfma_f32_16x16x32_bf16 v[108:111], v[154:157], v[198:201], v[108:111]
	v_mfma_f32_16x16x32_bf16 v[104:107], v[162:165], v[198:201], v[104:107]
	v_mfma_f32_16x16x32_bf16 v[92:95], v[154:157], v[206:209], v[92:95]
	v_mfma_f32_16x16x32_bf16 v[88:91], v[162:165], v[206:209], v[88:91]
	v_mfma_f32_16x16x32_bf16 v[76:79], v[154:157], v[214:217], v[76:79]
	v_mfma_f32_16x16x32_bf16 v[72:75], v[162:165], v[214:217], v[72:75]
	s_setprio 0
	s_setprio 1
	v_mfma_f32_16x16x32_bf16 v[116:119], v[166:169], v[182:185], v[116:119]
	v_mfma_f32_16x16x32_bf16 v[112:115], v[174:177], v[182:185], v[112:115]
	v_mfma_f32_16x16x32_bf16 v[100:103], v[166:169], v[194:197], v[100:103]
	v_mfma_f32_16x16x32_bf16 v[96:99], v[174:177], v[194:197], v[96:99]
	v_mfma_f32_16x16x32_bf16 v[84:87], v[166:169], v[202:205], v[84:87]
	v_mfma_f32_16x16x32_bf16 v[80:83], v[174:177], v[202:205], v[80:83]
	v_mfma_f32_16x16x32_bf16 v[68:71], v[166:169], v[210:213], v[68:71]
	v_mfma_f32_16x16x32_bf16 v[64:67], v[174:177], v[210:213], v[64:67]
	v_mfma_f32_16x16x32_bf16 v[116:119], v[170:173], v[186:189], v[116:119]
	v_mfma_f32_16x16x32_bf16 v[112:115], v[178:181], v[186:189], v[112:115]
	v_mfma_f32_16x16x32_bf16 v[100:103], v[170:173], v[198:201], v[100:103]
	v_mfma_f32_16x16x32_bf16 v[96:99], v[178:181], v[198:201], v[96:99]
	v_mfma_f32_16x16x32_bf16 v[84:87], v[170:173], v[206:209], v[84:87]
	v_mfma_f32_16x16x32_bf16 v[80:83], v[178:181], v[206:209], v[80:83]
	v_mfma_f32_16x16x32_bf16 v[68:71], v[170:173], v[214:217], v[68:71]
	v_mfma_f32_16x16x32_bf16 v[64:67], v[178:181], v[214:217], v[64:67]
	s_setprio 0
	s_barrier
; #define PG8_STAGE(bufoff, gbase, voff) do { _Pragma("unroll") for (int _i = 0; _i < 2; ++_i) \
;         __builtin_amdgcn_global_load_lds((const unsigned*)((const char*)(gbase) + (voff)[_i]), (PG8_LAS unsigned*)(lds + (bufoff) + ldsw + _i * 8192), 16, 0, 0); } while (0)
; #define PG8_LDA(dst, b, h) do { _Pragma("unroll") for (int m = 0; m < 4; ++m) _Pragma("unroll") for (int k = 0; k < 2; ++k) dst[m][k] = *(const PG8_LAS bf16x8*)(lds + PG8_SA(b, h) + aoff + m * 2048 + k * 1024); } while (0)
; #define PG8_MMA(ai, bj, At, Bt) do { __builtin_amdgcn_s_setprio(1); _Pragma("unroll") for (int m = 0; m < 4; ++m) _Pragma("unroll") for (int n = 0; n < 2; ++n) _Pragma("unroll") for (int k = 0; k < 2; ++k) \
;         acc[ai][bj][m][n] = __builtin_amdgcn_mfma_f32_16x16x32_bf16(Bt[n][k], At[m][k], acc[ai][bj][m][n], 0, 0, 0); __builtin_amdgcn_s_setprio(0); } while (0)
; #define PG8_WAIT_V(n) asm volatile("s_waitcnt vmcnt(" #n ")" ::: "memory")
; #define PG8_WAIT_L(n) asm volatile("s_waitcnt lgkmcnt(" #n ")" ::: "memory")
; #define PG8_BAR __builtin_amdgcn_s_barrier()
; #define PG8_SCHED __builtin_amdgcn_sched_barrier(0)
; template <class Epi, class Sched, bool ALIGN_EPI = false, bool SP2 = false>
; __device__ __forceinline__ void gemm_phase(PG8_LAS unsigned char* lds, const Gemm g, const Sched& S, const Epi& E) {
;     ...
;         for (int t = 0; t < nt; t += 2) {
;             const bool last = (t == nt - 2);
;     ...
;             PG8_LDA(At, 1, 1); PG8_STAGE(PG8_SB(1, 0), b3, voffB); PG8_STAGE(PG8_SB(1, 1), b3 + hstep, voffB); PG8_STAGE(PG8_SA(1, 0), a3, voffA);
;             PG8_WAIT_V(8); PG8_WAIT_L(0); PG8_BAR; PG8_MMA(1, 0, At, B0); PG8_MMA(1, 1, At, B1); PG8_BAR; PG8_SCHED;
	s_add_i32 s34, s66, s49
	v_lshl_add_u64 v[190:191], v[190:191], 0, s[12:13]
	s_mov_b32 m0, s34
	ds_read_b128 v[182:185], v153 offset:49152
	ds_read_b128 v[186:189], v153 offset:50176
	ds_read_b128 v[194:197], v153 offset:51200
	ds_read_b128 v[198:201], v153 offset:52224
	ds_read_b128 v[202:205], v153 offset:53248
	ds_read_b128 v[206:209], v153 offset:54272
	ds_read_b128 v[210:213], v153 offset:55296
	ds_read_b128 v[214:217], v153 offset:56320
	global_load_lds_dwordx4 v[190:191], off
	s_add_i32 m0, s34, 0x2000
	s_add_u32 s30, s30, 0x80080
	v_lshl_add_u64 v[190:191], v[218:219], 0, s[12:13]
	s_addc_u32 s31, s31, 0
	s_add_i32 s34, s67, s49
	global_load_lds_dwordx4 v[190:191], off
	v_lshl_add_u64 v[190:191], s[30:31], 0, v[132:133]
	s_mov_b32 m0, s34
	s_nop 0
	global_load_lds_dwordx4 v[190:191], off
	v_lshl_add_u64 v[190:191], s[30:31], 0, v[128:129]
	s_add_i32 m0, s34, 0x2000
	s_nop 0
	global_load_lds_dwordx4 v[190:191], off
	v_lshl_add_u64 v[190:191], v[220:221], 0, s[12:13]
	s_mov_b32 m0, s55
	s_nop 0
	global_load_lds_dwordx4 v[190:191], off
	v_lshl_add_u64 v[190:191], v[222:223], 0, s[12:13]
	s_mov_b32 m0, s56
	s_nop 0
	global_load_lds_dwordx4 v[190:191], off
	s_waitcnt vmcnt(8)
	s_waitcnt lgkmcnt(0)
	s_barrier
	s_setprio 1
	s_waitcnt lgkmcnt(0)
	v_mfma_f32_16x16x32_bf16 v[60:63], v[144:147], v[182:185], v[60:63]
	v_mfma_f32_16x16x32_bf16 v[56:59], v[158:161], v[182:185], v[56:59]
	v_mfma_f32_16x16x32_bf16 v[44:47], v[144:147], v[194:197], v[44:47]
	v_mfma_f32_16x16x32_bf16 v[40:43], v[158:161], v[194:197], v[40:43]
	v_mfma_f32_16x16x32_bf16 v[28:31], v[144:147], v[202:205], v[28:31]
	v_mfma_f32_16x16x32_bf16 v[24:27], v[158:161], v[202:205], v[24:27]
	v_mfma_f32_16x16x32_bf16 v[12:15], v[144:147], v[210:213], v[12:15]
	v_mfma_f32_16x16x32_bf16 v[8:11], v[158:161], v[210:213], v[8:11]
	v_mfma_f32_16x16x32_bf16 v[60:63], v[154:157], v[186:189], v[60:63]
	v_mfma_f32_16x16x32_bf16 v[56:59], v[162:165], v[186:189], v[56:59]
	v_mfma_f32_16x16x32_bf16 v[44:47], v[154:157], v[198:201], v[44:47]
	v_mfma_f32_16x16x32_bf16 v[40:43], v[162:165], v[198:201], v[40:43]
	v_mfma_f32_16x16x32_bf16 v[28:31], v[154:157], v[206:209], v[28:31]
	v_mfma_f32_16x16x32_bf16 v[24:27], v[162:165], v[206:209], v[24:27]
	v_mfma_f32_16x16x32_bf16 v[12:15], v[154:157], v[214:217], v[12:15]
	v_mfma_f32_16x16x32_bf16 v[8:11], v[162:165], v[214:217], v[8:11]
	s_setprio 0
	s_setprio 1
	v_mfma_f32_16x16x32_bf16 v[52:55], v[166:169], v[182:185], v[52:55]
	v_mfma_f32_16x16x32_bf16 v[48:51], v[174:177], v[182:185], v[48:51]
	v_mfma_f32_16x16x32_bf16 v[36:39], v[166:169], v[194:197], v[36:39]
	v_mfma_f32_16x16x32_bf16 v[32:35], v[174:177], v[194:197], v[32:35]
	v_mfma_f32_16x16x32_bf16 v[20:23], v[166:169], v[202:205], v[20:23]
	v_mfma_f32_16x16x32_bf16 v[16:19], v[174:177], v[202:205], v[16:19]
	v_mfma_f32_16x16x32_bf16 v[4:7], v[166:169], v[210:213], v[4:7]
	v_mfma_f32_16x16x32_bf16 v[0:3], v[174:177], v[210:213], v[0:3]
	v_mfma_f32_16x16x32_bf16 v[52:55], v[170:173], v[186:189], v[52:55]
	v_mfma_f32_16x16x32_bf16 v[48:51], v[178:181], v[186:189], v[48:51]
	v_mfma_f32_16x16x32_bf16 v[36:39], v[170:173], v[198:201], v[36:39]
	v_mfma_f32_16x16x32_bf16 v[32:35], v[178:181], v[198:201], v[32:35]
	v_mfma_f32_16x16x32_bf16 v[20:23], v[170:173], v[206:209], v[20:23]
	v_mfma_f32_16x16x32_bf16 v[16:19], v[178:181], v[206:209], v[16:19]
	v_mfma_f32_16x16x32_bf16 v[4:7], v[170:173], v[214:217], v[4:7]
	v_mfma_f32_16x16x32_bf16 v[0:3], v[178:181], v[214:217], v[0:3]
	s_setprio 0
	s_barrier
	s_add_i32 s65, s65, 2
	s_add_u32 s63, s63, 0x100
	s_addc_u32 s64, s64, 0
	s_add_u32 s28, s28, 0x100
	s_addc_u32 s29, s29, 0
	s_cmp_gt_u32 s65, 29
	s_cbranch_scc1 .Lpeel_exit_6
	.p2align	6

; #define PG8_STAGE(bufoff, gbase, voff) do { _Pragma("unroll") for (int _i = 0; _i < 2; ++_i) \
;         __builtin_amdgcn_global_load_lds((const unsigned*)((const char*)(gbase) + (voff)[_i]), (PG8_LAS unsigned*)(lds + (bufoff) + ldsw + _i * 8192), 16, 0, 0); } while (0)
; #define PG8_LDA(dst, b, h) do { _Pragma("unroll") for (int m = 0; m < 4; ++m) _Pragma("unroll") for (int k = 0; k < 2; ++k) dst[m][k] = *(const PG8_LAS bf16x8*)(lds + PG8_SA(b, h) + aoff + m * 2048 + k * 1024); } while (0)
; #define PG8_LDB(dst, b, h) do { _Pragma("unroll") for (int n = 0; n < 2; ++n) _Pragma("unroll") for (int k = 0; k < 2; ++k) dst[n][k] = *(const PG8_LAS bf16x8*)(lds + PG8_SB(b, h) + boff + n * 2048 + k * 1024); } while (0)
; #define PG8_MMA(ai, bj, At, Bt) do { __builtin_amdgcn_s_setprio(1); _Pragma("unroll") for (int m = 0; m < 4; ++m) _Pragma("unroll") for (int n = 0; n < 2; ++n) _Pragma("unroll") for (int k = 0; k < 2; ++k) \
;         acc[ai][bj][m][n] = __builtin_amdgcn_mfma_f32_16x16x32_bf16(Bt[n][k], At[m][k], acc[ai][bj][m][n], 0, 0, 0); __builtin_amdgcn_s_setprio(0); } while (0)
; #define PG8_WAIT_V(n) asm volatile("s_waitcnt vmcnt(" #n ")" ::: "memory")
; #define PG8_WAIT_L(n) asm volatile("s_waitcnt lgkmcnt(" #n ")" ::: "memory")
; #define PG8_BAR __builtin_amdgcn_s_barrier()
; #define PG8_SCHED __builtin_amdgcn_sched_barrier(0)
; template <class Epi, class Sched, bool ALIGN_EPI = false, bool SP2 = false>
; __device__ __forceinline__ void gemm_phase(PG8_LAS unsigned char* lds, const Gemm g, const Sched& S, const Epi& E) {
;     ...
;             const char* a2 = last ? nA : cA + (size_t)(t + 2) * kstep; const char* b2 = last ? nB : cB + (size_t)(t + 2) * kstep;
;             const char* a3 = a2 + kstep; const char* b3 = b2 + kstep;
;             if (last && has_next) S.a_ready(nxt);
;             if constexpr (SP2) {
;             PG8_LDB(B0, 0, 0); PG8_LDB(B1, 0, 1); PG8_SCHED; PG8_LDA(At, 0, 0); PG8_STAGE(PG8_SA(1, 1), a1 + hstep, voffA);
;             PG8_WAIT_V(8); PG8_WAIT_L(0); PG8_BAR; PG8_MMA(0, 0, At, B0); PG8_MMA(0, 1, At, B1); PG8_BAR; PG8_SCHED;
;             PG8_LDA(At, 0, 1); PG8_STAGE(PG8_SB(0, 0), b2, voffB); PG8_STAGE(PG8_SB(0, 1), b2 + hstep, voffB); PG8_STAGE(PG8_SA(0, 0), a2, voffA);
;             PG8_WAIT_V(8); PG8_WAIT_L(0); PG8_BAR; PG8_MMA(1, 0, At, B0); PG8_MMA(1, 1, At, B1); PG8_BAR; PG8_SCHED;
.LBB0_1249:
	s_add_u32 s71, s34, 0x100
	s_addc_u32 s72, s35, 0
	s_mov_b32 s73, -2
	ds_read_b128 v[124:127], v169
	ds_read_b128 v[132:135], v169 offset:1024
	ds_read_b128 v[136:139], v169 offset:2048
	ds_read_b128 v[140:143], v169 offset:3072
	ds_read_b128 v[160:163], v170
	ds_read_b128 v[172:175], v170 offset:1024
	ds_read_b128 v[176:179], v170 offset:2048
	ds_read_b128 v[180:183], v170 offset:3072
	s_add_u32 s34, s30, 0x100
	s_addc_u32 s35, s31, 0
	s_cmpk_eq_i32 s73, 0x54
	s_cselect_b32 s47, s9, s35
	s_cselect_b32 s46, s8, s34
	s_cselect_b32 s37, s29, s72
	s_cselect_b32 s36, s28, s71
	v_lshl_add_u64 v[164:165], s[30:31], 0, v[154:155]
	s_add_i32 m0, s55, 0xc000
	ds_read_b128 v[184:187], v171
	ds_read_b128 v[188:191], v171 offset:1024
	ds_read_b128 v[194:197], v171 offset:2048
	ds_read_b128 v[198:201], v171 offset:3072
	ds_read_b128 v[202:205], v171 offset:4096
	ds_read_b128 v[206:209], v171 offset:5120
	ds_read_b128 v[210:213], v171 offset:6144
	ds_read_b128 v[214:217], v171 offset:7168
	global_load_lds_dwordx4 v[164:165], off
	v_lshl_add_u64 v[164:165], s[30:31], 0, v[152:153]
	s_add_i32 m0, s55, 0xe000
	s_nop 0
	global_load_lds_dwordx4 v[164:165], off
	s_waitcnt vmcnt(8)
	s_waitcnt lgkmcnt(0)
	s_barrier
	s_setprio 1
	s_waitcnt lgkmcnt(0)
	v_mfma_f32_16x16x32_bf16 v[128:131], v[124:127], v[184:187], 0
	v_mfma_f32_16x16x32_bf16 v[120:123], v[136:139], v[184:187], 0
	v_mfma_f32_16x16x32_bf16 v[108:111], v[124:127], v[194:197], 0
	v_mfma_f32_16x16x32_bf16 v[104:107], v[136:139], v[194:197], 0
	v_mfma_f32_16x16x32_bf16 v[92:95], v[124:127], v[202:205], 0
	v_mfma_f32_16x16x32_bf16 v[88:91], v[136:139], v[202:205], 0
	v_mfma_f32_16x16x32_bf16 v[76:79], v[124:127], v[210:213], 0
	v_mfma_f32_16x16x32_bf16 v[72:75], v[136:139], v[210:213], 0
	v_mfma_f32_16x16x32_bf16 v[128:131], v[132:135], v[188:191], v[128:131]
	v_mfma_f32_16x16x32_bf16 v[120:123], v[140:143], v[188:191], v[120:123]
	v_mfma_f32_16x16x32_bf16 v[108:111], v[132:135], v[198:201], v[108:111]
	v_mfma_f32_16x16x32_bf16 v[104:107], v[140:143], v[198:201], v[104:107]
	v_mfma_f32_16x16x32_bf16 v[92:95], v[132:135], v[206:209], v[92:95]
	v_mfma_f32_16x16x32_bf16 v[88:91], v[140:143], v[206:209], v[88:91]
	v_mfma_f32_16x16x32_bf16 v[76:79], v[132:135], v[214:217], v[76:79]
	v_mfma_f32_16x16x32_bf16 v[72:75], v[140:143], v[214:217], v[72:75]
	s_setprio 0
	s_setprio 1
	v_mfma_f32_16x16x32_bf16 v[116:119], v[160:163], v[184:187], 0
	v_mfma_f32_16x16x32_bf16 v[112:115], v[176:179], v[184:187], 0
	v_mfma_f32_16x16x32_bf16 v[100:103], v[160:163], v[194:197], 0
	v_mfma_f32_16x16x32_bf16 v[96:99], v[176:179], v[194:197], 0
	v_mfma_f32_16x16x32_bf16 v[84:87], v[160:163], v[202:205], 0
	v_mfma_f32_16x16x32_bf16 v[80:83], v[176:179], v[202:205], 0
	v_mfma_f32_16x16x32_bf16 v[68:71], v[160:163], v[210:213], 0
	v_mfma_f32_16x16x32_bf16 v[64:67], v[176:179], v[210:213], 0
	v_mfma_f32_16x16x32_bf16 v[116:119], v[172:175], v[188:191], v[116:119]
	v_mfma_f32_16x16x32_bf16 v[112:115], v[180:183], v[188:191], v[112:115]
	v_mfma_f32_16x16x32_bf16 v[100:103], v[172:175], v[198:201], v[100:103]
	v_mfma_f32_16x16x32_bf16 v[96:99], v[180:183], v[198:201], v[96:99]
	v_mfma_f32_16x16x32_bf16 v[84:87], v[172:175], v[206:209], v[84:87]
	v_mfma_f32_16x16x32_bf16 v[80:83], v[180:183], v[206:209], v[80:83]
	v_mfma_f32_16x16x32_bf16 v[68:71], v[172:175], v[214:217], v[68:71]
	v_mfma_f32_16x16x32_bf16 v[64:67], v[180:183], v[214:217], v[64:67]
	s_setprio 0
	s_barrier
	s_add_i32 s30, s65, s54
	v_lshl_add_u64 v[164:165], s[36:37], 0, v[146:147]
	s_mov_b32 m0, s30
	ds_read_b128 v[184:187], v171 offset:16384
	ds_read_b128 v[188:191], v171 offset:17408
	ds_read_b128 v[194:197], v171 offset:18432
	ds_read_b128 v[198:201], v171 offset:19456
	ds_read_b128 v[202:205], v171 offset:20480
	ds_read_b128 v[206:209], v171 offset:21504
	ds_read_b128 v[210:213], v171 offset:22528
	ds_read_b128 v[214:217], v171 offset:23552
	global_load_lds_dwordx4 v[164:165], off
	s_add_i32 m0, s30, 0x2000
	s_add_u32 s30, s36, 0x160000
	v_lshl_add_u64 v[218:219], s[36:37], 0, v[150:151]
	s_addc_u32 s31, s37, 0
	s_add_i32 s74, s66, s54
	global_load_lds_dwordx4 v[218:219], off
	v_lshl_add_u64 v[220:221], s[30:31], 0, v[146:147]
	s_mov_b32 m0, s74
	v_lshl_add_u64 v[222:223], s[46:47], 0, v[148:149]
	global_load_lds_dwordx4 v[220:221], off
	v_lshl_add_u64 v[220:221], s[30:31], 0, v[150:151]
	s_add_i32 m0, s74, 0x2000
	s_nop 0
	global_load_lds_dwordx4 v[220:221], off
	v_lshl_add_u64 v[220:221], s[46:47], 0, v[144:145]
	s_mov_b32 m0, s55
	s_nop 0
	global_load_lds_dwordx4 v[220:221], off
	s_mov_b32 m0, s56
	s_nop 0
	global_load_lds_dwordx4 v[222:223], off
	s_waitcnt vmcnt(8)
	s_waitcnt lgkmcnt(0)
	s_barrier
; #define PG8_STAGE(bufoff, gbase, voff) do { _Pragma("unroll") for (int _i = 0; _i < 2; ++_i) \
;         __builtin_amdgcn_global_load_lds((const unsigned*)((const char*)(gbase) + (voff)[_i]), (PG8_LAS unsigned*)(lds + (bufoff) + ldsw + _i * 8192), 16, 0, 0); } while (0)
; #define PG8_LDA(dst, b, h) do { _Pragma("unroll") for (int m = 0; m < 4; ++m) _Pragma("unroll") for (int k = 0; k < 2; ++k) dst[m][k] = *(const PG8_LAS bf16x8*)(lds + PG8_SA(b, h) + aoff + m * 2048 + k * 1024); } while (0)
; #define PG8_LDB(dst, b, h) do { _Pragma("unroll") for (int n = 0; n < 2; ++n) _Pragma("unroll") for (int k = 0; k < 2; ++k) dst[n][k] = *(const PG8_LAS bf16x8*)(lds + PG8_SB(b, h) + boff + n * 2048 + k * 1024); } while (0)
; #define PG8_MMA(ai, bj, At, Bt) do { __builtin_amdgcn_s_setprio(1); _Pragma("unroll") for (int m = 0; m < 4; ++m) _Pragma("unroll") for (int n = 0; n < 2; ++n) _Pragma("unroll") for (int k = 0; k < 2; ++k) \
;         acc[ai][bj][m][n] = __builtin_amdgcn_mfma_f32_16x16x32_bf16(Bt[n][k], At[m][k], acc[ai][bj][m][n], 0, 0, 0); __builtin_amdgcn_s_setprio(0); } while (0)
; #define PG8_WAIT_V(n) asm volatile("s_waitcnt vmcnt(" #n ")" ::: "memory")
; #define PG8_WAIT_L(n) asm volatile("s_waitcnt lgkmcnt(" #n ")" ::: "memory")
; #define PG8_BAR __builtin_amdgcn_s_barrier()
; #define PG8_SCHED __builtin_amdgcn_sched_barrier(0)
; template <class Epi, class Sched, bool ALIGN_EPI = false, bool SP2 = false>
; __device__ __forceinline__ void gemm_phase(PG8_LAS unsigned char* lds, const Gemm g, const Sched& S, const Epi& E) {
;     ...
;             PG8_WAIT_V(8); PG8_WAIT_L(0); PG8_BAR; PG8_MMA(1, 0, At, B0); PG8_MMA(1, 1, At, B1); PG8_BAR; PG8_SCHED;
;             PG8_LDB(B0, 1, 0); PG8_LDB(B1, 1, 1); PG8_SCHED; PG8_LDA(At, 1, 0); PG8_STAGE(PG8_SA(0, 1), a2 + hstep, voffA);
;             PG8_WAIT_V(8); PG8_WAIT_L(0); PG8_BAR; PG8_MMA(0, 0, At, B0); PG8_MMA(0, 1, At, B1); PG8_BAR; PG8_SCHED;
	s_setprio 1
	s_waitcnt lgkmcnt(0)
	v_mfma_f32_16x16x32_bf16 v[60:63], v[124:127], v[184:187], 0
	v_mfma_f32_16x16x32_bf16 v[56:59], v[136:139], v[184:187], 0
	v_mfma_f32_16x16x32_bf16 v[44:47], v[124:127], v[194:197], 0
	v_mfma_f32_16x16x32_bf16 v[40:43], v[136:139], v[194:197], 0
	v_mfma_f32_16x16x32_bf16 v[28:31], v[124:127], v[202:205], 0
	v_mfma_f32_16x16x32_bf16 v[24:27], v[136:139], v[202:205], 0
	v_mfma_f32_16x16x32_bf16 v[12:15], v[124:127], v[210:213], 0
	v_mfma_f32_16x16x32_bf16 v[8:11], v[136:139], v[210:213], 0
	v_mfma_f32_16x16x32_bf16 v[60:63], v[132:135], v[188:191], v[60:63]
	v_mfma_f32_16x16x32_bf16 v[56:59], v[140:143], v[188:191], v[56:59]
	v_mfma_f32_16x16x32_bf16 v[44:47], v[132:135], v[198:201], v[44:47]
	v_mfma_f32_16x16x32_bf16 v[40:43], v[140:143], v[198:201], v[40:43]
	v_mfma_f32_16x16x32_bf16 v[28:31], v[132:135], v[206:209], v[28:31]
	v_mfma_f32_16x16x32_bf16 v[24:27], v[140:143], v[206:209], v[24:27]
	v_mfma_f32_16x16x32_bf16 v[12:15], v[132:135], v[214:217], v[12:15]
	v_mfma_f32_16x16x32_bf16 v[8:11], v[140:143], v[214:217], v[8:11]
	s_setprio 0
	s_setprio 1
	v_mfma_f32_16x16x32_bf16 v[52:55], v[160:163], v[184:187], 0
	v_mfma_f32_16x16x32_bf16 v[48:51], v[176:179], v[184:187], 0
	v_mfma_f32_16x16x32_bf16 v[36:39], v[160:163], v[194:197], 0
	v_mfma_f32_16x16x32_bf16 v[32:35], v[176:179], v[194:197], 0
	v_mfma_f32_16x16x32_bf16 v[20:23], v[160:163], v[202:205], 0
	v_mfma_f32_16x16x32_bf16 v[16:19], v[176:179], v[202:205], 0
	v_mfma_f32_16x16x32_bf16 v[4:7], v[160:163], v[210:213], 0
	v_mfma_f32_16x16x32_bf16 v[0:3], v[176:179], v[210:213], 0
	v_mfma_f32_16x16x32_bf16 v[52:55], v[172:175], v[188:191], v[52:55]
	v_mfma_f32_16x16x32_bf16 v[48:51], v[180:183], v[188:191], v[48:51]
	v_mfma_f32_16x16x32_bf16 v[36:39], v[172:175], v[198:201], v[36:39]
	v_mfma_f32_16x16x32_bf16 v[32:35], v[180:183], v[198:201], v[32:35]
	v_mfma_f32_16x16x32_bf16 v[20:23], v[172:175], v[206:209], v[20:23]
	v_mfma_f32_16x16x32_bf16 v[16:19], v[180:183], v[206:209], v[16:19]
	v_mfma_f32_16x16x32_bf16 v[4:7], v[172:175], v[214:217], v[4:7]
	v_mfma_f32_16x16x32_bf16 v[0:3], v[180:183], v[214:217], v[0:3]
	s_setprio 0
	s_barrier
	s_add_i32 s74, 0, 0x18000
	s_add_i32 s75, 0, 0x1c000
	v_add_u32_e32 v140, s74, v167
	v_add_u32_e32 v180, s75, v167
	ds_read_b128 v[124:127], v140
	ds_read_b128 v[132:135], v140 offset:1024
	ds_read_b128 v[136:139], v140 offset:2048
	ds_read_b128 v[140:143], v140 offset:3072
	ds_read_b128 v[160:163], v180
	ds_read_b128 v[172:175], v180 offset:1024
	ds_read_b128 v[176:179], v180 offset:2048
	ds_read_b128 v[180:183], v180 offset:3072
	s_add_u32 s30, s46, 0x160000
	s_addc_u32 s31, s47, 0
	s_mov_b32 m0, s57
	v_lshl_add_u64 v[224:225], s[30:31], 0, v[144:145]
	ds_read_b128 v[184:187], v171 offset:32768
	ds_read_b128 v[188:191], v171 offset:33792
	ds_read_b128 v[194:197], v171 offset:34816
	ds_read_b128 v[198:201], v171 offset:35840
	ds_read_b128 v[202:205], v171 offset:36864
	ds_read_b128 v[206:209], v171 offset:37888
	ds_read_b128 v[210:213], v171 offset:38912
	ds_read_b128 v[214:217], v171 offset:39936
	global_load_lds_dwordx4 v[224:225], off
	v_lshl_add_u64 v[224:225], s[30:31], 0, v[148:149]
	s_mov_b32 m0, s58
	s_nop 0
	global_load_lds_dwordx4 v[224:225], off
	s_waitcnt vmcnt(8)
	s_waitcnt lgkmcnt(0)
	s_barrier
	s_setprio 1
	s_waitcnt lgkmcnt(0)
	v_mfma_f32_16x16x32_bf16 v[128:131], v[124:127], v[184:187], v[128:131]
	v_mfma_f32_16x16x32_bf16 v[120:123], v[136:139], v[184:187], v[120:123]
	v_mfma_f32_16x16x32_bf16 v[108:111], v[124:127], v[194:197], v[108:111]
	v_mfma_f32_16x16x32_bf16 v[104:107], v[136:139], v[194:197], v[104:107]
	v_mfma_f32_16x16x32_bf16 v[92:95], v[124:127], v[202:205], v[92:95]
	v_mfma_f32_16x16x32_bf16 v[88:91], v[136:139], v[202:205], v[88:91]
	v_mfma_f32_16x16x32_bf16 v[76:79], v[124:127], v[210:213], v[76:79]
	v_mfma_f32_16x16x32_bf16 v[72:75], v[136:139], v[210:213], v[72:75]
	v_mfma_f32_16x16x32_bf16 v[128:131], v[132:135], v[188:191], v[128:131]
	v_mfma_f32_16x16x32_bf16 v[120:123], v[140:143], v[188:191], v[120:123]
	v_mfma_f32_16x16x32_bf16 v[108:111], v[132:135], v[198:201], v[108:111]
	v_mfma_f32_16x16x32_bf16 v[104:107], v[140:143], v[198:201], v[104:107]
	v_mfma_f32_16x16x32_bf16 v[92:95], v[132:135], v[206:209], v[92:95]
	v_mfma_f32_16x16x32_bf16 v[88:91], v[140:143], v[206:209], v[88:91]
	v_mfma_f32_16x16x32_bf16 v[76:79], v[132:135], v[214:217], v[76:79]
	v_mfma_f32_16x16x32_bf16 v[72:75], v[140:143], v[214:217], v[72:75]
	s_setprio 0
	s_setprio 1
	v_mfma_f32_16x16x32_bf16 v[116:119], v[160:163], v[184:187], v[116:119]
	v_mfma_f32_16x16x32_bf16 v[112:115], v[176:179], v[184:187], v[112:115]
	v_mfma_f32_16x16x32_bf16 v[100:103], v[160:163], v[194:197], v[100:103]
	v_mfma_f32_16x16x32_bf16 v[96:99], v[176:179], v[194:197], v[96:99]
	v_mfma_f32_16x16x32_bf16 v[84:87], v[160:163], v[202:205], v[84:87]
	v_mfma_f32_16x16x32_bf16 v[80:83], v[176:179], v[202:205], v[80:83]
	v_mfma_f32_16x16x32_bf16 v[68:71], v[160:163], v[210:213], v[68:71]
	v_mfma_f32_16x16x32_bf16 v[64:67], v[176:179], v[210:213], v[64:67]
	v_mfma_f32_16x16x32_bf16 v[116:119], v[172:175], v[188:191], v[116:119]
	v_mfma_f32_16x16x32_bf16 v[112:115], v[180:183], v[188:191], v[112:115]
	v_mfma_f32_16x16x32_bf16 v[100:103], v[172:175], v[198:201], v[100:103]
	v_mfma_f32_16x16x32_bf16 v[96:99], v[180:183], v[198:201], v[96:99]
	v_mfma_f32_16x16x32_bf16 v[84:87], v[172:175], v[206:209], v[84:87]
	v_mfma_f32_16x16x32_bf16 v[80:83], v[180:183], v[206:209], v[80:83]
	v_mfma_f32_16x16x32_bf16 v[68:71], v[172:175], v[214:217], v[68:71]
	v_mfma_f32_16x16x32_bf16 v[64:67], v[180:183], v[214:217], v[64:67]
	s_setprio 0
	s_barrier
; #define PG8_STAGE(bufoff, gbase, voff) do { _Pragma("unroll") for (int _i = 0; _i < 2; ++_i) \
;         __builtin_amdgcn_global_load_lds((const unsigned*)((const char*)(gbase) + (voff)[_i]), (PG8_LAS unsigned*)(lds + (bufoff) + ldsw + _i * 8192), 16, 0, 0); } while (0)
; #define PG8_LDA(dst, b, h) do { _Pragma("unroll") for (int m = 0; m < 4; ++m) _Pragma("unroll") for (int k = 0; k < 2; ++k) dst[m][k] = *(const PG8_LAS bf16x8*)(lds + PG8_SA(b, h) + aoff + m * 2048 + k * 1024); } while (0)
; #define PG8_MMA(ai, bj, At, Bt) do { __builtin_amdgcn_s_setprio(1); _Pragma("unroll") for (int m = 0; m < 4; ++m) _Pragma("unroll") for (int n = 0; n < 2; ++n) _Pragma("unroll") for (int k = 0; k < 2; ++k) \
;         acc[ai][bj][m][n] = __builtin_amdgcn_mfma_f32_16x16x32_bf16(Bt[n][k], At[m][k], acc[ai][bj][m][n], 0, 0, 0); __builtin_amdgcn_s_setprio(0); } while (0)
; #define PG8_WAIT_V(n) asm volatile("s_waitcnt vmcnt(" #n ")" ::: "memory")
; #define PG8_WAIT_L(n) asm volatile("s_waitcnt lgkmcnt(" #n ")" ::: "memory")
; #define PG8_BAR __builtin_amdgcn_s_barrier()
; #define PG8_SCHED __builtin_amdgcn_sched_barrier(0)
; template <class Epi, class Sched, bool ALIGN_EPI = false, bool SP2 = false>
; __device__ __forceinline__ void gemm_phase(PG8_LAS unsigned char* lds, const Gemm g, const Sched& S, const Epi& E) {
;     ...
;         for (int t = 0; t < nt; t += 2) {
;             const bool last = (t == nt - 2);
;     ...
;             PG8_LDA(At, 1, 1); PG8_STAGE(PG8_SB(1, 0), b3, voffB); PG8_STAGE(PG8_SB(1, 1), b3 + hstep, voffB); PG8_STAGE(PG8_SA(1, 0), a3, voffA);
;             PG8_WAIT_V(8); PG8_WAIT_L(0); PG8_BAR; PG8_MMA(1, 0, At, B0); PG8_MMA(1, 1, At, B1); PG8_BAR; PG8_SCHED;
	s_add_i32 s30, s74, s54
	v_lshl_add_u64 v[164:165], v[164:165], 0, s[16:17]
	s_mov_b32 m0, s30
	ds_read_b128 v[184:187], v171 offset:49152
	ds_read_b128 v[188:191], v171 offset:50176
	ds_read_b128 v[194:197], v171 offset:51200
	ds_read_b128 v[198:201], v171 offset:52224
	ds_read_b128 v[202:205], v171 offset:53248
	ds_read_b128 v[206:209], v171 offset:54272
	ds_read_b128 v[210:213], v171 offset:55296
	ds_read_b128 v[214:217], v171 offset:56320
	global_load_lds_dwordx4 v[164:165], off
	s_add_i32 m0, s30, 0x2000
	s_add_u32 s30, s36, 0x160080
	v_lshl_add_u64 v[164:165], v[218:219], 0, s[16:17]
	s_addc_u32 s31, s37, 0
	s_add_i32 s36, s75, s54
	global_load_lds_dwordx4 v[164:165], off
	v_lshl_add_u64 v[164:165], s[30:31], 0, v[146:147]
	s_mov_b32 m0, s36
	s_nop 0
	global_load_lds_dwordx4 v[164:165], off
	v_lshl_add_u64 v[164:165], s[30:31], 0, v[150:151]
	s_add_i32 m0, s36, 0x2000
	s_nop 0
	global_load_lds_dwordx4 v[164:165], off
	v_lshl_add_u64 v[164:165], v[220:221], 0, s[16:17]
	s_mov_b32 m0, s62
	s_nop 0
	global_load_lds_dwordx4 v[164:165], off
	v_lshl_add_u64 v[164:165], v[222:223], 0, s[16:17]
	s_mov_b32 m0, s63
	s_nop 0
	global_load_lds_dwordx4 v[164:165], off
	s_waitcnt vmcnt(8)
	s_waitcnt lgkmcnt(0)
	s_barrier
	s_setprio 1
	s_waitcnt lgkmcnt(0)
	v_mfma_f32_16x16x32_bf16 v[60:63], v[124:127], v[184:187], v[60:63]
	v_mfma_f32_16x16x32_bf16 v[56:59], v[136:139], v[184:187], v[56:59]
	v_mfma_f32_16x16x32_bf16 v[44:47], v[124:127], v[194:197], v[44:47]
	v_mfma_f32_16x16x32_bf16 v[40:43], v[136:139], v[194:197], v[40:43]
	v_mfma_f32_16x16x32_bf16 v[28:31], v[124:127], v[202:205], v[28:31]
	v_mfma_f32_16x16x32_bf16 v[24:27], v[136:139], v[202:205], v[24:27]
	v_mfma_f32_16x16x32_bf16 v[12:15], v[124:127], v[210:213], v[12:15]
	v_mfma_f32_16x16x32_bf16 v[8:11], v[136:139], v[210:213], v[8:11]
	v_mfma_f32_16x16x32_bf16 v[60:63], v[132:135], v[188:191], v[60:63]
	v_mfma_f32_16x16x32_bf16 v[56:59], v[140:143], v[188:191], v[56:59]
	v_mfma_f32_16x16x32_bf16 v[44:47], v[132:135], v[198:201], v[44:47]
	v_mfma_f32_16x16x32_bf16 v[40:43], v[140:143], v[198:201], v[40:43]
	v_mfma_f32_16x16x32_bf16 v[28:31], v[132:135], v[206:209], v[28:31]
	v_mfma_f32_16x16x32_bf16 v[24:27], v[140:143], v[206:209], v[24:27]
	v_mfma_f32_16x16x32_bf16 v[12:15], v[132:135], v[214:217], v[12:15]
	v_mfma_f32_16x16x32_bf16 v[8:11], v[140:143], v[214:217], v[8:11]
	s_setprio 0
	s_setprio 1
	v_mfma_f32_16x16x32_bf16 v[52:55], v[160:163], v[184:187], v[52:55]
	v_mfma_f32_16x16x32_bf16 v[48:51], v[176:179], v[184:187], v[48:51]
	v_mfma_f32_16x16x32_bf16 v[36:39], v[160:163], v[194:197], v[36:39]
	v_mfma_f32_16x16x32_bf16 v[32:35], v[176:179], v[194:197], v[32:35]
	v_mfma_f32_16x16x32_bf16 v[20:23], v[160:163], v[202:205], v[20:23]
	v_mfma_f32_16x16x32_bf16 v[16:19], v[176:179], v[202:205], v[16:19]
	v_mfma_f32_16x16x32_bf16 v[4:7], v[160:163], v[210:213], v[4:7]
	v_mfma_f32_16x16x32_bf16 v[0:3], v[176:179], v[210:213], v[0:3]
	v_mfma_f32_16x16x32_bf16 v[52:55], v[172:175], v[188:191], v[52:55]
	v_mfma_f32_16x16x32_bf16 v[48:51], v[180:183], v[188:191], v[48:51]
	v_mfma_f32_16x16x32_bf16 v[36:39], v[172:175], v[198:201], v[36:39]
	v_mfma_f32_16x16x32_bf16 v[32:35], v[180:183], v[198:201], v[32:35]
	v_mfma_f32_16x16x32_bf16 v[20:23], v[172:175], v[206:209], v[20:23]
	v_mfma_f32_16x16x32_bf16 v[16:19], v[180:183], v[206:209], v[16:19]
	v_mfma_f32_16x16x32_bf16 v[4:7], v[172:175], v[214:217], v[4:7]
	v_mfma_f32_16x16x32_bf16 v[0:3], v[180:183], v[214:217], v[0:3]
	s_setprio 0
	s_barrier
	s_add_i32 s73, s73, 2
	s_add_u32 s71, s71, 0x100
	s_addc_u32 s72, s72, 0
	s_cmpk_gt_u32 s73, 0x55
	s_mov_b64 s[30:31], s[34:35]
	s_cbranch_scc1 .Lpeel_exit_7
	.p2align	6
